# S5 final phase: LDS x tile row pitch 288 B (conflict-free column reads) on top of the XCD-aware mapping
# baseline (speedup 1.0000x reference)
; __device__ __forceinline__ bf16x8 pack8(const float (&f)[8]) { u32x4 h; h.x = pk2(f[0], f[1]); h.y = pk2(f[2], f[3]); h.z = pk2(f[4], f[5]); h.w = pk2(f[6], f[7]); return __builtin_bit_cast(bf16x8, h); }
;     __device__ __forceinline__ bf16* R(int i) const { return (bf16*)(ws + OFF_R0 + (size_t)i * RSZ); }
; template <bool FINAL> __device__ __forceinline__ void phase_s5_scan(const Fr& F) {
;     const bf16* U = F.R(1); float* E = (float*)F.R(6);
;     float* BUl = (float*)(F.lds + F.wave * 16384);
;     const int lane = F.lane, l15 = lane & 15, lq = lane >> 4;
;     const float* BBf = (const float*)(F.ws + OFF_BB);
;     const int sg = F.gw >> 4, g = sg & 63, s = sg >> 6;
;     const f32x4 av = *(const f32x4*)((const float*)(F.ws + OFF_S5A) + (sg * 64 + lane) * 4);
;     const float ar = av.x, ai = av.y;
;     bf16x8 B1[8];
; #pragma unroll
;     for (int nt = 0; nt < 8; ++nt) {
;         const int n = 16 * nt + l15; const float* bp = BBf + (size_t)(sg * 64 + (n & 63)) * 32 + 16 * (n >> 6) + 8 * (lq & 1);
;         const f32x4 t0 = *(const f32x4*)bp, t1 = *(const f32x4*)(bp + 4); const float f[8] = {t0.x, t0.y, t0.z, t0.w, t1.x, t1.y, t1.z, t1.w};
;         B1[nt] = lq < 2 ? pack8(f) : (bf16x8){0, 0, 0, 0, 0, 0, 0, 0};
;     }
;     bf16x8 Chi[4];
;     if (FINAL) {
; #pragma unroll
;         for (int ks = 0; ks < 4; ++ks) {
;             const int k = 32 * ks + 8 * lq; const float* cp = (k < 64 ? F.a->in[32] : F.a->in[33]) + (size_t)g * 1024 + l15 * 64 + (k & 63); const float sg_ = k < 64 ? 1.f : -1.f;
;             const f32x4 t0 = *(const f32x4*)cp, t1 = *(const f32x4*)(cp + 4); const float f[8] = {sg_ * t0.x, sg_ * t0.y, sg_ * t0.z, sg_ * t0.w, sg_ * t1.x, sg_ * t1.y, sg_ * t1.z, sg_ * t1.w};
;             Chi[ks] = pack8(f);
;         }
;     }
;     u32x4 ua[4]; float e0 = 0.f, e1 = 0.f;
;     {   const int ti = F.gw & 15, b = ti / 68, chunk = ti - b * 68;
; #pragma unroll
;         for (int sb = 0; sb < 4; ++sb) ua[sb] = lq < 2 ? *(const u32x4*)(U + ((size_t)b * TB + tokof(s, chunk * 64 + sb * 16 + l15)) * D + g * 16 + 8 * lq) : (u32x4){0u, 0u, 0u, 0u};
;         if (FINAL) { const float* e = E + ((size_t)(((s * 4 + b) * 64 + g) * 68 + chunk) * 64 + lane) * 2; e0 = e[0]; e1 = e[1]; } }
.LBB0_1716:
	s_or_b64 exec, exec, s[6:7]
	v_cmp_gt_i32_e32 vcc, 18, v2
	v_cmp_lt_i32_e64 s[6:7], 17, v3
	s_and_b64 s[6:7], vcc, s[6:7]
	s_and_saveexec_b64 s[12:13], s[6:7]
	s_cbranch_execz .LBB0_1762
	s_and_b32 s15, s2, 7
	s_lshr_b32 s16, s2, 3
	s_lshr_b32 s17, s16, 3
	s_lshl_b32 s15, s15, 2
	s_add_i32 s15, s15, s17
	s_lshr_b32 s9, s15, 4
	s_and_b32 s15, s15, 15
	s_and_b32 s16, s16, 7
	s_lshr_b32 s17, s16, 1
	s_lshl_b32 s8, s15, 2
	s_add_i32 s8, s8, s17
	s_lshl_b32 s3, s9, 6
	s_add_i32 s3, s3, s8
	s_and_b32 s16, s16, 1
	s_lshl_b32 s55, s16, 3
	s_add_i32 s55, s55, s68
	s_cmp_lt_u32 s55, 4
	s_cselect_b32 s56, 5, 4
	v_and_b32_e32 v236, 15, v130
	v_lshrrev_b32_e32 v237, 4, v130
	s_add_u32 s42, s26, 0x100000
	s_addc_u32 s43, s27, 0
	s_add_u32 s44, s26, 0x40000
	s_addc_u32 s45, s27, 0
	s_add_u32 s20, s26, 0x3400000
	s_addc_u32 s21, s27, 0
	s_add_u32 s22, s26, 0xde00000
	s_addc_u32 s23, s27, 0
	s_mul_i32 s15, s9, 0x2200000
	s_add_u32 s24, s26, s15
	s_addc_u32 s25, s27, 0
	s_add_u32 s24, s24, 0x9a00000
	s_addc_u32 s25, s25, 0
	s_load_dwordx2 s[46:47], s[0:1], 0x100
	s_load_dwordx2 s[48:49], s[0:1], 0x108
	s_lshl_b32 s15, s3, 6
	v_add_u32_e32 v216, s15, v236
	v_and_b32_e32 v217, 1, v237
	v_lshlrev_b32_e32 v217, 5, v217
	v_lshl_add_u32 v218, v216, 7, v217
	v_add_u32_e32 v219, 0x1000, v218
	global_load_dwordx4 v[56:59], v218, s[42:43] offset:0
	global_load_dwordx4 v[60:63], v218, s[42:43] offset:16
	global_load_dwordx4 v[64:67], v218, s[42:43] offset:2048
	global_load_dwordx4 v[68:71], v218, s[42:43] offset:2064
	global_load_dwordx4 v[72:75], v219, s[42:43] offset:0
	global_load_dwordx4 v[76:79], v219, s[42:43] offset:16
	global_load_dwordx4 v[80:83], v219, s[42:43] offset:2048
	global_load_dwordx4 v[84:87], v219, s[42:43] offset:2064
	global_load_dwordx4 v[88:91], v218, s[42:43] offset:64
	global_load_dwordx4 v[92:95], v218, s[42:43] offset:80
	global_load_dwordx4 v[96:99], v218, s[42:43] offset:2112
	global_load_dwordx4 v[100:103], v218, s[42:43] offset:2128
	global_load_dwordx4 v[104:107], v219, s[42:43] offset:64
	global_load_dwordx4 v[108:111], v219, s[42:43] offset:80
	global_load_dwordx4 v[112:115], v219, s[42:43] offset:2112
	global_load_dwordx4 v[116:119], v219, s[42:43] offset:2128
	v_lshlrev_b32_e32 v220, 4, v216
	global_load_dwordx2 v[32:33], v220, s[44:45] offset:0
	global_load_dwordx2 v[34:35], v220, s[44:45] offset:256
	global_load_dwordx2 v[36:37], v220, s[44:45] offset:512
	global_load_dwordx2 v[38:39], v220, s[44:45] offset:768
	s_waitcnt vmcnt(0)
	v_cmp_gt_u32_e32 vcc, 2, v237
	v_cvt_pk_bf16_f32 v0, v56, v57
	v_cvt_pk_bf16_f32 v1, v58, v59
	v_cvt_pk_bf16_f32 v2, v60, v61
	v_cvt_pk_bf16_f32 v3, v62, v63
	v_cvt_pk_bf16_f32 v4, v64, v65
	v_cvt_pk_bf16_f32 v5, v66, v67
	v_cvt_pk_bf16_f32 v6, v68, v69
	v_cvt_pk_bf16_f32 v7, v70, v71
	v_cvt_pk_bf16_f32 v8, v72, v73
	v_cvt_pk_bf16_f32 v9, v74, v75
	v_cvt_pk_bf16_f32 v10, v76, v77
	v_cvt_pk_bf16_f32 v11, v78, v79
	v_cvt_pk_bf16_f32 v12, v80, v81
	v_cvt_pk_bf16_f32 v13, v82, v83
	v_cvt_pk_bf16_f32 v14, v84, v85
	v_cvt_pk_bf16_f32 v15, v86, v87
	v_cvt_pk_bf16_f32 v16, v88, v89
	v_cvt_pk_bf16_f32 v17, v90, v91
	v_cvt_pk_bf16_f32 v18, v92, v93
	v_cvt_pk_bf16_f32 v19, v94, v95
	v_cvt_pk_bf16_f32 v20, v96, v97
	v_cvt_pk_bf16_f32 v21, v98, v99
	v_cvt_pk_bf16_f32 v22, v100, v101
	v_cvt_pk_bf16_f32 v23, v102, v103
	v_cvt_pk_bf16_f32 v24, v104, v105
	v_cvt_pk_bf16_f32 v25, v106, v107
	v_cvt_pk_bf16_f32 v26, v108, v109
	v_cvt_pk_bf16_f32 v27, v110, v111
	v_cvt_pk_bf16_f32 v28, v112, v113
	v_cvt_pk_bf16_f32 v29, v114, v115
	v_cvt_pk_bf16_f32 v30, v116, v117
	v_cvt_pk_bf16_f32 v31, v118, v119
	v_cndmask_b32_e32 v0, 0, v0, vcc
	v_cndmask_b32_e32 v1, 0, v1, vcc
	v_cndmask_b32_e32 v2, 0, v2, vcc
	v_cndmask_b32_e32 v3, 0, v3, vcc
	v_cndmask_b32_e32 v4, 0, v4, vcc
	v_cndmask_b32_e32 v5, 0, v5, vcc
	v_cndmask_b32_e32 v6, 0, v6, vcc
	v_cndmask_b32_e32 v7, 0, v7, vcc
	v_cndmask_b32_e32 v8, 0, v8, vcc
	v_cndmask_b32_e32 v9, 0, v9, vcc
	v_cndmask_b32_e32 v10, 0, v10, vcc
	v_cndmask_b32_e32 v11, 0, v11, vcc
	v_cndmask_b32_e32 v12, 0, v12, vcc
	v_cndmask_b32_e32 v13, 0, v13, vcc
	v_cndmask_b32_e32 v14, 0, v14, vcc
	v_cndmask_b32_e32 v15, 0, v15, vcc
	v_cndmask_b32_e32 v16, 0, v16, vcc
	v_cndmask_b32_e32 v17, 0, v17, vcc
	v_cndmask_b32_e32 v18, 0, v18, vcc
	v_cndmask_b32_e32 v19, 0, v19, vcc
	v_cndmask_b32_e32 v20, 0, v20, vcc
	v_cndmask_b32_e32 v21, 0, v21, vcc
	v_cndmask_b32_e32 v22, 0, v22, vcc
	v_cndmask_b32_e32 v23, 0, v23, vcc
	v_cndmask_b32_e32 v24, 0, v24, vcc
	v_cndmask_b32_e32 v25, 0, v25, vcc
	v_cndmask_b32_e32 v26, 0, v26, vcc
	v_cndmask_b32_e32 v27, 0, v27, vcc
	v_cndmask_b32_e32 v28, 0, v28, vcc
	v_cndmask_b32_e32 v29, 0, v29, vcc
	v_cndmask_b32_e32 v30, 0, v30, vcc
	v_cndmask_b32_e32 v31, 0, v31, vcc
	s_lshl_b32 s15, s8, 4
	v_add_u32_e32 v221, s15, v236
	v_lshl_add_u32 v221, v221, 6, v237
	v_lshlrev_b32_e32 v221, 2, v221
	s_waitcnt lgkmcnt(0)
; __device__ __forceinline__ bf16x8 pack8(const float (&f)[8]) { u32x4 h; h.x = pk2(f[0], f[1]); h.y = pk2(f[2], f[3]); h.z = pk2(f[4], f[5]); h.w = pk2(f[6], f[7]); return __builtin_bit_cast(bf16x8, h); }
; template <bool FINAL> __device__ __forceinline__ void phase_s5_scan(const Fr& F) {
;     ...
;     bf16x8 Chi[4];
;     if (FINAL) {
; #pragma unroll
;         for (int ks = 0; ks < 4; ++ks) {
;             const int k = 32 * ks + 8 * lq; const float* cp = (k < 64 ? F.a->in[32] : F.a->in[33]) + (size_t)g * 1024 + l15 * 64 + (k & 63); const float sg_ = k < 64 ? 1.f : -1.f;
;             const f32x4 t0 = *(const f32x4*)cp, t1 = *(const f32x4*)(cp + 4); const float f[8] = {sg_ * t0.x, sg_ * t0.y, sg_ * t0.z, sg_ * t0.w, sg_ * t1.x, sg_ * t1.y, sg_ * t1.z, sg_ * t1.w};
;             Chi[ks] = pack8(f);
;         }
;     }
;     u32x4 ua[4]; float e0 = 0.f, e1 = 0.f;
;     {   const int ti = F.gw & 15, b = ti / 68, chunk = ti - b * 68;
; #pragma unroll
;         for (int sb = 0; sb < 4; ++sb) ua[sb] = lq < 2 ? *(const u32x4*)(U + ((size_t)b * TB + tokof(s, chunk * 64 + sb * 16 + l15)) * D + g * 16 + 8 * lq) : (u32x4){0u, 0u, 0u, 0u};
;         if (FINAL) { const float* e = E + ((size_t)(((s * 4 + b) * 64 + g) * 68 + chunk) * 64 + lane) * 2; e0 = e[0]; e1 = e[1]; } }
	global_load_dword v56, v221, s[46:47] offset:0
	global_load_dword v57, v221, s[48:49] offset:0
	global_load_dword v58, v221, s[46:47] offset:64
	global_load_dword v59, v221, s[48:49] offset:64
	global_load_dword v60, v221, s[46:47] offset:128
	global_load_dword v61, v221, s[48:49] offset:128
	global_load_dword v62, v221, s[46:47] offset:192
	global_load_dword v63, v221, s[48:49] offset:192
	global_load_dword v64, v221, s[46:47] offset:16
	global_load_dword v65, v221, s[48:49] offset:16
	global_load_dword v66, v221, s[46:47] offset:80
	global_load_dword v67, v221, s[48:49] offset:80
	global_load_dword v68, v221, s[46:47] offset:144
	global_load_dword v69, v221, s[48:49] offset:144
	global_load_dword v70, v221, s[46:47] offset:208
	global_load_dword v71, v221, s[48:49] offset:208
	global_load_dword v72, v221, s[46:47] offset:32
	global_load_dword v73, v221, s[48:49] offset:32
	global_load_dword v74, v221, s[46:47] offset:96
	global_load_dword v75, v221, s[48:49] offset:96
	global_load_dword v76, v221, s[46:47] offset:160
	global_load_dword v77, v221, s[48:49] offset:160
	global_load_dword v78, v221, s[46:47] offset:224
	global_load_dword v79, v221, s[48:49] offset:224
	global_load_dword v80, v221, s[46:47] offset:48
	global_load_dword v81, v221, s[48:49] offset:48
	global_load_dword v82, v221, s[46:47] offset:112
	global_load_dword v83, v221, s[48:49] offset:112
	global_load_dword v84, v221, s[46:47] offset:176
	global_load_dword v85, v221, s[48:49] offset:176
	global_load_dword v86, v221, s[46:47] offset:240
	global_load_dword v87, v221, s[48:49] offset:240
	s_waitcnt vmcnt(0)
	v_cvt_pk_bf16_f32 v40, v56, -v57
	v_cvt_pk_bf16_f32 v41, v58, -v59
	v_cvt_pk_bf16_f32 v42, v60, -v61
	v_cvt_pk_bf16_f32 v43, v62, -v63
	v_cvt_pk_bf16_f32 v44, v64, -v65
	v_cvt_pk_bf16_f32 v45, v66, -v67
	v_cvt_pk_bf16_f32 v46, v68, -v69
	v_cvt_pk_bf16_f32 v47, v70, -v71
	v_cvt_pk_bf16_f32 v48, v72, -v73
	v_cvt_pk_bf16_f32 v49, v74, -v75
	v_cvt_pk_bf16_f32 v50, v76, -v77
	v_cvt_pk_bf16_f32 v51, v78, -v79
	v_cvt_pk_bf16_f32 v52, v80, -v81
	v_cvt_pk_bf16_f32 v53, v82, -v83
	v_cvt_pk_bf16_f32 v54, v84, -v85
	v_cvt_pk_bf16_f32 v55, v86, -v87
	s_lshl_b32 s15, s68, 14
	v_mul_u32_u24_e32 v241, 0x480, v237
	v_lshl_add_u32 v241, v236, 4, v241
	v_add_u32_e32 v241, s15, v241
	v_mul_u32_u24_e32 v242, 0x120, v236
	v_lshl_add_u32 v242, v237, 4, v242
	v_add_u32_e32 v242, s15, v242
	s_cmp_eq_u32 s9, 0
	s_mov_b32 s18, 0xffffe000
	s_cselect_b32 s18, 0x2000, s18
	v_mov_b32_e32 v243, s18
	s_mov_b32 s14, s55
	s_lshl_b32 s15, s14, 2
	v_lshrrev_b32_e32 v244, 2, v236
	v_add_u32_e32 v244, s15, v244
	v_mul_u32_u24_e32 v245, 0xf1, v244
	v_lshrrev_b32_e32 v245, 14, v245
	v_mul_u32_u24_e32 v232, 68, v245
	v_sub_u32_e32 v244, v244, v232
	v_and_b32_e32 v232, 3, v236
	v_lshl_add_u32 v232, v244, 6, v232
	v_mov_b32_e32 v233, 0x11ff
	v_mov_b32_e32 v234, 0xff
	v_cmp_gt_u32_e32 vcc, 4, v244
	s_nop 1
	v_cndmask_b32_e32 v233, v233, v234, vcc
	v_sub_u32_e32 v233, v233, v232
	s_cmp_eq_u32 s9, 0
	s_cselect_b64 vcc, -1, 0
	s_nop 1
	v_cndmask_b32_e32 v232, v233, v232, vcc
	v_mul_u32_u24_e32 v245, 0x1100, v245
	v_add_u32_e32 v232, v232, v245
	s_lshl_b32 s16, s8, 5
	v_and_b32_e32 v233, 1, v237
	v_lshl_add_u32 v233, v233, 4, s16
	v_lshl_add_u32 v238, v232, 11, v233
	v_add_u32_e32 v244, s15, v237
	v_mul_u32_u24_e32 v245, 0xf1, v244
	v_lshrrev_b32_e32 v245, 14, v245
	v_mul_u32_u24_e32 v232, 68, v245
	v_sub_u32_e32 v244, v244, v232
	s_lshl_b32 s17, s9, 2
	v_add_u32_e32 v245, s17, v245
	v_lshl_add_u32 v245, v245, 6, s8
	v_mul_u32_u24_e32 v245, 68, v245
	v_add_u32_e32 v245, v245, v244
	v_lshl_add_u32 v245, v245, 6, v236
	v_lshlrev_b32_e32 v240, 3, v245
	global_load_dwordx2 v[246:247], v240, s[22:23] offset:0
	global_load_dwordx2 v[248:249], v240, s[22:23] offset:128
	global_load_dwordx2 v[250:251], v240, s[22:23] offset:256
	global_load_dwordx2 v[252:253], v240, s[22:23] offset:384
	global_load_dwordx4 v[56:59], v238, s[20:21]
	v_add_u32_e32 v238, v238, v243
	global_load_dwordx4 v[60:63], v238, s[20:21]
	v_add_u32_e32 v238, v238, v243
	global_load_dwordx4 v[64:67], v238, s[20:21]
	v_add_u32_e32 v238, v238, v243
	global_load_dwordx4 v[68:71], v238, s[20:21]
	v_add_u32_e32 v238, v238, v243
	global_load_dwordx4 v[72:75], v238, s[20:21]
	v_add_u32_e32 v238, v238, v243
	global_load_dwordx4 v[76:79], v238, s[20:21]
	v_add_u32_e32 v238, v238, v243
	global_load_dwordx4 v[80:83], v238, s[20:21]
	v_add_u32_e32 v238, v238, v243
	global_load_dwordx4 v[84:87], v238, s[20:21]
	v_add_u32_e32 v238, v238, v243
	global_load_dwordx4 v[88:91], v238, s[20:21]
	v_add_u32_e32 v238, v238, v243
	global_load_dwordx4 v[92:95], v238, s[20:21]
	v_add_u32_e32 v238, v238, v243
	global_load_dwordx4 v[96:99], v238, s[20:21]
	v_add_u32_e32 v238, v238, v243
	global_load_dwordx4 v[100:103], v238, s[20:21]
	v_add_u32_e32 v238, v238, v243
	global_load_dwordx4 v[104:107], v238, s[20:21]
	v_add_u32_e32 v238, v238, v243
	global_load_dwordx4 v[108:111], v238, s[20:21]
	v_add_u32_e32 v238, v238, v243
	global_load_dwordx4 v[112:115], v238, s[20:21]
	v_add_u32_e32 v238, v238, v243
	global_load_dwordx4 v[116:119], v238, s[20:21]
	v_add_u32_e32 v238, v238, v243
	s_mov_b32 s19, 0
	s_waitcnt vmcnt(0)
;     __device__ __forceinline__ bf16* R(int i) const { return (bf16*)(ws + OFF_R0 + (size_t)i * RSZ); }
; template <bool FINAL> __device__ __forceinline__ void phase_s5_scan(const Fr& F) {
;     ...
;     for (int ti = (F.gw & 15); ti < NB * 68; ti += 16) {
;         const int b = ti / 68, chunk = ti - b * 68, sbg = (s * 4 + b) * 64 + g, task = sbg * 68 + chunk;
;         float xr = FINAL ? e0 : 0.f, xi = FINAL ? e1 : 0.f;
;         bf16* Yb = F.R(4 + s);
;         u32x4 uc[4];
; #pragma unroll
;         for (int sb = 0; sb < 4; ++sb) uc[sb] = ua[sb];
;         if (ti + 16 < NB * 68) {
;             const int tn = ti + 16, bn = tn / 68, cn = tn - bn * 68;
; #pragma unroll
;             for (int sb = 0; sb < 4; ++sb) ua[sb] = lq < 2 ? *(const u32x4*)(U + ((size_t)bn * TB + tokof(s, cn * 64 + sb * 16 + l15)) * D + g * 16 + 8 * lq) : (u32x4){0u, 0u, 0u, 0u};
;             if (FINAL) { const float* e = E + ((size_t)(((s * 4 + bn) * 64 + g) * 68 + cn) * 64 + lane) * 2; e0 = e[0]; e1 = e[1]; }
;         }
; #pragma unroll
;         for (int sub = 0; sub < 4; ++sub) {
;             const bf16x8 A1 = __builtin_bit_cast(bf16x8, uc[sub]);
; #pragma unroll
;             for (int nt = 0; nt < 8; ++nt) {
;                 f32x4 acc = {0.f, 0.f, 0.f, 0.f};
;                 acc = __builtin_amdgcn_mfma_f32_16x16x32_bf16(A1, B1[nt], acc, 0, 0, 0);
; #pragma unroll
;                 for (int reg = 0; reg < 4; ++reg) BUl[(4 * lq + reg) * 132 + 16 * nt + l15] = acc[reg];
;             }
;             asm volatile("s_waitcnt lgkmcnt(0)" ::: "memory");
; #pragma unroll 4
;             for (int jj = 0; jj < 16; ++jj) {
;                 const float br_ = BUl[jj * 132 + lane], bi_ = BUl[jj * 132 + 64 + lane];
;                 const float nr = ar * xr - ai * xi + br_, ni = ar * xi + ai * xr + bi_; xr = nr; xi = ni;
;                 if (FINAL) { BUl[jj * 132 + lane] = xr; BUl[jj * 132 + 64 + lane] = xi; }
.Ls5b_grp:
	s_lshl_b32 s15, s14, 2
	v_lshrrev_b32_e32 v244, 2, v236
	v_add_u32_e32 v244, s15, v244
	v_mul_u32_u24_e32 v245, 0xf1, v244
	v_lshrrev_b32_e32 v245, 14, v245
	v_mul_u32_u24_e32 v232, 68, v245
	v_sub_u32_e32 v244, v244, v232
	v_and_b32_e32 v232, 3, v236
	v_lshl_add_u32 v232, v244, 6, v232
	v_mov_b32_e32 v233, 0x11ff
	v_mov_b32_e32 v234, 0xff
	v_cmp_gt_u32_e32 vcc, 4, v244
	s_nop 1
	v_cndmask_b32_e32 v233, v233, v234, vcc
	v_sub_u32_e32 v233, v233, v232
	s_cmp_eq_u32 s9, 0
	s_cselect_b64 vcc, -1, 0
	s_nop 1
	v_cndmask_b32_e32 v232, v233, v232, vcc
	v_mul_u32_u24_e32 v245, 0x1100, v245
	v_add_u32_e32 v232, v232, v245
	s_lshl_b32 s16, s8, 5
	v_and_b32_e32 v233, 1, v237
	v_lshl_add_u32 v233, v233, 4, s16
	v_lshl_add_u32 v235, v232, 11, v233
	v_lshl_add_u32 v233, v237, 3, s16
	v_lshl_add_u32 v239, v232, 11, v233
	s_add_i32 s54, s14, 16
	s_lshl_b32 s15, s54, 2
	v_lshrrev_b32_e32 v244, 2, v236
	v_add_u32_e32 v244, s15, v244
	v_mul_u32_u24_e32 v245, 0xf1, v244
	v_lshrrev_b32_e32 v245, 14, v245
	v_mul_u32_u24_e32 v232, 68, v245
	v_sub_u32_e32 v244, v244, v232
	v_and_b32_e32 v232, 3, v236
	v_lshl_add_u32 v232, v244, 6, v232
	v_mov_b32_e32 v233, 0x11ff
	v_mov_b32_e32 v234, 0xff
	v_cmp_gt_u32_e32 vcc, 4, v244
	s_nop 1
	v_cndmask_b32_e32 v233, v233, v234, vcc
	v_sub_u32_e32 v233, v233, v232
	s_cmp_eq_u32 s9, 0
	s_cselect_b64 vcc, -1, 0
	s_nop 1
	v_cndmask_b32_e32 v232, v233, v232, vcc
	v_mul_u32_u24_e32 v245, 0x1100, v245
	v_add_u32_e32 v232, v232, v245
	s_lshl_b32 s16, s8, 5
	v_and_b32_e32 v233, 1, v237
	v_lshl_add_u32 v233, v233, 4, s16
	v_lshl_add_u32 v238, v232, 11, v233
	v_add_u32_e32 v244, s15, v237
	v_mul_u32_u24_e32 v245, 0xf1, v244
	v_lshrrev_b32_e32 v245, 14, v245
	v_mul_u32_u24_e32 v232, 68, v245
	v_sub_u32_e32 v244, v244, v232
	s_lshl_b32 s17, s9, 2
	v_add_u32_e32 v245, s17, v245
	v_lshl_add_u32 v245, v245, 6, s8
	v_mul_u32_u24_e32 v245, 68, v245
	v_add_u32_e32 v245, v245, v244
	v_lshl_add_u32 v245, v245, 6, v236
	v_lshlrev_b32_e32 v240, 3, v245
	s_waitcnt vmcnt(31)
	v_mov_b32_e32 v200, v246
	v_mov_b32_e32 v201, v247
	v_mov_b32_e32 v202, v248
	v_mov_b32_e32 v203, v249
	v_mov_b32_e32 v204, v250
	v_mov_b32_e32 v205, v251
	v_mov_b32_e32 v206, v252
	v_mov_b32_e32 v207, v253
	s_nop 0
	global_load_dwordx2 v[246:247], v240, s[22:23] offset:0
	global_load_dwordx2 v[248:249], v240, s[22:23] offset:128
	global_load_dwordx2 v[250:251], v240, s[22:23] offset:256
	global_load_dwordx2 v[252:253], v240, s[22:23] offset:384
	v_mfma_f32_16x16x32_bf16 v[136:139], v[56:59], v[0:3], 0
	v_mfma_f32_16x16x32_bf16 v[140:143], v[56:59], v[4:7], 0
	v_mfma_f32_16x16x32_bf16 v[144:147], v[56:59], v[8:11], 0
	v_mfma_f32_16x16x32_bf16 v[148:151], v[56:59], v[12:15], 0
	v_mfma_f32_16x16x32_bf16 v[152:155], v[56:59], v[16:19], 0
	v_mfma_f32_16x16x32_bf16 v[156:159], v[56:59], v[20:23], 0
	v_mfma_f32_16x16x32_bf16 v[160:163], v[56:59], v[24:27], 0
	v_mfma_f32_16x16x32_bf16 v[164:167], v[56:59], v[28:31], 0
	s_waitcnt vmcnt(33)
	v_mfma_f32_16x16x32_bf16 v[168:171], v[60:63], v[0:3], 0
	v_mfma_f32_16x16x32_bf16 v[172:175], v[60:63], v[4:7], 0
	v_mfma_f32_16x16x32_bf16 v[176:179], v[60:63], v[8:11], 0
	v_mfma_f32_16x16x32_bf16 v[180:183], v[60:63], v[12:15], 0
	v_mfma_f32_16x16x32_bf16 v[184:187], v[60:63], v[16:19], 0
	v_mfma_f32_16x16x32_bf16 v[188:191], v[60:63], v[20:23], 0
	v_mfma_f32_16x16x32_bf16 v[192:195], v[60:63], v[24:27], 0
	v_mfma_f32_16x16x32_bf16 v[196:199], v[60:63], v[28:31], 0
	v_pk_mov_b32 v[232:233], v[136:137], v[152:153] op_sel:[0,0]
	v_pk_mov_b32 v[234:235], v[140:141], v[156:157] op_sel:[0,0]
	v_pk_mov_b32 v[244:245], v[144:145], v[160:161] op_sel:[0,0]
	v_pk_mov_b32 v[254:255], v[148:149], v[164:165] op_sel:[0,0]
	v_pk_fma_f32 v[232:233], v[32:33], v[200:201], v[232:233] op_sel_hi:[0,1,1]
	v_pk_fma_f32 v[234:235], v[34:35], v[202:203], v[234:235] op_sel_hi:[0,1,1]
	v_pk_fma_f32 v[244:245], v[36:37], v[204:205], v[244:245] op_sel_hi:[0,1,1]
	v_pk_fma_f32 v[254:255], v[38:39], v[206:207], v[254:255] op_sel_hi:[0,1,1]
	v_pk_fma_f32 v[200:201], v[32:33], v[200:201], v[232:233] op_sel:[1,1,0] op_sel_hi:[1,0,1] neg_lo:[1,0,0]
	v_pk_fma_f32 v[202:203], v[34:35], v[202:203], v[234:235] op_sel:[1,1,0] op_sel_hi:[1,0,1] neg_lo:[1,0,0]
	v_pk_fma_f32 v[204:205], v[36:37], v[204:205], v[244:245] op_sel:[1,1,0] op_sel_hi:[1,0,1] neg_lo:[1,0,0]
	v_pk_fma_f32 v[206:207], v[38:39], v[206:207], v[254:255] op_sel:[1,1,0] op_sel_hi:[1,0,1] neg_lo:[1,0,0]
	v_cvt_pk_bf16_f32 v124, v200, v201
	v_cvt_pk_bf16_f32 v125, v202, v203
	v_cvt_pk_bf16_f32 v126, v204, v205
	v_cvt_pk_bf16_f32 v127, v206, v207
	ds_write_b128 v241, v[124:127] offset:0
	v_pk_mov_b32 v[232:233], v[136:137], v[152:153] op_sel:[1,1]
	v_pk_mov_b32 v[234:235], v[140:141], v[156:157] op_sel:[1,1]
	v_pk_mov_b32 v[244:245], v[144:145], v[160:161] op_sel:[1,1]
	v_pk_mov_b32 v[254:255], v[148:149], v[164:165] op_sel:[1,1]
	v_pk_fma_f32 v[232:233], v[32:33], v[200:201], v[232:233] op_sel_hi:[0,1,1]
	v_pk_fma_f32 v[234:235], v[34:35], v[202:203], v[234:235] op_sel_hi:[0,1,1]
	v_pk_fma_f32 v[244:245], v[36:37], v[204:205], v[244:245] op_sel_hi:[0,1,1]
	v_pk_fma_f32 v[254:255], v[38:39], v[206:207], v[254:255] op_sel_hi:[0,1,1]
	v_pk_fma_f32 v[200:201], v[32:33], v[200:201], v[232:233] op_sel:[1,1,0] op_sel_hi:[1,0,1] neg_lo:[1,0,0]
	v_pk_fma_f32 v[202:203], v[34:35], v[202:203], v[234:235] op_sel:[1,1,0] op_sel_hi:[1,0,1] neg_lo:[1,0,0]
	v_pk_fma_f32 v[204:205], v[36:37], v[204:205], v[244:245] op_sel:[1,1,0] op_sel_hi:[1,0,1] neg_lo:[1,0,0]
	v_pk_fma_f32 v[206:207], v[38:39], v[206:207], v[254:255] op_sel:[1,1,0] op_sel_hi:[1,0,1] neg_lo:[1,0,0]
	v_cvt_pk_bf16_f32 v124, v200, v201
	v_cvt_pk_bf16_f32 v125, v202, v203
; __device__ __forceinline__ unsigned f2bf(float f) { unsigned u = __builtin_bit_cast(unsigned, f); return (u + 0x7fffu + ((u >> 16) & 1u)) >> 16; }
; __device__ __forceinline__ bf16x8 pack8(const float (&f)[8]) { u32x4 h; h.x = pk2(f[0], f[1]); h.y = pk2(f[2], f[3]); h.z = pk2(f[4], f[5]); h.w = pk2(f[6], f[7]); return __builtin_bit_cast(bf16x8, h); }
; template <bool FINAL> __device__ __forceinline__ void phase_s5_scan(const Fr& F) {
;     ...
;         for (int sub = 0; sub < 4; ++sub) {
;             const bf16x8 A1 = __builtin_bit_cast(bf16x8, uc[sub]);
; #pragma unroll
;             for (int nt = 0; nt < 8; ++nt) {
;                 f32x4 acc = {0.f, 0.f, 0.f, 0.f};
;                 acc = __builtin_amdgcn_mfma_f32_16x16x32_bf16(A1, B1[nt], acc, 0, 0, 0);
; #pragma unroll
;                 for (int reg = 0; reg < 4; ++reg) BUl[(4 * lq + reg) * 132 + 16 * nt + l15] = acc[reg];
;             }
;             asm volatile("s_waitcnt lgkmcnt(0)" ::: "memory");
; #pragma unroll 4
;             for (int jj = 0; jj < 16; ++jj) {
;                 const float br_ = BUl[jj * 132 + lane], bi_ = BUl[jj * 132 + 64 + lane];
;                 const float nr = ar * xr - ai * xi + br_, ni = ar * xi + ai * xr + bi_; xr = nr; xi = ni;
;                 if (FINAL) { BUl[jj * 132 + lane] = xr; BUl[jj * 132 + 64 + lane] = xi; }
;             }
;             if (FINAL) {
;                 asm volatile("s_waitcnt lgkmcnt(0)" ::: "memory");
;                 f32x4 acc = {0.f, 0.f, 0.f, 0.f};
; #pragma unroll
;                 for (int ks = 0; ks < 4; ++ks) {
;                     const f32x4 t0 = *(const f32x4*)(BUl + l15 * 132 + 32 * ks + 8 * lq), t1 = *(const f32x4*)(BUl + l15 * 132 + 32 * ks + 8 * lq + 4);
;                     const float xf[8] = {t0.x, t0.y, t0.z, t0.w, t1.x, t1.y, t1.z, t1.w};
;                     acc = __builtin_amdgcn_mfma_f32_16x16x32_bf16(pack8(xf), Chi[ks], acc, 0, 0, 0);
;                 }
; #pragma unroll
;                 for (int reg = 0; reg < 4; ++reg) { const int tok = tokof(s, chunk * 64 + sub * 16 + 4 * lq + reg);
;                     Yb[((size_t)b * TB + tok) * D + g * 16 + l15] = (bf16)f2bf(acc[reg]); }
;                 asm volatile("s_waitcnt lgkmcnt(0)" ::: "memory");
	v_cvt_pk_bf16_f32 v126, v204, v205
	v_cvt_pk_bf16_f32 v127, v206, v207
	ds_write_b128 v241, v[124:127] offset:288
	v_pk_mov_b32 v[232:233], v[138:139], v[154:155] op_sel:[0,0]
	v_pk_mov_b32 v[234:235], v[142:143], v[158:159] op_sel:[0,0]
	v_pk_mov_b32 v[244:245], v[146:147], v[162:163] op_sel:[0,0]
	v_pk_mov_b32 v[254:255], v[150:151], v[166:167] op_sel:[0,0]
	v_pk_fma_f32 v[232:233], v[32:33], v[200:201], v[232:233] op_sel_hi:[0,1,1]
	v_pk_fma_f32 v[234:235], v[34:35], v[202:203], v[234:235] op_sel_hi:[0,1,1]
	v_pk_fma_f32 v[244:245], v[36:37], v[204:205], v[244:245] op_sel_hi:[0,1,1]
	v_pk_fma_f32 v[254:255], v[38:39], v[206:207], v[254:255] op_sel_hi:[0,1,1]
	v_pk_fma_f32 v[200:201], v[32:33], v[200:201], v[232:233] op_sel:[1,1,0] op_sel_hi:[1,0,1] neg_lo:[1,0,0]
	v_pk_fma_f32 v[202:203], v[34:35], v[202:203], v[234:235] op_sel:[1,1,0] op_sel_hi:[1,0,1] neg_lo:[1,0,0]
	v_pk_fma_f32 v[204:205], v[36:37], v[204:205], v[244:245] op_sel:[1,1,0] op_sel_hi:[1,0,1] neg_lo:[1,0,0]
	v_pk_fma_f32 v[206:207], v[38:39], v[206:207], v[254:255] op_sel:[1,1,0] op_sel_hi:[1,0,1] neg_lo:[1,0,0]
	v_cvt_pk_bf16_f32 v124, v200, v201
	v_cvt_pk_bf16_f32 v125, v202, v203
	v_cvt_pk_bf16_f32 v126, v204, v205
	v_cvt_pk_bf16_f32 v127, v206, v207
	ds_write_b128 v241, v[124:127] offset:576
	v_pk_mov_b32 v[232:233], v[138:139], v[154:155] op_sel:[1,1]
	v_pk_mov_b32 v[234:235], v[142:143], v[158:159] op_sel:[1,1]
	v_pk_mov_b32 v[244:245], v[146:147], v[162:163] op_sel:[1,1]
	v_pk_mov_b32 v[254:255], v[150:151], v[166:167] op_sel:[1,1]
	v_pk_fma_f32 v[232:233], v[32:33], v[200:201], v[232:233] op_sel_hi:[0,1,1]
	v_pk_fma_f32 v[234:235], v[34:35], v[202:203], v[234:235] op_sel_hi:[0,1,1]
	v_pk_fma_f32 v[244:245], v[36:37], v[204:205], v[244:245] op_sel_hi:[0,1,1]
	v_pk_fma_f32 v[254:255], v[38:39], v[206:207], v[254:255] op_sel_hi:[0,1,1]
	v_pk_fma_f32 v[200:201], v[32:33], v[200:201], v[232:233] op_sel:[1,1,0] op_sel_hi:[1,0,1] neg_lo:[1,0,0]
	v_pk_fma_f32 v[202:203], v[34:35], v[202:203], v[234:235] op_sel:[1,1,0] op_sel_hi:[1,0,1] neg_lo:[1,0,0]
	v_pk_fma_f32 v[204:205], v[36:37], v[204:205], v[244:245] op_sel:[1,1,0] op_sel_hi:[1,0,1] neg_lo:[1,0,0]
	v_pk_fma_f32 v[206:207], v[38:39], v[206:207], v[254:255] op_sel:[1,1,0] op_sel_hi:[1,0,1] neg_lo:[1,0,0]
	v_cvt_pk_bf16_f32 v124, v200, v201
	v_cvt_pk_bf16_f32 v125, v202, v203
	v_cvt_pk_bf16_f32 v126, v204, v205
	v_cvt_pk_bf16_f32 v127, v206, v207
	ds_write_b128 v241, v[124:127] offset:864
	global_load_dwordx4 v[56:59], v238, s[20:21]
	v_add_u32_e32 v238, v238, v243
	s_waitcnt vmcnt(33)
	v_mfma_f32_16x16x32_bf16 v[136:139], v[64:67], v[0:3], 0
	v_mfma_f32_16x16x32_bf16 v[140:143], v[64:67], v[4:7], 0
	v_mfma_f32_16x16x32_bf16 v[144:147], v[64:67], v[8:11], 0
	v_mfma_f32_16x16x32_bf16 v[148:151], v[64:67], v[12:15], 0
	v_mfma_f32_16x16x32_bf16 v[152:155], v[64:67], v[16:19], 0
	v_mfma_f32_16x16x32_bf16 v[156:159], v[64:67], v[20:23], 0
	v_mfma_f32_16x16x32_bf16 v[160:163], v[64:67], v[24:27], 0
	v_mfma_f32_16x16x32_bf16 v[164:167], v[64:67], v[28:31], 0
	ds_read_b128 v[216:219], v242 offset:0
	ds_read_b128 v[220:223], v242 offset:64
	ds_read_b128 v[224:227], v242 offset:128
	ds_read_b128 v[228:231], v242 offset:192
	v_pk_mov_b32 v[232:233], v[168:169], v[184:185] op_sel:[0,0]
	v_pk_mov_b32 v[234:235], v[172:173], v[188:189] op_sel:[0,0]
	v_pk_mov_b32 v[244:245], v[176:177], v[192:193] op_sel:[0,0]
	v_pk_mov_b32 v[254:255], v[180:181], v[196:197] op_sel:[0,0]
	v_pk_fma_f32 v[232:233], v[32:33], v[200:201], v[232:233] op_sel_hi:[0,1,1]
	v_pk_fma_f32 v[234:235], v[34:35], v[202:203], v[234:235] op_sel_hi:[0,1,1]
	v_pk_fma_f32 v[244:245], v[36:37], v[204:205], v[244:245] op_sel_hi:[0,1,1]
	v_pk_fma_f32 v[254:255], v[38:39], v[206:207], v[254:255] op_sel_hi:[0,1,1]
	v_pk_fma_f32 v[200:201], v[32:33], v[200:201], v[232:233] op_sel:[1,1,0] op_sel_hi:[1,0,1] neg_lo:[1,0,0]
	v_pk_fma_f32 v[202:203], v[34:35], v[202:203], v[234:235] op_sel:[1,1,0] op_sel_hi:[1,0,1] neg_lo:[1,0,0]
	v_pk_fma_f32 v[204:205], v[36:37], v[204:205], v[244:245] op_sel:[1,1,0] op_sel_hi:[1,0,1] neg_lo:[1,0,0]
	v_pk_fma_f32 v[206:207], v[38:39], v[206:207], v[254:255] op_sel:[1,1,0] op_sel_hi:[1,0,1] neg_lo:[1,0,0]
	v_cvt_pk_bf16_f32 v124, v200, v201
	v_cvt_pk_bf16_f32 v125, v202, v203
	v_cvt_pk_bf16_f32 v126, v204, v205
	v_cvt_pk_bf16_f32 v127, v206, v207
	ds_write_b128 v241, v[124:127] offset:4608
	v_pk_mov_b32 v[232:233], v[168:169], v[184:185] op_sel:[1,1]
	v_pk_mov_b32 v[234:235], v[172:173], v[188:189] op_sel:[1,1]
	v_pk_mov_b32 v[244:245], v[176:177], v[192:193] op_sel:[1,1]
	v_pk_mov_b32 v[254:255], v[180:181], v[196:197] op_sel:[1,1]
	v_pk_fma_f32 v[232:233], v[32:33], v[200:201], v[232:233] op_sel_hi:[0,1,1]
	v_pk_fma_f32 v[234:235], v[34:35], v[202:203], v[234:235] op_sel_hi:[0,1,1]
	v_pk_fma_f32 v[244:245], v[36:37], v[204:205], v[244:245] op_sel_hi:[0,1,1]
	v_pk_fma_f32 v[254:255], v[38:39], v[206:207], v[254:255] op_sel_hi:[0,1,1]
	v_pk_fma_f32 v[200:201], v[32:33], v[200:201], v[232:233] op_sel:[1,1,0] op_sel_hi:[1,0,1] neg_lo:[1,0,0]
	v_pk_fma_f32 v[202:203], v[34:35], v[202:203], v[234:235] op_sel:[1,1,0] op_sel_hi:[1,0,1] neg_lo:[1,0,0]
	v_pk_fma_f32 v[204:205], v[36:37], v[204:205], v[244:245] op_sel:[1,1,0] op_sel_hi:[1,0,1] neg_lo:[1,0,0]
	v_pk_fma_f32 v[206:207], v[38:39], v[206:207], v[254:255] op_sel:[1,1,0] op_sel_hi:[1,0,1] neg_lo:[1,0,0]
	v_cvt_pk_bf16_f32 v124, v200, v201
	v_cvt_pk_bf16_f32 v125, v202, v203
	v_cvt_pk_bf16_f32 v126, v204, v205
	v_cvt_pk_bf16_f32 v127, v206, v207
	ds_write_b128 v241, v[124:127] offset:4896
	s_waitcnt lgkmcnt(2)
; __device__ __forceinline__ unsigned f2bf(float f) { unsigned u = __builtin_bit_cast(unsigned, f); return (u + 0x7fffu + ((u >> 16) & 1u)) >> 16; }
; __device__ __forceinline__ bf16x8 pack8(const float (&f)[8]) { u32x4 h; h.x = pk2(f[0], f[1]); h.y = pk2(f[2], f[3]); h.z = pk2(f[4], f[5]); h.w = pk2(f[6], f[7]); return __builtin_bit_cast(bf16x8, h); }
; template <bool FINAL> __device__ __forceinline__ void phase_s5_scan(const Fr& F) {
;     ...
;         for (int sub = 0; sub < 4; ++sub) {
;             const bf16x8 A1 = __builtin_bit_cast(bf16x8, uc[sub]);
; #pragma unroll
;             for (int nt = 0; nt < 8; ++nt) {
;                 f32x4 acc = {0.f, 0.f, 0.f, 0.f};
;                 acc = __builtin_amdgcn_mfma_f32_16x16x32_bf16(A1, B1[nt], acc, 0, 0, 0);
; #pragma unroll
;                 for (int reg = 0; reg < 4; ++reg) BUl[(4 * lq + reg) * 132 + 16 * nt + l15] = acc[reg];
;             }
;             asm volatile("s_waitcnt lgkmcnt(0)" ::: "memory");
; #pragma unroll 4
;             for (int jj = 0; jj < 16; ++jj) {
;                 const float br_ = BUl[jj * 132 + lane], bi_ = BUl[jj * 132 + 64 + lane];
;                 const float nr = ar * xr - ai * xi + br_, ni = ar * xi + ai * xr + bi_; xr = nr; xi = ni;
;                 if (FINAL) { BUl[jj * 132 + lane] = xr; BUl[jj * 132 + 64 + lane] = xi; }
;             }
;             if (FINAL) {
;                 asm volatile("s_waitcnt lgkmcnt(0)" ::: "memory");
;                 f32x4 acc = {0.f, 0.f, 0.f, 0.f};
; #pragma unroll
;                 for (int ks = 0; ks < 4; ++ks) {
;                     const f32x4 t0 = *(const f32x4*)(BUl + l15 * 132 + 32 * ks + 8 * lq), t1 = *(const f32x4*)(BUl + l15 * 132 + 32 * ks + 8 * lq + 4);
;                     const float xf[8] = {t0.x, t0.y, t0.z, t0.w, t1.x, t1.y, t1.z, t1.w};
;                     acc = __builtin_amdgcn_mfma_f32_16x16x32_bf16(pack8(xf), Chi[ks], acc, 0, 0, 0);
;                 }
; #pragma unroll
;                 for (int reg = 0; reg < 4; ++reg) { const int tok = tokof(s, chunk * 64 + sub * 16 + 4 * lq + reg);
;                     Yb[((size_t)b * TB + tok) * D + g * 16 + l15] = (bf16)f2bf(acc[reg]); }
;                 asm volatile("s_waitcnt lgkmcnt(0)" ::: "memory");
	v_mfma_f32_16x16x32_bf16 v[120:123], v[40:43], v[216:219], 0
	v_mfma_f32_16x16x32_bf16 v[120:123], v[44:47], v[220:223], v[120:123]
	v_mfma_f32_16x16x32_bf16 v[120:123], v[48:51], v[224:227], v[120:123]
	v_mfma_f32_16x16x32_bf16 v[120:123], v[52:55], v[228:231], v[120:123]
	v_pk_mov_b32 v[232:233], v[170:171], v[186:187] op_sel:[0,0]
	v_pk_mov_b32 v[234:235], v[174:175], v[190:191] op_sel:[0,0]
	v_pk_mov_b32 v[244:245], v[178:179], v[194:195] op_sel:[0,0]
	v_pk_mov_b32 v[254:255], v[182:183], v[198:199] op_sel:[0,0]
	v_pk_fma_f32 v[232:233], v[32:33], v[200:201], v[232:233] op_sel_hi:[0,1,1]
	v_pk_fma_f32 v[234:235], v[34:35], v[202:203], v[234:235] op_sel_hi:[0,1,1]
	v_pk_fma_f32 v[244:245], v[36:37], v[204:205], v[244:245] op_sel_hi:[0,1,1]
	v_pk_fma_f32 v[254:255], v[38:39], v[206:207], v[254:255] op_sel_hi:[0,1,1]
	v_pk_fma_f32 v[200:201], v[32:33], v[200:201], v[232:233] op_sel:[1,1,0] op_sel_hi:[1,0,1] neg_lo:[1,0,0]
	v_pk_fma_f32 v[202:203], v[34:35], v[202:203], v[234:235] op_sel:[1,1,0] op_sel_hi:[1,0,1] neg_lo:[1,0,0]
	v_pk_fma_f32 v[204:205], v[36:37], v[204:205], v[244:245] op_sel:[1,1,0] op_sel_hi:[1,0,1] neg_lo:[1,0,0]
	v_pk_fma_f32 v[206:207], v[38:39], v[206:207], v[254:255] op_sel:[1,1,0] op_sel_hi:[1,0,1] neg_lo:[1,0,0]
	v_cvt_pk_bf16_f32 v124, v200, v201
	v_cvt_pk_bf16_f32 v125, v202, v203
	v_cvt_pk_bf16_f32 v126, v204, v205
	v_cvt_pk_bf16_f32 v127, v206, v207
	ds_write_b128 v241, v[124:127] offset:5184
	v_pk_mov_b32 v[232:233], v[170:171], v[186:187] op_sel:[1,1]
	v_pk_mov_b32 v[234:235], v[174:175], v[190:191] op_sel:[1,1]
	v_pk_mov_b32 v[244:245], v[178:179], v[194:195] op_sel:[1,1]
	v_pk_mov_b32 v[254:255], v[182:183], v[198:199] op_sel:[1,1]
	v_pk_fma_f32 v[232:233], v[32:33], v[200:201], v[232:233] op_sel_hi:[0,1,1]
	v_pk_fma_f32 v[234:235], v[34:35], v[202:203], v[234:235] op_sel_hi:[0,1,1]
	v_pk_fma_f32 v[244:245], v[36:37], v[204:205], v[244:245] op_sel_hi:[0,1,1]
	v_pk_fma_f32 v[254:255], v[38:39], v[206:207], v[254:255] op_sel_hi:[0,1,1]
	v_pk_fma_f32 v[200:201], v[32:33], v[200:201], v[232:233] op_sel:[1,1,0] op_sel_hi:[1,0,1] neg_lo:[1,0,0]
	v_pk_fma_f32 v[202:203], v[34:35], v[202:203], v[234:235] op_sel:[1,1,0] op_sel_hi:[1,0,1] neg_lo:[1,0,0]
	v_pk_fma_f32 v[204:205], v[36:37], v[204:205], v[244:245] op_sel:[1,1,0] op_sel_hi:[1,0,1] neg_lo:[1,0,0]
	v_pk_fma_f32 v[206:207], v[38:39], v[206:207], v[254:255] op_sel:[1,1,0] op_sel_hi:[1,0,1] neg_lo:[1,0,0]
	v_cvt_pk_bf16_f32 v124, v200, v201
	v_cvt_pk_bf16_f32 v125, v202, v203
	v_cvt_pk_bf16_f32 v126, v204, v205
	v_cvt_pk_bf16_f32 v127, v206, v207
	ds_write_b128 v241, v[124:127] offset:5472
	global_load_dwordx4 v[60:63], v238, s[20:21]
	v_add_u32_e32 v238, v238, v243
	v_cvt_pk_bf16_f32 v124, v120, v121
	v_cvt_pk_bf16_f32 v125, v122, v123
	s_nop 0
	global_store_dwordx2 v239, v[124:125], s[24:25]
	v_add_u32_e32 v239, v239, v243
	s_waitcnt vmcnt(33)
	v_mfma_f32_16x16x32_bf16 v[168:171], v[68:71], v[0:3], 0
	v_mfma_f32_16x16x32_bf16 v[172:175], v[68:71], v[4:7], 0
	v_mfma_f32_16x16x32_bf16 v[176:179], v[68:71], v[8:11], 0
	v_mfma_f32_16x16x32_bf16 v[180:183], v[68:71], v[12:15], 0
	v_mfma_f32_16x16x32_bf16 v[184:187], v[68:71], v[16:19], 0
	v_mfma_f32_16x16x32_bf16 v[188:191], v[68:71], v[20:23], 0
	v_mfma_f32_16x16x32_bf16 v[192:195], v[68:71], v[24:27], 0
	v_mfma_f32_16x16x32_bf16 v[196:199], v[68:71], v[28:31], 0
	ds_read_b128 v[216:219], v242 offset:4608
	ds_read_b128 v[220:223], v242 offset:4672
	ds_read_b128 v[224:227], v242 offset:4736
	ds_read_b128 v[228:231], v242 offset:4800
	v_pk_mov_b32 v[232:233], v[136:137], v[152:153] op_sel:[0,0]
	v_pk_mov_b32 v[234:235], v[140:141], v[156:157] op_sel:[0,0]
	v_pk_mov_b32 v[244:245], v[144:145], v[160:161] op_sel:[0,0]
	v_pk_mov_b32 v[254:255], v[148:149], v[164:165] op_sel:[0,0]
	v_pk_fma_f32 v[232:233], v[32:33], v[200:201], v[232:233] op_sel_hi:[0,1,1]
	v_pk_fma_f32 v[234:235], v[34:35], v[202:203], v[234:235] op_sel_hi:[0,1,1]
	v_pk_fma_f32 v[244:245], v[36:37], v[204:205], v[244:245] op_sel_hi:[0,1,1]
	v_pk_fma_f32 v[254:255], v[38:39], v[206:207], v[254:255] op_sel_hi:[0,1,1]
	v_pk_fma_f32 v[200:201], v[32:33], v[200:201], v[232:233] op_sel:[1,1,0] op_sel_hi:[1,0,1] neg_lo:[1,0,0]
	v_pk_fma_f32 v[202:203], v[34:35], v[202:203], v[234:235] op_sel:[1,1,0] op_sel_hi:[1,0,1] neg_lo:[1,0,0]
	v_pk_fma_f32 v[204:205], v[36:37], v[204:205], v[244:245] op_sel:[1,1,0] op_sel_hi:[1,0,1] neg_lo:[1,0,0]
	v_pk_fma_f32 v[206:207], v[38:39], v[206:207], v[254:255] op_sel:[1,1,0] op_sel_hi:[1,0,1] neg_lo:[1,0,0]
	v_cvt_pk_bf16_f32 v124, v200, v201
	v_cvt_pk_bf16_f32 v125, v202, v203
	v_cvt_pk_bf16_f32 v126, v204, v205
	v_cvt_pk_bf16_f32 v127, v206, v207
	ds_write_b128 v241, v[124:127] offset:0
	v_pk_mov_b32 v[232:233], v[136:137], v[152:153] op_sel:[1,1]
	v_pk_mov_b32 v[234:235], v[140:141], v[156:157] op_sel:[1,1]
	v_pk_mov_b32 v[244:245], v[144:145], v[160:161] op_sel:[1,1]
	v_pk_mov_b32 v[254:255], v[148:149], v[164:165] op_sel:[1,1]
	v_pk_fma_f32 v[232:233], v[32:33], v[200:201], v[232:233] op_sel_hi:[0,1,1]
	v_pk_fma_f32 v[234:235], v[34:35], v[202:203], v[234:235] op_sel_hi:[0,1,1]
	v_pk_fma_f32 v[244:245], v[36:37], v[204:205], v[244:245] op_sel_hi:[0,1,1]
	v_pk_fma_f32 v[254:255], v[38:39], v[206:207], v[254:255] op_sel_hi:[0,1,1]
	v_pk_fma_f32 v[200:201], v[32:33], v[200:201], v[232:233] op_sel:[1,1,0] op_sel_hi:[1,0,1] neg_lo:[1,0,0]
	v_pk_fma_f32 v[202:203], v[34:35], v[202:203], v[234:235] op_sel:[1,1,0] op_sel_hi:[1,0,1] neg_lo:[1,0,0]
	v_pk_fma_f32 v[204:205], v[36:37], v[204:205], v[244:245] op_sel:[1,1,0] op_sel_hi:[1,0,1] neg_lo:[1,0,0]
	v_pk_fma_f32 v[206:207], v[38:39], v[206:207], v[254:255] op_sel:[1,1,0] op_sel_hi:[1,0,1] neg_lo:[1,0,0]
	v_cvt_pk_bf16_f32 v124, v200, v201
	v_cvt_pk_bf16_f32 v125, v202, v203
	v_cvt_pk_bf16_f32 v126, v204, v205
	v_cvt_pk_bf16_f32 v127, v206, v207
	ds_write_b128 v241, v[124:127] offset:288
	s_waitcnt lgkmcnt(2)
; __device__ __forceinline__ unsigned f2bf(float f) { unsigned u = __builtin_bit_cast(unsigned, f); return (u + 0x7fffu + ((u >> 16) & 1u)) >> 16; }
; __device__ __forceinline__ bf16x8 pack8(const float (&f)[8]) { u32x4 h; h.x = pk2(f[0], f[1]); h.y = pk2(f[2], f[3]); h.z = pk2(f[4], f[5]); h.w = pk2(f[6], f[7]); return __builtin_bit_cast(bf16x8, h); }
; template <bool FINAL> __device__ __forceinline__ void phase_s5_scan(const Fr& F) {
;     ...
;         for (int sub = 0; sub < 4; ++sub) {
;             const bf16x8 A1 = __builtin_bit_cast(bf16x8, uc[sub]);
; #pragma unroll
;             for (int nt = 0; nt < 8; ++nt) {
;                 f32x4 acc = {0.f, 0.f, 0.f, 0.f};
;                 acc = __builtin_amdgcn_mfma_f32_16x16x32_bf16(A1, B1[nt], acc, 0, 0, 0);
; #pragma unroll
;                 for (int reg = 0; reg < 4; ++reg) BUl[(4 * lq + reg) * 132 + 16 * nt + l15] = acc[reg];
;             }
;             asm volatile("s_waitcnt lgkmcnt(0)" ::: "memory");
; #pragma unroll 4
;             for (int jj = 0; jj < 16; ++jj) {
;                 const float br_ = BUl[jj * 132 + lane], bi_ = BUl[jj * 132 + 64 + lane];
;                 const float nr = ar * xr - ai * xi + br_, ni = ar * xi + ai * xr + bi_; xr = nr; xi = ni;
;                 if (FINAL) { BUl[jj * 132 + lane] = xr; BUl[jj * 132 + 64 + lane] = xi; }
;             }
;             if (FINAL) {
;                 asm volatile("s_waitcnt lgkmcnt(0)" ::: "memory");
;                 f32x4 acc = {0.f, 0.f, 0.f, 0.f};
; #pragma unroll
;                 for (int ks = 0; ks < 4; ++ks) {
;                     const f32x4 t0 = *(const f32x4*)(BUl + l15 * 132 + 32 * ks + 8 * lq), t1 = *(const f32x4*)(BUl + l15 * 132 + 32 * ks + 8 * lq + 4);
;                     const float xf[8] = {t0.x, t0.y, t0.z, t0.w, t1.x, t1.y, t1.z, t1.w};
;                     acc = __builtin_amdgcn_mfma_f32_16x16x32_bf16(pack8(xf), Chi[ks], acc, 0, 0, 0);
;                 }
; #pragma unroll
;                 for (int reg = 0; reg < 4; ++reg) { const int tok = tokof(s, chunk * 64 + sub * 16 + 4 * lq + reg);
;                     Yb[((size_t)b * TB + tok) * D + g * 16 + l15] = (bf16)f2bf(acc[reg]); }
;                 asm volatile("s_waitcnt lgkmcnt(0)" ::: "memory");
	v_mfma_f32_16x16x32_bf16 v[120:123], v[40:43], v[216:219], 0
	v_mfma_f32_16x16x32_bf16 v[120:123], v[44:47], v[220:223], v[120:123]
	v_mfma_f32_16x16x32_bf16 v[120:123], v[48:51], v[224:227], v[120:123]
	v_mfma_f32_16x16x32_bf16 v[120:123], v[52:55], v[228:231], v[120:123]
	v_pk_mov_b32 v[232:233], v[138:139], v[154:155] op_sel:[0,0]
	v_pk_mov_b32 v[234:235], v[142:143], v[158:159] op_sel:[0,0]
	v_pk_mov_b32 v[244:245], v[146:147], v[162:163] op_sel:[0,0]
	v_pk_mov_b32 v[254:255], v[150:151], v[166:167] op_sel:[0,0]
	v_pk_fma_f32 v[232:233], v[32:33], v[200:201], v[232:233] op_sel_hi:[0,1,1]
	v_pk_fma_f32 v[234:235], v[34:35], v[202:203], v[234:235] op_sel_hi:[0,1,1]
	v_pk_fma_f32 v[244:245], v[36:37], v[204:205], v[244:245] op_sel_hi:[0,1,1]
	v_pk_fma_f32 v[254:255], v[38:39], v[206:207], v[254:255] op_sel_hi:[0,1,1]
	v_pk_fma_f32 v[200:201], v[32:33], v[200:201], v[232:233] op_sel:[1,1,0] op_sel_hi:[1,0,1] neg_lo:[1,0,0]
	v_pk_fma_f32 v[202:203], v[34:35], v[202:203], v[234:235] op_sel:[1,1,0] op_sel_hi:[1,0,1] neg_lo:[1,0,0]
	v_pk_fma_f32 v[204:205], v[36:37], v[204:205], v[244:245] op_sel:[1,1,0] op_sel_hi:[1,0,1] neg_lo:[1,0,0]
	v_pk_fma_f32 v[206:207], v[38:39], v[206:207], v[254:255] op_sel:[1,1,0] op_sel_hi:[1,0,1] neg_lo:[1,0,0]
	v_cvt_pk_bf16_f32 v124, v200, v201
	v_cvt_pk_bf16_f32 v125, v202, v203
	v_cvt_pk_bf16_f32 v126, v204, v205
	v_cvt_pk_bf16_f32 v127, v206, v207
	ds_write_b128 v241, v[124:127] offset:576
	v_pk_mov_b32 v[232:233], v[138:139], v[154:155] op_sel:[1,1]
	v_pk_mov_b32 v[234:235], v[142:143], v[158:159] op_sel:[1,1]
	v_pk_mov_b32 v[244:245], v[146:147], v[162:163] op_sel:[1,1]
	v_pk_mov_b32 v[254:255], v[150:151], v[166:167] op_sel:[1,1]
	v_pk_fma_f32 v[232:233], v[32:33], v[200:201], v[232:233] op_sel_hi:[0,1,1]
	v_pk_fma_f32 v[234:235], v[34:35], v[202:203], v[234:235] op_sel_hi:[0,1,1]
	v_pk_fma_f32 v[244:245], v[36:37], v[204:205], v[244:245] op_sel_hi:[0,1,1]
	v_pk_fma_f32 v[254:255], v[38:39], v[206:207], v[254:255] op_sel_hi:[0,1,1]
	v_pk_fma_f32 v[200:201], v[32:33], v[200:201], v[232:233] op_sel:[1,1,0] op_sel_hi:[1,0,1] neg_lo:[1,0,0]
	v_pk_fma_f32 v[202:203], v[34:35], v[202:203], v[234:235] op_sel:[1,1,0] op_sel_hi:[1,0,1] neg_lo:[1,0,0]
	v_pk_fma_f32 v[204:205], v[36:37], v[204:205], v[244:245] op_sel:[1,1,0] op_sel_hi:[1,0,1] neg_lo:[1,0,0]
	v_pk_fma_f32 v[206:207], v[38:39], v[206:207], v[254:255] op_sel:[1,1,0] op_sel_hi:[1,0,1] neg_lo:[1,0,0]
	v_cvt_pk_bf16_f32 v124, v200, v201
	v_cvt_pk_bf16_f32 v125, v202, v203
	v_cvt_pk_bf16_f32 v126, v204, v205
	v_cvt_pk_bf16_f32 v127, v206, v207
	ds_write_b128 v241, v[124:127] offset:864
	global_load_dwordx4 v[64:67], v238, s[20:21]
	v_add_u32_e32 v238, v238, v243
	v_cvt_pk_bf16_f32 v124, v120, v121
	v_cvt_pk_bf16_f32 v125, v122, v123
	s_nop 0
	global_store_dwordx2 v239, v[124:125], s[24:25]
	v_add_u32_e32 v239, v239, v243
	s_waitcnt vmcnt(33)
	v_mfma_f32_16x16x32_bf16 v[136:139], v[72:75], v[0:3], 0
	v_mfma_f32_16x16x32_bf16 v[140:143], v[72:75], v[4:7], 0
	v_mfma_f32_16x16x32_bf16 v[144:147], v[72:75], v[8:11], 0
	v_mfma_f32_16x16x32_bf16 v[148:151], v[72:75], v[12:15], 0
	v_mfma_f32_16x16x32_bf16 v[152:155], v[72:75], v[16:19], 0
	v_mfma_f32_16x16x32_bf16 v[156:159], v[72:75], v[20:23], 0
	v_mfma_f32_16x16x32_bf16 v[160:163], v[72:75], v[24:27], 0
	v_mfma_f32_16x16x32_bf16 v[164:167], v[72:75], v[28:31], 0
	ds_read_b128 v[216:219], v242 offset:0
	ds_read_b128 v[220:223], v242 offset:64
	ds_read_b128 v[224:227], v242 offset:128
	ds_read_b128 v[228:231], v242 offset:192
	v_pk_mov_b32 v[232:233], v[168:169], v[184:185] op_sel:[0,0]
	v_pk_mov_b32 v[234:235], v[172:173], v[188:189] op_sel:[0,0]
	v_pk_mov_b32 v[244:245], v[176:177], v[192:193] op_sel:[0,0]
	v_pk_mov_b32 v[254:255], v[180:181], v[196:197] op_sel:[0,0]
	v_pk_fma_f32 v[232:233], v[32:33], v[200:201], v[232:233] op_sel_hi:[0,1,1]
	v_pk_fma_f32 v[234:235], v[34:35], v[202:203], v[234:235] op_sel_hi:[0,1,1]
	v_pk_fma_f32 v[244:245], v[36:37], v[204:205], v[244:245] op_sel_hi:[0,1,1]
	v_pk_fma_f32 v[254:255], v[38:39], v[206:207], v[254:255] op_sel_hi:[0,1,1]
	v_pk_fma_f32 v[200:201], v[32:33], v[200:201], v[232:233] op_sel:[1,1,0] op_sel_hi:[1,0,1] neg_lo:[1,0,0]
	v_pk_fma_f32 v[202:203], v[34:35], v[202:203], v[234:235] op_sel:[1,1,0] op_sel_hi:[1,0,1] neg_lo:[1,0,0]
	v_pk_fma_f32 v[204:205], v[36:37], v[204:205], v[244:245] op_sel:[1,1,0] op_sel_hi:[1,0,1] neg_lo:[1,0,0]
	v_pk_fma_f32 v[206:207], v[38:39], v[206:207], v[254:255] op_sel:[1,1,0] op_sel_hi:[1,0,1] neg_lo:[1,0,0]
	v_cvt_pk_bf16_f32 v124, v200, v201
	v_cvt_pk_bf16_f32 v125, v202, v203
	v_cvt_pk_bf16_f32 v126, v204, v205
	v_cvt_pk_bf16_f32 v127, v206, v207
	ds_write_b128 v241, v[124:127] offset:4608
	v_pk_mov_b32 v[232:233], v[168:169], v[184:185] op_sel:[1,1]
	v_pk_mov_b32 v[234:235], v[172:173], v[188:189] op_sel:[1,1]
	v_pk_mov_b32 v[244:245], v[176:177], v[192:193] op_sel:[1,1]
	v_pk_mov_b32 v[254:255], v[180:181], v[196:197] op_sel:[1,1]
	v_pk_fma_f32 v[232:233], v[32:33], v[200:201], v[232:233] op_sel_hi:[0,1,1]
	v_pk_fma_f32 v[234:235], v[34:35], v[202:203], v[234:235] op_sel_hi:[0,1,1]
	v_pk_fma_f32 v[244:245], v[36:37], v[204:205], v[244:245] op_sel_hi:[0,1,1]
	v_pk_fma_f32 v[254:255], v[38:39], v[206:207], v[254:255] op_sel_hi:[0,1,1]
	v_pk_fma_f32 v[200:201], v[32:33], v[200:201], v[232:233] op_sel:[1,1,0] op_sel_hi:[1,0,1] neg_lo:[1,0,0]
	v_pk_fma_f32 v[202:203], v[34:35], v[202:203], v[234:235] op_sel:[1,1,0] op_sel_hi:[1,0,1] neg_lo:[1,0,0]
	v_pk_fma_f32 v[204:205], v[36:37], v[204:205], v[244:245] op_sel:[1,1,0] op_sel_hi:[1,0,1] neg_lo:[1,0,0]
	v_pk_fma_f32 v[206:207], v[38:39], v[206:207], v[254:255] op_sel:[1,1,0] op_sel_hi:[1,0,1] neg_lo:[1,0,0]
	v_cvt_pk_bf16_f32 v124, v200, v201
	v_cvt_pk_bf16_f32 v125, v202, v203
	v_cvt_pk_bf16_f32 v126, v204, v205
	v_cvt_pk_bf16_f32 v127, v206, v207
	ds_write_b128 v241, v[124:127] offset:4896
	s_waitcnt lgkmcnt(2)
; __device__ __forceinline__ unsigned f2bf(float f) { unsigned u = __builtin_bit_cast(unsigned, f); return (u + 0x7fffu + ((u >> 16) & 1u)) >> 16; }
; __device__ __forceinline__ bf16x8 pack8(const float (&f)[8]) { u32x4 h; h.x = pk2(f[0], f[1]); h.y = pk2(f[2], f[3]); h.z = pk2(f[4], f[5]); h.w = pk2(f[6], f[7]); return __builtin_bit_cast(bf16x8, h); }
; template <bool FINAL> __device__ __forceinline__ void phase_s5_scan(const Fr& F) {
;     ...
;         for (int sub = 0; sub < 4; ++sub) {
;             const bf16x8 A1 = __builtin_bit_cast(bf16x8, uc[sub]);
; #pragma unroll
;             for (int nt = 0; nt < 8; ++nt) {
;                 f32x4 acc = {0.f, 0.f, 0.f, 0.f};
;                 acc = __builtin_amdgcn_mfma_f32_16x16x32_bf16(A1, B1[nt], acc, 0, 0, 0);
; #pragma unroll
;                 for (int reg = 0; reg < 4; ++reg) BUl[(4 * lq + reg) * 132 + 16 * nt + l15] = acc[reg];
;             }
;             asm volatile("s_waitcnt lgkmcnt(0)" ::: "memory");
; #pragma unroll 4
;             for (int jj = 0; jj < 16; ++jj) {
;                 const float br_ = BUl[jj * 132 + lane], bi_ = BUl[jj * 132 + 64 + lane];
;                 const float nr = ar * xr - ai * xi + br_, ni = ar * xi + ai * xr + bi_; xr = nr; xi = ni;
;                 if (FINAL) { BUl[jj * 132 + lane] = xr; BUl[jj * 132 + 64 + lane] = xi; }
;             }
;             if (FINAL) {
;                 asm volatile("s_waitcnt lgkmcnt(0)" ::: "memory");
;                 f32x4 acc = {0.f, 0.f, 0.f, 0.f};
; #pragma unroll
;                 for (int ks = 0; ks < 4; ++ks) {
;                     const f32x4 t0 = *(const f32x4*)(BUl + l15 * 132 + 32 * ks + 8 * lq), t1 = *(const f32x4*)(BUl + l15 * 132 + 32 * ks + 8 * lq + 4);
;                     const float xf[8] = {t0.x, t0.y, t0.z, t0.w, t1.x, t1.y, t1.z, t1.w};
;                     acc = __builtin_amdgcn_mfma_f32_16x16x32_bf16(pack8(xf), Chi[ks], acc, 0, 0, 0);
;                 }
; #pragma unroll
;                 for (int reg = 0; reg < 4; ++reg) { const int tok = tokof(s, chunk * 64 + sub * 16 + 4 * lq + reg);
;                     Yb[((size_t)b * TB + tok) * D + g * 16 + l15] = (bf16)f2bf(acc[reg]); }
;                 asm volatile("s_waitcnt lgkmcnt(0)" ::: "memory");
	v_mfma_f32_16x16x32_bf16 v[120:123], v[40:43], v[216:219], 0
	v_mfma_f32_16x16x32_bf16 v[120:123], v[44:47], v[220:223], v[120:123]
	v_mfma_f32_16x16x32_bf16 v[120:123], v[48:51], v[224:227], v[120:123]
	v_mfma_f32_16x16x32_bf16 v[120:123], v[52:55], v[228:231], v[120:123]
	v_pk_mov_b32 v[232:233], v[170:171], v[186:187] op_sel:[0,0]
	v_pk_mov_b32 v[234:235], v[174:175], v[190:191] op_sel:[0,0]
	v_pk_mov_b32 v[244:245], v[178:179], v[194:195] op_sel:[0,0]
	v_pk_mov_b32 v[254:255], v[182:183], v[198:199] op_sel:[0,0]
	v_pk_fma_f32 v[232:233], v[32:33], v[200:201], v[232:233] op_sel_hi:[0,1,1]
	v_pk_fma_f32 v[234:235], v[34:35], v[202:203], v[234:235] op_sel_hi:[0,1,1]
	v_pk_fma_f32 v[244:245], v[36:37], v[204:205], v[244:245] op_sel_hi:[0,1,1]
	v_pk_fma_f32 v[254:255], v[38:39], v[206:207], v[254:255] op_sel_hi:[0,1,1]
	v_pk_fma_f32 v[200:201], v[32:33], v[200:201], v[232:233] op_sel:[1,1,0] op_sel_hi:[1,0,1] neg_lo:[1,0,0]
	v_pk_fma_f32 v[202:203], v[34:35], v[202:203], v[234:235] op_sel:[1,1,0] op_sel_hi:[1,0,1] neg_lo:[1,0,0]
	v_pk_fma_f32 v[204:205], v[36:37], v[204:205], v[244:245] op_sel:[1,1,0] op_sel_hi:[1,0,1] neg_lo:[1,0,0]
	v_pk_fma_f32 v[206:207], v[38:39], v[206:207], v[254:255] op_sel:[1,1,0] op_sel_hi:[1,0,1] neg_lo:[1,0,0]
	v_cvt_pk_bf16_f32 v124, v200, v201
	v_cvt_pk_bf16_f32 v125, v202, v203
	v_cvt_pk_bf16_f32 v126, v204, v205
	v_cvt_pk_bf16_f32 v127, v206, v207
	ds_write_b128 v241, v[124:127] offset:5184
	v_pk_mov_b32 v[232:233], v[170:171], v[186:187] op_sel:[1,1]
	v_pk_mov_b32 v[234:235], v[174:175], v[190:191] op_sel:[1,1]
	v_pk_mov_b32 v[244:245], v[178:179], v[194:195] op_sel:[1,1]
	v_pk_mov_b32 v[254:255], v[182:183], v[198:199] op_sel:[1,1]
	v_pk_fma_f32 v[232:233], v[32:33], v[200:201], v[232:233] op_sel_hi:[0,1,1]
	v_pk_fma_f32 v[234:235], v[34:35], v[202:203], v[234:235] op_sel_hi:[0,1,1]
	v_pk_fma_f32 v[244:245], v[36:37], v[204:205], v[244:245] op_sel_hi:[0,1,1]
	v_pk_fma_f32 v[254:255], v[38:39], v[206:207], v[254:255] op_sel_hi:[0,1,1]
	v_pk_fma_f32 v[200:201], v[32:33], v[200:201], v[232:233] op_sel:[1,1,0] op_sel_hi:[1,0,1] neg_lo:[1,0,0]
	v_pk_fma_f32 v[202:203], v[34:35], v[202:203], v[234:235] op_sel:[1,1,0] op_sel_hi:[1,0,1] neg_lo:[1,0,0]
	v_pk_fma_f32 v[204:205], v[36:37], v[204:205], v[244:245] op_sel:[1,1,0] op_sel_hi:[1,0,1] neg_lo:[1,0,0]
	v_pk_fma_f32 v[206:207], v[38:39], v[206:207], v[254:255] op_sel:[1,1,0] op_sel_hi:[1,0,1] neg_lo:[1,0,0]
	v_cvt_pk_bf16_f32 v124, v200, v201
	v_cvt_pk_bf16_f32 v125, v202, v203
	v_cvt_pk_bf16_f32 v126, v204, v205
	v_cvt_pk_bf16_f32 v127, v206, v207
	ds_write_b128 v241, v[124:127] offset:5472
	global_load_dwordx4 v[68:71], v238, s[20:21]
	v_add_u32_e32 v238, v238, v243
	v_cvt_pk_bf16_f32 v124, v120, v121
	v_cvt_pk_bf16_f32 v125, v122, v123
	s_nop 0
	global_store_dwordx2 v239, v[124:125], s[24:25]
	v_add_u32_e32 v239, v239, v243
	s_waitcnt vmcnt(33)
	v_mfma_f32_16x16x32_bf16 v[168:171], v[76:79], v[0:3], 0
	v_mfma_f32_16x16x32_bf16 v[172:175], v[76:79], v[4:7], 0
	v_mfma_f32_16x16x32_bf16 v[176:179], v[76:79], v[8:11], 0
	v_mfma_f32_16x16x32_bf16 v[180:183], v[76:79], v[12:15], 0
	v_mfma_f32_16x16x32_bf16 v[184:187], v[76:79], v[16:19], 0
	v_mfma_f32_16x16x32_bf16 v[188:191], v[76:79], v[20:23], 0
	v_mfma_f32_16x16x32_bf16 v[192:195], v[76:79], v[24:27], 0
	v_mfma_f32_16x16x32_bf16 v[196:199], v[76:79], v[28:31], 0
	ds_read_b128 v[216:219], v242 offset:4608
	ds_read_b128 v[220:223], v242 offset:4672
	ds_read_b128 v[224:227], v242 offset:4736
	ds_read_b128 v[228:231], v242 offset:4800
	v_pk_mov_b32 v[232:233], v[136:137], v[152:153] op_sel:[0,0]
	v_pk_mov_b32 v[234:235], v[140:141], v[156:157] op_sel:[0,0]
	v_pk_mov_b32 v[244:245], v[144:145], v[160:161] op_sel:[0,0]
	v_pk_mov_b32 v[254:255], v[148:149], v[164:165] op_sel:[0,0]
	v_pk_fma_f32 v[232:233], v[32:33], v[200:201], v[232:233] op_sel_hi:[0,1,1]
	v_pk_fma_f32 v[234:235], v[34:35], v[202:203], v[234:235] op_sel_hi:[0,1,1]
	v_pk_fma_f32 v[244:245], v[36:37], v[204:205], v[244:245] op_sel_hi:[0,1,1]
	v_pk_fma_f32 v[254:255], v[38:39], v[206:207], v[254:255] op_sel_hi:[0,1,1]
	v_pk_fma_f32 v[200:201], v[32:33], v[200:201], v[232:233] op_sel:[1,1,0] op_sel_hi:[1,0,1] neg_lo:[1,0,0]
	v_pk_fma_f32 v[202:203], v[34:35], v[202:203], v[234:235] op_sel:[1,1,0] op_sel_hi:[1,0,1] neg_lo:[1,0,0]
	v_pk_fma_f32 v[204:205], v[36:37], v[204:205], v[244:245] op_sel:[1,1,0] op_sel_hi:[1,0,1] neg_lo:[1,0,0]
	v_pk_fma_f32 v[206:207], v[38:39], v[206:207], v[254:255] op_sel:[1,1,0] op_sel_hi:[1,0,1] neg_lo:[1,0,0]
	v_cvt_pk_bf16_f32 v124, v200, v201
	v_cvt_pk_bf16_f32 v125, v202, v203
	v_cvt_pk_bf16_f32 v126, v204, v205
	v_cvt_pk_bf16_f32 v127, v206, v207
	ds_write_b128 v241, v[124:127] offset:0
	v_pk_mov_b32 v[232:233], v[136:137], v[152:153] op_sel:[1,1]
	v_pk_mov_b32 v[234:235], v[140:141], v[156:157] op_sel:[1,1]
	v_pk_mov_b32 v[244:245], v[144:145], v[160:161] op_sel:[1,1]
	v_pk_mov_b32 v[254:255], v[148:149], v[164:165] op_sel:[1,1]
	v_pk_fma_f32 v[232:233], v[32:33], v[200:201], v[232:233] op_sel_hi:[0,1,1]
	v_pk_fma_f32 v[234:235], v[34:35], v[202:203], v[234:235] op_sel_hi:[0,1,1]
	v_pk_fma_f32 v[244:245], v[36:37], v[204:205], v[244:245] op_sel_hi:[0,1,1]
	v_pk_fma_f32 v[254:255], v[38:39], v[206:207], v[254:255] op_sel_hi:[0,1,1]
	v_pk_fma_f32 v[200:201], v[32:33], v[200:201], v[232:233] op_sel:[1,1,0] op_sel_hi:[1,0,1] neg_lo:[1,0,0]
	v_pk_fma_f32 v[202:203], v[34:35], v[202:203], v[234:235] op_sel:[1,1,0] op_sel_hi:[1,0,1] neg_lo:[1,0,0]
	v_pk_fma_f32 v[204:205], v[36:37], v[204:205], v[244:245] op_sel:[1,1,0] op_sel_hi:[1,0,1] neg_lo:[1,0,0]
	v_pk_fma_f32 v[206:207], v[38:39], v[206:207], v[254:255] op_sel:[1,1,0] op_sel_hi:[1,0,1] neg_lo:[1,0,0]
	v_cvt_pk_bf16_f32 v124, v200, v201
	v_cvt_pk_bf16_f32 v125, v202, v203
	v_cvt_pk_bf16_f32 v126, v204, v205
	v_cvt_pk_bf16_f32 v127, v206, v207
	ds_write_b128 v241, v[124:127] offset:288
	s_waitcnt lgkmcnt(2)
; __device__ __forceinline__ unsigned f2bf(float f) { unsigned u = __builtin_bit_cast(unsigned, f); return (u + 0x7fffu + ((u >> 16) & 1u)) >> 16; }
; __device__ __forceinline__ bf16x8 pack8(const float (&f)[8]) { u32x4 h; h.x = pk2(f[0], f[1]); h.y = pk2(f[2], f[3]); h.z = pk2(f[4], f[5]); h.w = pk2(f[6], f[7]); return __builtin_bit_cast(bf16x8, h); }
; template <bool FINAL> __device__ __forceinline__ void phase_s5_scan(const Fr& F) {
;     ...
;         for (int sub = 0; sub < 4; ++sub) {
;             const bf16x8 A1 = __builtin_bit_cast(bf16x8, uc[sub]);
; #pragma unroll
;             for (int nt = 0; nt < 8; ++nt) {
;                 f32x4 acc = {0.f, 0.f, 0.f, 0.f};
;                 acc = __builtin_amdgcn_mfma_f32_16x16x32_bf16(A1, B1[nt], acc, 0, 0, 0);
; #pragma unroll
;                 for (int reg = 0; reg < 4; ++reg) BUl[(4 * lq + reg) * 132 + 16 * nt + l15] = acc[reg];
;             }
;             asm volatile("s_waitcnt lgkmcnt(0)" ::: "memory");
; #pragma unroll 4
;             for (int jj = 0; jj < 16; ++jj) {
;                 const float br_ = BUl[jj * 132 + lane], bi_ = BUl[jj * 132 + 64 + lane];
;                 const float nr = ar * xr - ai * xi + br_, ni = ar * xi + ai * xr + bi_; xr = nr; xi = ni;
;                 if (FINAL) { BUl[jj * 132 + lane] = xr; BUl[jj * 132 + 64 + lane] = xi; }
;             }
;             if (FINAL) {
;                 asm volatile("s_waitcnt lgkmcnt(0)" ::: "memory");
;                 f32x4 acc = {0.f, 0.f, 0.f, 0.f};
; #pragma unroll
;                 for (int ks = 0; ks < 4; ++ks) {
;                     const f32x4 t0 = *(const f32x4*)(BUl + l15 * 132 + 32 * ks + 8 * lq), t1 = *(const f32x4*)(BUl + l15 * 132 + 32 * ks + 8 * lq + 4);
;                     const float xf[8] = {t0.x, t0.y, t0.z, t0.w, t1.x, t1.y, t1.z, t1.w};
;                     acc = __builtin_amdgcn_mfma_f32_16x16x32_bf16(pack8(xf), Chi[ks], acc, 0, 0, 0);
;                 }
; #pragma unroll
;                 for (int reg = 0; reg < 4; ++reg) { const int tok = tokof(s, chunk * 64 + sub * 16 + 4 * lq + reg);
;                     Yb[((size_t)b * TB + tok) * D + g * 16 + l15] = (bf16)f2bf(acc[reg]); }
;                 asm volatile("s_waitcnt lgkmcnt(0)" ::: "memory");
	v_mfma_f32_16x16x32_bf16 v[120:123], v[40:43], v[216:219], 0
	v_mfma_f32_16x16x32_bf16 v[120:123], v[44:47], v[220:223], v[120:123]
	v_mfma_f32_16x16x32_bf16 v[120:123], v[48:51], v[224:227], v[120:123]
	v_mfma_f32_16x16x32_bf16 v[120:123], v[52:55], v[228:231], v[120:123]
	v_pk_mov_b32 v[232:233], v[138:139], v[154:155] op_sel:[0,0]
	v_pk_mov_b32 v[234:235], v[142:143], v[158:159] op_sel:[0,0]
	v_pk_mov_b32 v[244:245], v[146:147], v[162:163] op_sel:[0,0]
	v_pk_mov_b32 v[254:255], v[150:151], v[166:167] op_sel:[0,0]
	v_pk_fma_f32 v[232:233], v[32:33], v[200:201], v[232:233] op_sel_hi:[0,1,1]
	v_pk_fma_f32 v[234:235], v[34:35], v[202:203], v[234:235] op_sel_hi:[0,1,1]
	v_pk_fma_f32 v[244:245], v[36:37], v[204:205], v[244:245] op_sel_hi:[0,1,1]
	v_pk_fma_f32 v[254:255], v[38:39], v[206:207], v[254:255] op_sel_hi:[0,1,1]
	v_pk_fma_f32 v[200:201], v[32:33], v[200:201], v[232:233] op_sel:[1,1,0] op_sel_hi:[1,0,1] neg_lo:[1,0,0]
	v_pk_fma_f32 v[202:203], v[34:35], v[202:203], v[234:235] op_sel:[1,1,0] op_sel_hi:[1,0,1] neg_lo:[1,0,0]
	v_pk_fma_f32 v[204:205], v[36:37], v[204:205], v[244:245] op_sel:[1,1,0] op_sel_hi:[1,0,1] neg_lo:[1,0,0]
	v_pk_fma_f32 v[206:207], v[38:39], v[206:207], v[254:255] op_sel:[1,1,0] op_sel_hi:[1,0,1] neg_lo:[1,0,0]
	v_cvt_pk_bf16_f32 v124, v200, v201
	v_cvt_pk_bf16_f32 v125, v202, v203
	v_cvt_pk_bf16_f32 v126, v204, v205
	v_cvt_pk_bf16_f32 v127, v206, v207
	ds_write_b128 v241, v[124:127] offset:576
	v_pk_mov_b32 v[232:233], v[138:139], v[154:155] op_sel:[1,1]
	v_pk_mov_b32 v[234:235], v[142:143], v[158:159] op_sel:[1,1]
	v_pk_mov_b32 v[244:245], v[146:147], v[162:163] op_sel:[1,1]
	v_pk_mov_b32 v[254:255], v[150:151], v[166:167] op_sel:[1,1]
	v_pk_fma_f32 v[232:233], v[32:33], v[200:201], v[232:233] op_sel_hi:[0,1,1]
	v_pk_fma_f32 v[234:235], v[34:35], v[202:203], v[234:235] op_sel_hi:[0,1,1]
	v_pk_fma_f32 v[244:245], v[36:37], v[204:205], v[244:245] op_sel_hi:[0,1,1]
	v_pk_fma_f32 v[254:255], v[38:39], v[206:207], v[254:255] op_sel_hi:[0,1,1]
	v_pk_fma_f32 v[200:201], v[32:33], v[200:201], v[232:233] op_sel:[1,1,0] op_sel_hi:[1,0,1] neg_lo:[1,0,0]
	v_pk_fma_f32 v[202:203], v[34:35], v[202:203], v[234:235] op_sel:[1,1,0] op_sel_hi:[1,0,1] neg_lo:[1,0,0]
	v_pk_fma_f32 v[204:205], v[36:37], v[204:205], v[244:245] op_sel:[1,1,0] op_sel_hi:[1,0,1] neg_lo:[1,0,0]
	v_pk_fma_f32 v[206:207], v[38:39], v[206:207], v[254:255] op_sel:[1,1,0] op_sel_hi:[1,0,1] neg_lo:[1,0,0]
	v_cvt_pk_bf16_f32 v124, v200, v201
	v_cvt_pk_bf16_f32 v125, v202, v203
	v_cvt_pk_bf16_f32 v126, v204, v205
	v_cvt_pk_bf16_f32 v127, v206, v207
	ds_write_b128 v241, v[124:127] offset:864
	global_load_dwordx4 v[72:75], v238, s[20:21]
	v_add_u32_e32 v238, v238, v243
	v_cvt_pk_bf16_f32 v124, v120, v121
	v_cvt_pk_bf16_f32 v125, v122, v123
	s_nop 0
	global_store_dwordx2 v239, v[124:125], s[24:25]
	v_add_u32_e32 v239, v239, v243
	s_waitcnt vmcnt(33)
	v_mfma_f32_16x16x32_bf16 v[136:139], v[80:83], v[0:3], 0
	v_mfma_f32_16x16x32_bf16 v[140:143], v[80:83], v[4:7], 0
	v_mfma_f32_16x16x32_bf16 v[144:147], v[80:83], v[8:11], 0
	v_mfma_f32_16x16x32_bf16 v[148:151], v[80:83], v[12:15], 0
	v_mfma_f32_16x16x32_bf16 v[152:155], v[80:83], v[16:19], 0
	v_mfma_f32_16x16x32_bf16 v[156:159], v[80:83], v[20:23], 0
	v_mfma_f32_16x16x32_bf16 v[160:163], v[80:83], v[24:27], 0
	v_mfma_f32_16x16x32_bf16 v[164:167], v[80:83], v[28:31], 0
	ds_read_b128 v[216:219], v242 offset:0
	ds_read_b128 v[220:223], v242 offset:64
	ds_read_b128 v[224:227], v242 offset:128
	ds_read_b128 v[228:231], v242 offset:192
	v_pk_mov_b32 v[232:233], v[168:169], v[184:185] op_sel:[0,0]
	v_pk_mov_b32 v[234:235], v[172:173], v[188:189] op_sel:[0,0]
	v_pk_mov_b32 v[244:245], v[176:177], v[192:193] op_sel:[0,0]
	v_pk_mov_b32 v[254:255], v[180:181], v[196:197] op_sel:[0,0]
	v_pk_fma_f32 v[232:233], v[32:33], v[200:201], v[232:233] op_sel_hi:[0,1,1]
	v_pk_fma_f32 v[234:235], v[34:35], v[202:203], v[234:235] op_sel_hi:[0,1,1]
	v_pk_fma_f32 v[244:245], v[36:37], v[204:205], v[244:245] op_sel_hi:[0,1,1]
	v_pk_fma_f32 v[254:255], v[38:39], v[206:207], v[254:255] op_sel_hi:[0,1,1]
	v_pk_fma_f32 v[200:201], v[32:33], v[200:201], v[232:233] op_sel:[1,1,0] op_sel_hi:[1,0,1] neg_lo:[1,0,0]
	v_pk_fma_f32 v[202:203], v[34:35], v[202:203], v[234:235] op_sel:[1,1,0] op_sel_hi:[1,0,1] neg_lo:[1,0,0]
	v_pk_fma_f32 v[204:205], v[36:37], v[204:205], v[244:245] op_sel:[1,1,0] op_sel_hi:[1,0,1] neg_lo:[1,0,0]
	v_pk_fma_f32 v[206:207], v[38:39], v[206:207], v[254:255] op_sel:[1,1,0] op_sel_hi:[1,0,1] neg_lo:[1,0,0]
	v_cvt_pk_bf16_f32 v124, v200, v201
	v_cvt_pk_bf16_f32 v125, v202, v203
	v_cvt_pk_bf16_f32 v126, v204, v205
	v_cvt_pk_bf16_f32 v127, v206, v207
	ds_write_b128 v241, v[124:127] offset:4608
	v_pk_mov_b32 v[232:233], v[168:169], v[184:185] op_sel:[1,1]
	v_pk_mov_b32 v[234:235], v[172:173], v[188:189] op_sel:[1,1]
	v_pk_mov_b32 v[244:245], v[176:177], v[192:193] op_sel:[1,1]
	v_pk_mov_b32 v[254:255], v[180:181], v[196:197] op_sel:[1,1]
	v_pk_fma_f32 v[232:233], v[32:33], v[200:201], v[232:233] op_sel_hi:[0,1,1]
	v_pk_fma_f32 v[234:235], v[34:35], v[202:203], v[234:235] op_sel_hi:[0,1,1]
	v_pk_fma_f32 v[244:245], v[36:37], v[204:205], v[244:245] op_sel_hi:[0,1,1]
	v_pk_fma_f32 v[254:255], v[38:39], v[206:207], v[254:255] op_sel_hi:[0,1,1]
	v_pk_fma_f32 v[200:201], v[32:33], v[200:201], v[232:233] op_sel:[1,1,0] op_sel_hi:[1,0,1] neg_lo:[1,0,0]
	v_pk_fma_f32 v[202:203], v[34:35], v[202:203], v[234:235] op_sel:[1,1,0] op_sel_hi:[1,0,1] neg_lo:[1,0,0]
	v_pk_fma_f32 v[204:205], v[36:37], v[204:205], v[244:245] op_sel:[1,1,0] op_sel_hi:[1,0,1] neg_lo:[1,0,0]
	v_pk_fma_f32 v[206:207], v[38:39], v[206:207], v[254:255] op_sel:[1,1,0] op_sel_hi:[1,0,1] neg_lo:[1,0,0]
	v_cvt_pk_bf16_f32 v124, v200, v201
	v_cvt_pk_bf16_f32 v125, v202, v203
	v_cvt_pk_bf16_f32 v126, v204, v205
	v_cvt_pk_bf16_f32 v127, v206, v207
	ds_write_b128 v241, v[124:127] offset:4896
	s_waitcnt lgkmcnt(2)
; __device__ __forceinline__ unsigned f2bf(float f) { unsigned u = __builtin_bit_cast(unsigned, f); return (u + 0x7fffu + ((u >> 16) & 1u)) >> 16; }
; __device__ __forceinline__ bf16x8 pack8(const float (&f)[8]) { u32x4 h; h.x = pk2(f[0], f[1]); h.y = pk2(f[2], f[3]); h.z = pk2(f[4], f[5]); h.w = pk2(f[6], f[7]); return __builtin_bit_cast(bf16x8, h); }
; template <bool FINAL> __device__ __forceinline__ void phase_s5_scan(const Fr& F) {
;     ...
;         for (int sub = 0; sub < 4; ++sub) {
;             const bf16x8 A1 = __builtin_bit_cast(bf16x8, uc[sub]);
; #pragma unroll
;             for (int nt = 0; nt < 8; ++nt) {
;                 f32x4 acc = {0.f, 0.f, 0.f, 0.f};
;                 acc = __builtin_amdgcn_mfma_f32_16x16x32_bf16(A1, B1[nt], acc, 0, 0, 0);
; #pragma unroll
;                 for (int reg = 0; reg < 4; ++reg) BUl[(4 * lq + reg) * 132 + 16 * nt + l15] = acc[reg];
;             }
;             asm volatile("s_waitcnt lgkmcnt(0)" ::: "memory");
; #pragma unroll 4
;             for (int jj = 0; jj < 16; ++jj) {
;                 const float br_ = BUl[jj * 132 + lane], bi_ = BUl[jj * 132 + 64 + lane];
;                 const float nr = ar * xr - ai * xi + br_, ni = ar * xi + ai * xr + bi_; xr = nr; xi = ni;
;                 if (FINAL) { BUl[jj * 132 + lane] = xr; BUl[jj * 132 + 64 + lane] = xi; }
;             }
;             if (FINAL) {
;                 asm volatile("s_waitcnt lgkmcnt(0)" ::: "memory");
;                 f32x4 acc = {0.f, 0.f, 0.f, 0.f};
; #pragma unroll
;                 for (int ks = 0; ks < 4; ++ks) {
;                     const f32x4 t0 = *(const f32x4*)(BUl + l15 * 132 + 32 * ks + 8 * lq), t1 = *(const f32x4*)(BUl + l15 * 132 + 32 * ks + 8 * lq + 4);
;                     const float xf[8] = {t0.x, t0.y, t0.z, t0.w, t1.x, t1.y, t1.z, t1.w};
;                     acc = __builtin_amdgcn_mfma_f32_16x16x32_bf16(pack8(xf), Chi[ks], acc, 0, 0, 0);
;                 }
; #pragma unroll
;                 for (int reg = 0; reg < 4; ++reg) { const int tok = tokof(s, chunk * 64 + sub * 16 + 4 * lq + reg);
;                     Yb[((size_t)b * TB + tok) * D + g * 16 + l15] = (bf16)f2bf(acc[reg]); }
;                 asm volatile("s_waitcnt lgkmcnt(0)" ::: "memory");
	v_mfma_f32_16x16x32_bf16 v[120:123], v[40:43], v[216:219], 0
	v_mfma_f32_16x16x32_bf16 v[120:123], v[44:47], v[220:223], v[120:123]
	v_mfma_f32_16x16x32_bf16 v[120:123], v[48:51], v[224:227], v[120:123]
	v_mfma_f32_16x16x32_bf16 v[120:123], v[52:55], v[228:231], v[120:123]
	v_pk_mov_b32 v[232:233], v[170:171], v[186:187] op_sel:[0,0]
	v_pk_mov_b32 v[234:235], v[174:175], v[190:191] op_sel:[0,0]
	v_pk_mov_b32 v[244:245], v[178:179], v[194:195] op_sel:[0,0]
	v_pk_mov_b32 v[254:255], v[182:183], v[198:199] op_sel:[0,0]
	v_pk_fma_f32 v[232:233], v[32:33], v[200:201], v[232:233] op_sel_hi:[0,1,1]
	v_pk_fma_f32 v[234:235], v[34:35], v[202:203], v[234:235] op_sel_hi:[0,1,1]
	v_pk_fma_f32 v[244:245], v[36:37], v[204:205], v[244:245] op_sel_hi:[0,1,1]
	v_pk_fma_f32 v[254:255], v[38:39], v[206:207], v[254:255] op_sel_hi:[0,1,1]
	v_pk_fma_f32 v[200:201], v[32:33], v[200:201], v[232:233] op_sel:[1,1,0] op_sel_hi:[1,0,1] neg_lo:[1,0,0]
	v_pk_fma_f32 v[202:203], v[34:35], v[202:203], v[234:235] op_sel:[1,1,0] op_sel_hi:[1,0,1] neg_lo:[1,0,0]
	v_pk_fma_f32 v[204:205], v[36:37], v[204:205], v[244:245] op_sel:[1,1,0] op_sel_hi:[1,0,1] neg_lo:[1,0,0]
	v_pk_fma_f32 v[206:207], v[38:39], v[206:207], v[254:255] op_sel:[1,1,0] op_sel_hi:[1,0,1] neg_lo:[1,0,0]
	v_cvt_pk_bf16_f32 v124, v200, v201
	v_cvt_pk_bf16_f32 v125, v202, v203
	v_cvt_pk_bf16_f32 v126, v204, v205
	v_cvt_pk_bf16_f32 v127, v206, v207
	ds_write_b128 v241, v[124:127] offset:5184
	v_pk_mov_b32 v[232:233], v[170:171], v[186:187] op_sel:[1,1]
	v_pk_mov_b32 v[234:235], v[174:175], v[190:191] op_sel:[1,1]
	v_pk_mov_b32 v[244:245], v[178:179], v[194:195] op_sel:[1,1]
	v_pk_mov_b32 v[254:255], v[182:183], v[198:199] op_sel:[1,1]
	v_pk_fma_f32 v[232:233], v[32:33], v[200:201], v[232:233] op_sel_hi:[0,1,1]
	v_pk_fma_f32 v[234:235], v[34:35], v[202:203], v[234:235] op_sel_hi:[0,1,1]
	v_pk_fma_f32 v[244:245], v[36:37], v[204:205], v[244:245] op_sel_hi:[0,1,1]
	v_pk_fma_f32 v[254:255], v[38:39], v[206:207], v[254:255] op_sel_hi:[0,1,1]
	v_pk_fma_f32 v[200:201], v[32:33], v[200:201], v[232:233] op_sel:[1,1,0] op_sel_hi:[1,0,1] neg_lo:[1,0,0]
	v_pk_fma_f32 v[202:203], v[34:35], v[202:203], v[234:235] op_sel:[1,1,0] op_sel_hi:[1,0,1] neg_lo:[1,0,0]
	v_pk_fma_f32 v[204:205], v[36:37], v[204:205], v[244:245] op_sel:[1,1,0] op_sel_hi:[1,0,1] neg_lo:[1,0,0]
	v_pk_fma_f32 v[206:207], v[38:39], v[206:207], v[254:255] op_sel:[1,1,0] op_sel_hi:[1,0,1] neg_lo:[1,0,0]
	v_cvt_pk_bf16_f32 v124, v200, v201
	v_cvt_pk_bf16_f32 v125, v202, v203
	v_cvt_pk_bf16_f32 v126, v204, v205
	v_cvt_pk_bf16_f32 v127, v206, v207
	ds_write_b128 v241, v[124:127] offset:5472
	global_load_dwordx4 v[76:79], v238, s[20:21]
	v_add_u32_e32 v238, v238, v243
	v_cvt_pk_bf16_f32 v124, v120, v121
	v_cvt_pk_bf16_f32 v125, v122, v123
	s_nop 0
	global_store_dwordx2 v239, v[124:125], s[24:25]
	v_add_u32_e32 v239, v239, v243
	s_waitcnt vmcnt(33)
	v_mfma_f32_16x16x32_bf16 v[168:171], v[84:87], v[0:3], 0
	v_mfma_f32_16x16x32_bf16 v[172:175], v[84:87], v[4:7], 0
	v_mfma_f32_16x16x32_bf16 v[176:179], v[84:87], v[8:11], 0
	v_mfma_f32_16x16x32_bf16 v[180:183], v[84:87], v[12:15], 0
	v_mfma_f32_16x16x32_bf16 v[184:187], v[84:87], v[16:19], 0
	v_mfma_f32_16x16x32_bf16 v[188:191], v[84:87], v[20:23], 0
	v_mfma_f32_16x16x32_bf16 v[192:195], v[84:87], v[24:27], 0
	v_mfma_f32_16x16x32_bf16 v[196:199], v[84:87], v[28:31], 0
	ds_read_b128 v[216:219], v242 offset:4608
	ds_read_b128 v[220:223], v242 offset:4672
	ds_read_b128 v[224:227], v242 offset:4736
	ds_read_b128 v[228:231], v242 offset:4800
	v_pk_mov_b32 v[232:233], v[136:137], v[152:153] op_sel:[0,0]
	v_pk_mov_b32 v[234:235], v[140:141], v[156:157] op_sel:[0,0]
	v_pk_mov_b32 v[244:245], v[144:145], v[160:161] op_sel:[0,0]
	v_pk_mov_b32 v[254:255], v[148:149], v[164:165] op_sel:[0,0]
	v_pk_fma_f32 v[232:233], v[32:33], v[200:201], v[232:233] op_sel_hi:[0,1,1]
	v_pk_fma_f32 v[234:235], v[34:35], v[202:203], v[234:235] op_sel_hi:[0,1,1]
	v_pk_fma_f32 v[244:245], v[36:37], v[204:205], v[244:245] op_sel_hi:[0,1,1]
	v_pk_fma_f32 v[254:255], v[38:39], v[206:207], v[254:255] op_sel_hi:[0,1,1]
	v_pk_fma_f32 v[200:201], v[32:33], v[200:201], v[232:233] op_sel:[1,1,0] op_sel_hi:[1,0,1] neg_lo:[1,0,0]
	v_pk_fma_f32 v[202:203], v[34:35], v[202:203], v[234:235] op_sel:[1,1,0] op_sel_hi:[1,0,1] neg_lo:[1,0,0]
	v_pk_fma_f32 v[204:205], v[36:37], v[204:205], v[244:245] op_sel:[1,1,0] op_sel_hi:[1,0,1] neg_lo:[1,0,0]
	v_pk_fma_f32 v[206:207], v[38:39], v[206:207], v[254:255] op_sel:[1,1,0] op_sel_hi:[1,0,1] neg_lo:[1,0,0]
	v_cvt_pk_bf16_f32 v124, v200, v201
	v_cvt_pk_bf16_f32 v125, v202, v203
	v_cvt_pk_bf16_f32 v126, v204, v205
	v_cvt_pk_bf16_f32 v127, v206, v207
	ds_write_b128 v241, v[124:127] offset:0
	v_pk_mov_b32 v[232:233], v[136:137], v[152:153] op_sel:[1,1]
	v_pk_mov_b32 v[234:235], v[140:141], v[156:157] op_sel:[1,1]
	v_pk_mov_b32 v[244:245], v[144:145], v[160:161] op_sel:[1,1]
	v_pk_mov_b32 v[254:255], v[148:149], v[164:165] op_sel:[1,1]
	v_pk_fma_f32 v[232:233], v[32:33], v[200:201], v[232:233] op_sel_hi:[0,1,1]
	v_pk_fma_f32 v[234:235], v[34:35], v[202:203], v[234:235] op_sel_hi:[0,1,1]
	v_pk_fma_f32 v[244:245], v[36:37], v[204:205], v[244:245] op_sel_hi:[0,1,1]
	v_pk_fma_f32 v[254:255], v[38:39], v[206:207], v[254:255] op_sel_hi:[0,1,1]
	v_pk_fma_f32 v[200:201], v[32:33], v[200:201], v[232:233] op_sel:[1,1,0] op_sel_hi:[1,0,1] neg_lo:[1,0,0]
	v_pk_fma_f32 v[202:203], v[34:35], v[202:203], v[234:235] op_sel:[1,1,0] op_sel_hi:[1,0,1] neg_lo:[1,0,0]
	v_pk_fma_f32 v[204:205], v[36:37], v[204:205], v[244:245] op_sel:[1,1,0] op_sel_hi:[1,0,1] neg_lo:[1,0,0]
	v_pk_fma_f32 v[206:207], v[38:39], v[206:207], v[254:255] op_sel:[1,1,0] op_sel_hi:[1,0,1] neg_lo:[1,0,0]
	v_cvt_pk_bf16_f32 v124, v200, v201
	v_cvt_pk_bf16_f32 v125, v202, v203
	v_cvt_pk_bf16_f32 v126, v204, v205
	v_cvt_pk_bf16_f32 v127, v206, v207
	ds_write_b128 v241, v[124:127] offset:288
	s_waitcnt lgkmcnt(2)
; __device__ __forceinline__ unsigned f2bf(float f) { unsigned u = __builtin_bit_cast(unsigned, f); return (u + 0x7fffu + ((u >> 16) & 1u)) >> 16; }
; __device__ __forceinline__ bf16x8 pack8(const float (&f)[8]) { u32x4 h; h.x = pk2(f[0], f[1]); h.y = pk2(f[2], f[3]); h.z = pk2(f[4], f[5]); h.w = pk2(f[6], f[7]); return __builtin_bit_cast(bf16x8, h); }
; template <bool FINAL> __device__ __forceinline__ void phase_s5_scan(const Fr& F) {
;     ...
;         for (int sub = 0; sub < 4; ++sub) {
;             const bf16x8 A1 = __builtin_bit_cast(bf16x8, uc[sub]);
; #pragma unroll
;             for (int nt = 0; nt < 8; ++nt) {
;                 f32x4 acc = {0.f, 0.f, 0.f, 0.f};
;                 acc = __builtin_amdgcn_mfma_f32_16x16x32_bf16(A1, B1[nt], acc, 0, 0, 0);
; #pragma unroll
;                 for (int reg = 0; reg < 4; ++reg) BUl[(4 * lq + reg) * 132 + 16 * nt + l15] = acc[reg];
;             }
;             asm volatile("s_waitcnt lgkmcnt(0)" ::: "memory");
; #pragma unroll 4
;             for (int jj = 0; jj < 16; ++jj) {
;                 const float br_ = BUl[jj * 132 + lane], bi_ = BUl[jj * 132 + 64 + lane];
;                 const float nr = ar * xr - ai * xi + br_, ni = ar * xi + ai * xr + bi_; xr = nr; xi = ni;
;                 if (FINAL) { BUl[jj * 132 + lane] = xr; BUl[jj * 132 + 64 + lane] = xi; }
;             }
;             if (FINAL) {
;                 asm volatile("s_waitcnt lgkmcnt(0)" ::: "memory");
;                 f32x4 acc = {0.f, 0.f, 0.f, 0.f};
; #pragma unroll
;                 for (int ks = 0; ks < 4; ++ks) {
;                     const f32x4 t0 = *(const f32x4*)(BUl + l15 * 132 + 32 * ks + 8 * lq), t1 = *(const f32x4*)(BUl + l15 * 132 + 32 * ks + 8 * lq + 4);
;                     const float xf[8] = {t0.x, t0.y, t0.z, t0.w, t1.x, t1.y, t1.z, t1.w};
;                     acc = __builtin_amdgcn_mfma_f32_16x16x32_bf16(pack8(xf), Chi[ks], acc, 0, 0, 0);
;                 }
; #pragma unroll
;                 for (int reg = 0; reg < 4; ++reg) { const int tok = tokof(s, chunk * 64 + sub * 16 + 4 * lq + reg);
;                     Yb[((size_t)b * TB + tok) * D + g * 16 + l15] = (bf16)f2bf(acc[reg]); }
;                 asm volatile("s_waitcnt lgkmcnt(0)" ::: "memory");
	v_mfma_f32_16x16x32_bf16 v[120:123], v[40:43], v[216:219], 0
	v_mfma_f32_16x16x32_bf16 v[120:123], v[44:47], v[220:223], v[120:123]
	v_mfma_f32_16x16x32_bf16 v[120:123], v[48:51], v[224:227], v[120:123]
	v_mfma_f32_16x16x32_bf16 v[120:123], v[52:55], v[228:231], v[120:123]
	v_pk_mov_b32 v[232:233], v[138:139], v[154:155] op_sel:[0,0]
	v_pk_mov_b32 v[234:235], v[142:143], v[158:159] op_sel:[0,0]
	v_pk_mov_b32 v[244:245], v[146:147], v[162:163] op_sel:[0,0]
	v_pk_mov_b32 v[254:255], v[150:151], v[166:167] op_sel:[0,0]
	v_pk_fma_f32 v[232:233], v[32:33], v[200:201], v[232:233] op_sel_hi:[0,1,1]
	v_pk_fma_f32 v[234:235], v[34:35], v[202:203], v[234:235] op_sel_hi:[0,1,1]
	v_pk_fma_f32 v[244:245], v[36:37], v[204:205], v[244:245] op_sel_hi:[0,1,1]
	v_pk_fma_f32 v[254:255], v[38:39], v[206:207], v[254:255] op_sel_hi:[0,1,1]
	v_pk_fma_f32 v[200:201], v[32:33], v[200:201], v[232:233] op_sel:[1,1,0] op_sel_hi:[1,0,1] neg_lo:[1,0,0]
	v_pk_fma_f32 v[202:203], v[34:35], v[202:203], v[234:235] op_sel:[1,1,0] op_sel_hi:[1,0,1] neg_lo:[1,0,0]
	v_pk_fma_f32 v[204:205], v[36:37], v[204:205], v[244:245] op_sel:[1,1,0] op_sel_hi:[1,0,1] neg_lo:[1,0,0]
	v_pk_fma_f32 v[206:207], v[38:39], v[206:207], v[254:255] op_sel:[1,1,0] op_sel_hi:[1,0,1] neg_lo:[1,0,0]
	v_cvt_pk_bf16_f32 v124, v200, v201
	v_cvt_pk_bf16_f32 v125, v202, v203
	v_cvt_pk_bf16_f32 v126, v204, v205
	v_cvt_pk_bf16_f32 v127, v206, v207
	ds_write_b128 v241, v[124:127] offset:576
	v_pk_mov_b32 v[232:233], v[138:139], v[154:155] op_sel:[1,1]
	v_pk_mov_b32 v[234:235], v[142:143], v[158:159] op_sel:[1,1]
	v_pk_mov_b32 v[244:245], v[146:147], v[162:163] op_sel:[1,1]
	v_pk_mov_b32 v[254:255], v[150:151], v[166:167] op_sel:[1,1]
	v_pk_fma_f32 v[232:233], v[32:33], v[200:201], v[232:233] op_sel_hi:[0,1,1]
	v_pk_fma_f32 v[234:235], v[34:35], v[202:203], v[234:235] op_sel_hi:[0,1,1]
	v_pk_fma_f32 v[244:245], v[36:37], v[204:205], v[244:245] op_sel_hi:[0,1,1]
	v_pk_fma_f32 v[254:255], v[38:39], v[206:207], v[254:255] op_sel_hi:[0,1,1]
	v_pk_fma_f32 v[200:201], v[32:33], v[200:201], v[232:233] op_sel:[1,1,0] op_sel_hi:[1,0,1] neg_lo:[1,0,0]
	v_pk_fma_f32 v[202:203], v[34:35], v[202:203], v[234:235] op_sel:[1,1,0] op_sel_hi:[1,0,1] neg_lo:[1,0,0]
	v_pk_fma_f32 v[204:205], v[36:37], v[204:205], v[244:245] op_sel:[1,1,0] op_sel_hi:[1,0,1] neg_lo:[1,0,0]
	v_pk_fma_f32 v[206:207], v[38:39], v[206:207], v[254:255] op_sel:[1,1,0] op_sel_hi:[1,0,1] neg_lo:[1,0,0]
	v_cvt_pk_bf16_f32 v124, v200, v201
	v_cvt_pk_bf16_f32 v125, v202, v203
	v_cvt_pk_bf16_f32 v126, v204, v205
	v_cvt_pk_bf16_f32 v127, v206, v207
	ds_write_b128 v241, v[124:127] offset:864
	global_load_dwordx4 v[80:83], v238, s[20:21]
	v_add_u32_e32 v238, v238, v243
	v_cvt_pk_bf16_f32 v124, v120, v121
	v_cvt_pk_bf16_f32 v125, v122, v123
	s_nop 0
	global_store_dwordx2 v239, v[124:125], s[24:25]
	v_add_u32_e32 v239, v239, v243
	s_waitcnt vmcnt(33)
	v_mfma_f32_16x16x32_bf16 v[136:139], v[88:91], v[0:3], 0
	v_mfma_f32_16x16x32_bf16 v[140:143], v[88:91], v[4:7], 0
	v_mfma_f32_16x16x32_bf16 v[144:147], v[88:91], v[8:11], 0
	v_mfma_f32_16x16x32_bf16 v[148:151], v[88:91], v[12:15], 0
	v_mfma_f32_16x16x32_bf16 v[152:155], v[88:91], v[16:19], 0
	v_mfma_f32_16x16x32_bf16 v[156:159], v[88:91], v[20:23], 0
	v_mfma_f32_16x16x32_bf16 v[160:163], v[88:91], v[24:27], 0
	v_mfma_f32_16x16x32_bf16 v[164:167], v[88:91], v[28:31], 0
	ds_read_b128 v[216:219], v242 offset:0
	ds_read_b128 v[220:223], v242 offset:64
	ds_read_b128 v[224:227], v242 offset:128
	ds_read_b128 v[228:231], v242 offset:192
	v_pk_mov_b32 v[232:233], v[168:169], v[184:185] op_sel:[0,0]
	v_pk_mov_b32 v[234:235], v[172:173], v[188:189] op_sel:[0,0]
	v_pk_mov_b32 v[244:245], v[176:177], v[192:193] op_sel:[0,0]
	v_pk_mov_b32 v[254:255], v[180:181], v[196:197] op_sel:[0,0]
	v_pk_fma_f32 v[232:233], v[32:33], v[200:201], v[232:233] op_sel_hi:[0,1,1]
	v_pk_fma_f32 v[234:235], v[34:35], v[202:203], v[234:235] op_sel_hi:[0,1,1]
	v_pk_fma_f32 v[244:245], v[36:37], v[204:205], v[244:245] op_sel_hi:[0,1,1]
	v_pk_fma_f32 v[254:255], v[38:39], v[206:207], v[254:255] op_sel_hi:[0,1,1]
	v_pk_fma_f32 v[200:201], v[32:33], v[200:201], v[232:233] op_sel:[1,1,0] op_sel_hi:[1,0,1] neg_lo:[1,0,0]
	v_pk_fma_f32 v[202:203], v[34:35], v[202:203], v[234:235] op_sel:[1,1,0] op_sel_hi:[1,0,1] neg_lo:[1,0,0]
	v_pk_fma_f32 v[204:205], v[36:37], v[204:205], v[244:245] op_sel:[1,1,0] op_sel_hi:[1,0,1] neg_lo:[1,0,0]
	v_pk_fma_f32 v[206:207], v[38:39], v[206:207], v[254:255] op_sel:[1,1,0] op_sel_hi:[1,0,1] neg_lo:[1,0,0]
	v_cvt_pk_bf16_f32 v124, v200, v201
	v_cvt_pk_bf16_f32 v125, v202, v203
	v_cvt_pk_bf16_f32 v126, v204, v205
	v_cvt_pk_bf16_f32 v127, v206, v207
	ds_write_b128 v241, v[124:127] offset:4608
	v_pk_mov_b32 v[232:233], v[168:169], v[184:185] op_sel:[1,1]
	v_pk_mov_b32 v[234:235], v[172:173], v[188:189] op_sel:[1,1]
	v_pk_mov_b32 v[244:245], v[176:177], v[192:193] op_sel:[1,1]
	v_pk_mov_b32 v[254:255], v[180:181], v[196:197] op_sel:[1,1]
	v_pk_fma_f32 v[232:233], v[32:33], v[200:201], v[232:233] op_sel_hi:[0,1,1]
	v_pk_fma_f32 v[234:235], v[34:35], v[202:203], v[234:235] op_sel_hi:[0,1,1]
	v_pk_fma_f32 v[244:245], v[36:37], v[204:205], v[244:245] op_sel_hi:[0,1,1]
	v_pk_fma_f32 v[254:255], v[38:39], v[206:207], v[254:255] op_sel_hi:[0,1,1]
	v_pk_fma_f32 v[200:201], v[32:33], v[200:201], v[232:233] op_sel:[1,1,0] op_sel_hi:[1,0,1] neg_lo:[1,0,0]
	v_pk_fma_f32 v[202:203], v[34:35], v[202:203], v[234:235] op_sel:[1,1,0] op_sel_hi:[1,0,1] neg_lo:[1,0,0]
	v_pk_fma_f32 v[204:205], v[36:37], v[204:205], v[244:245] op_sel:[1,1,0] op_sel_hi:[1,0,1] neg_lo:[1,0,0]
	v_pk_fma_f32 v[206:207], v[38:39], v[206:207], v[254:255] op_sel:[1,1,0] op_sel_hi:[1,0,1] neg_lo:[1,0,0]
	v_cvt_pk_bf16_f32 v124, v200, v201
	v_cvt_pk_bf16_f32 v125, v202, v203
	v_cvt_pk_bf16_f32 v126, v204, v205
	v_cvt_pk_bf16_f32 v127, v206, v207
	ds_write_b128 v241, v[124:127] offset:4896
	s_waitcnt lgkmcnt(2)
; __device__ __forceinline__ unsigned f2bf(float f) { unsigned u = __builtin_bit_cast(unsigned, f); return (u + 0x7fffu + ((u >> 16) & 1u)) >> 16; }
; __device__ __forceinline__ bf16x8 pack8(const float (&f)[8]) { u32x4 h; h.x = pk2(f[0], f[1]); h.y = pk2(f[2], f[3]); h.z = pk2(f[4], f[5]); h.w = pk2(f[6], f[7]); return __builtin_bit_cast(bf16x8, h); }
; template <bool FINAL> __device__ __forceinline__ void phase_s5_scan(const Fr& F) {
;     ...
;         for (int sub = 0; sub < 4; ++sub) {
;             const bf16x8 A1 = __builtin_bit_cast(bf16x8, uc[sub]);
; #pragma unroll
;             for (int nt = 0; nt < 8; ++nt) {
;                 f32x4 acc = {0.f, 0.f, 0.f, 0.f};
;                 acc = __builtin_amdgcn_mfma_f32_16x16x32_bf16(A1, B1[nt], acc, 0, 0, 0);
; #pragma unroll
;                 for (int reg = 0; reg < 4; ++reg) BUl[(4 * lq + reg) * 132 + 16 * nt + l15] = acc[reg];
;             }
;             asm volatile("s_waitcnt lgkmcnt(0)" ::: "memory");
; #pragma unroll 4
;             for (int jj = 0; jj < 16; ++jj) {
;                 const float br_ = BUl[jj * 132 + lane], bi_ = BUl[jj * 132 + 64 + lane];
;                 const float nr = ar * xr - ai * xi + br_, ni = ar * xi + ai * xr + bi_; xr = nr; xi = ni;
;                 if (FINAL) { BUl[jj * 132 + lane] = xr; BUl[jj * 132 + 64 + lane] = xi; }
;             }
;             if (FINAL) {
;                 asm volatile("s_waitcnt lgkmcnt(0)" ::: "memory");
;                 f32x4 acc = {0.f, 0.f, 0.f, 0.f};
; #pragma unroll
;                 for (int ks = 0; ks < 4; ++ks) {
;                     const f32x4 t0 = *(const f32x4*)(BUl + l15 * 132 + 32 * ks + 8 * lq), t1 = *(const f32x4*)(BUl + l15 * 132 + 32 * ks + 8 * lq + 4);
;                     const float xf[8] = {t0.x, t0.y, t0.z, t0.w, t1.x, t1.y, t1.z, t1.w};
;                     acc = __builtin_amdgcn_mfma_f32_16x16x32_bf16(pack8(xf), Chi[ks], acc, 0, 0, 0);
;                 }
; #pragma unroll
;                 for (int reg = 0; reg < 4; ++reg) { const int tok = tokof(s, chunk * 64 + sub * 16 + 4 * lq + reg);
;                     Yb[((size_t)b * TB + tok) * D + g * 16 + l15] = (bf16)f2bf(acc[reg]); }
;                 asm volatile("s_waitcnt lgkmcnt(0)" ::: "memory");
	v_mfma_f32_16x16x32_bf16 v[120:123], v[40:43], v[216:219], 0
	v_mfma_f32_16x16x32_bf16 v[120:123], v[44:47], v[220:223], v[120:123]
	v_mfma_f32_16x16x32_bf16 v[120:123], v[48:51], v[224:227], v[120:123]
	v_mfma_f32_16x16x32_bf16 v[120:123], v[52:55], v[228:231], v[120:123]
	v_pk_mov_b32 v[232:233], v[170:171], v[186:187] op_sel:[0,0]
	v_pk_mov_b32 v[234:235], v[174:175], v[190:191] op_sel:[0,0]
	v_pk_mov_b32 v[244:245], v[178:179], v[194:195] op_sel:[0,0]
	v_pk_mov_b32 v[254:255], v[182:183], v[198:199] op_sel:[0,0]
	v_pk_fma_f32 v[232:233], v[32:33], v[200:201], v[232:233] op_sel_hi:[0,1,1]
	v_pk_fma_f32 v[234:235], v[34:35], v[202:203], v[234:235] op_sel_hi:[0,1,1]
	v_pk_fma_f32 v[244:245], v[36:37], v[204:205], v[244:245] op_sel_hi:[0,1,1]
	v_pk_fma_f32 v[254:255], v[38:39], v[206:207], v[254:255] op_sel_hi:[0,1,1]
	v_pk_fma_f32 v[200:201], v[32:33], v[200:201], v[232:233] op_sel:[1,1,0] op_sel_hi:[1,0,1] neg_lo:[1,0,0]
	v_pk_fma_f32 v[202:203], v[34:35], v[202:203], v[234:235] op_sel:[1,1,0] op_sel_hi:[1,0,1] neg_lo:[1,0,0]
	v_pk_fma_f32 v[204:205], v[36:37], v[204:205], v[244:245] op_sel:[1,1,0] op_sel_hi:[1,0,1] neg_lo:[1,0,0]
	v_pk_fma_f32 v[206:207], v[38:39], v[206:207], v[254:255] op_sel:[1,1,0] op_sel_hi:[1,0,1] neg_lo:[1,0,0]
	v_cvt_pk_bf16_f32 v124, v200, v201
	v_cvt_pk_bf16_f32 v125, v202, v203
	v_cvt_pk_bf16_f32 v126, v204, v205
	v_cvt_pk_bf16_f32 v127, v206, v207
	ds_write_b128 v241, v[124:127] offset:5184
	v_pk_mov_b32 v[232:233], v[170:171], v[186:187] op_sel:[1,1]
	v_pk_mov_b32 v[234:235], v[174:175], v[190:191] op_sel:[1,1]
	v_pk_mov_b32 v[244:245], v[178:179], v[194:195] op_sel:[1,1]
	v_pk_mov_b32 v[254:255], v[182:183], v[198:199] op_sel:[1,1]
	v_pk_fma_f32 v[232:233], v[32:33], v[200:201], v[232:233] op_sel_hi:[0,1,1]
	v_pk_fma_f32 v[234:235], v[34:35], v[202:203], v[234:235] op_sel_hi:[0,1,1]
	v_pk_fma_f32 v[244:245], v[36:37], v[204:205], v[244:245] op_sel_hi:[0,1,1]
	v_pk_fma_f32 v[254:255], v[38:39], v[206:207], v[254:255] op_sel_hi:[0,1,1]
	v_pk_fma_f32 v[200:201], v[32:33], v[200:201], v[232:233] op_sel:[1,1,0] op_sel_hi:[1,0,1] neg_lo:[1,0,0]
	v_pk_fma_f32 v[202:203], v[34:35], v[202:203], v[234:235] op_sel:[1,1,0] op_sel_hi:[1,0,1] neg_lo:[1,0,0]
	v_pk_fma_f32 v[204:205], v[36:37], v[204:205], v[244:245] op_sel:[1,1,0] op_sel_hi:[1,0,1] neg_lo:[1,0,0]
	v_pk_fma_f32 v[206:207], v[38:39], v[206:207], v[254:255] op_sel:[1,1,0] op_sel_hi:[1,0,1] neg_lo:[1,0,0]
	v_cvt_pk_bf16_f32 v124, v200, v201
	v_cvt_pk_bf16_f32 v125, v202, v203
	v_cvt_pk_bf16_f32 v126, v204, v205
	v_cvt_pk_bf16_f32 v127, v206, v207
	ds_write_b128 v241, v[124:127] offset:5472
	global_load_dwordx4 v[84:87], v238, s[20:21]
	v_add_u32_e32 v238, v238, v243
	v_cvt_pk_bf16_f32 v124, v120, v121
	v_cvt_pk_bf16_f32 v125, v122, v123
	s_nop 0
	global_store_dwordx2 v239, v[124:125], s[24:25]
	v_add_u32_e32 v239, v239, v243
	s_waitcnt vmcnt(33)
	v_mfma_f32_16x16x32_bf16 v[168:171], v[92:95], v[0:3], 0
	v_mfma_f32_16x16x32_bf16 v[172:175], v[92:95], v[4:7], 0
	v_mfma_f32_16x16x32_bf16 v[176:179], v[92:95], v[8:11], 0
	v_mfma_f32_16x16x32_bf16 v[180:183], v[92:95], v[12:15], 0
	v_mfma_f32_16x16x32_bf16 v[184:187], v[92:95], v[16:19], 0
	v_mfma_f32_16x16x32_bf16 v[188:191], v[92:95], v[20:23], 0
	v_mfma_f32_16x16x32_bf16 v[192:195], v[92:95], v[24:27], 0
	v_mfma_f32_16x16x32_bf16 v[196:199], v[92:95], v[28:31], 0
	ds_read_b128 v[216:219], v242 offset:4608
	ds_read_b128 v[220:223], v242 offset:4672
	ds_read_b128 v[224:227], v242 offset:4736
	ds_read_b128 v[228:231], v242 offset:4800
	v_pk_mov_b32 v[232:233], v[136:137], v[152:153] op_sel:[0,0]
	v_pk_mov_b32 v[234:235], v[140:141], v[156:157] op_sel:[0,0]
	v_pk_mov_b32 v[244:245], v[144:145], v[160:161] op_sel:[0,0]
	v_pk_mov_b32 v[254:255], v[148:149], v[164:165] op_sel:[0,0]
	v_pk_fma_f32 v[232:233], v[32:33], v[200:201], v[232:233] op_sel_hi:[0,1,1]
	v_pk_fma_f32 v[234:235], v[34:35], v[202:203], v[234:235] op_sel_hi:[0,1,1]
	v_pk_fma_f32 v[244:245], v[36:37], v[204:205], v[244:245] op_sel_hi:[0,1,1]
	v_pk_fma_f32 v[254:255], v[38:39], v[206:207], v[254:255] op_sel_hi:[0,1,1]
	v_pk_fma_f32 v[200:201], v[32:33], v[200:201], v[232:233] op_sel:[1,1,0] op_sel_hi:[1,0,1] neg_lo:[1,0,0]
	v_pk_fma_f32 v[202:203], v[34:35], v[202:203], v[234:235] op_sel:[1,1,0] op_sel_hi:[1,0,1] neg_lo:[1,0,0]
	v_pk_fma_f32 v[204:205], v[36:37], v[204:205], v[244:245] op_sel:[1,1,0] op_sel_hi:[1,0,1] neg_lo:[1,0,0]
	v_pk_fma_f32 v[206:207], v[38:39], v[206:207], v[254:255] op_sel:[1,1,0] op_sel_hi:[1,0,1] neg_lo:[1,0,0]
	v_cvt_pk_bf16_f32 v124, v200, v201
	v_cvt_pk_bf16_f32 v125, v202, v203
	v_cvt_pk_bf16_f32 v126, v204, v205
	v_cvt_pk_bf16_f32 v127, v206, v207
	ds_write_b128 v241, v[124:127] offset:0
	v_pk_mov_b32 v[232:233], v[136:137], v[152:153] op_sel:[1,1]
	v_pk_mov_b32 v[234:235], v[140:141], v[156:157] op_sel:[1,1]
	v_pk_mov_b32 v[244:245], v[144:145], v[160:161] op_sel:[1,1]
	v_pk_mov_b32 v[254:255], v[148:149], v[164:165] op_sel:[1,1]
	v_pk_fma_f32 v[232:233], v[32:33], v[200:201], v[232:233] op_sel_hi:[0,1,1]
	v_pk_fma_f32 v[234:235], v[34:35], v[202:203], v[234:235] op_sel_hi:[0,1,1]
	v_pk_fma_f32 v[244:245], v[36:37], v[204:205], v[244:245] op_sel_hi:[0,1,1]
	v_pk_fma_f32 v[254:255], v[38:39], v[206:207], v[254:255] op_sel_hi:[0,1,1]
	v_pk_fma_f32 v[200:201], v[32:33], v[200:201], v[232:233] op_sel:[1,1,0] op_sel_hi:[1,0,1] neg_lo:[1,0,0]
	v_pk_fma_f32 v[202:203], v[34:35], v[202:203], v[234:235] op_sel:[1,1,0] op_sel_hi:[1,0,1] neg_lo:[1,0,0]
	v_pk_fma_f32 v[204:205], v[36:37], v[204:205], v[244:245] op_sel:[1,1,0] op_sel_hi:[1,0,1] neg_lo:[1,0,0]
	v_pk_fma_f32 v[206:207], v[38:39], v[206:207], v[254:255] op_sel:[1,1,0] op_sel_hi:[1,0,1] neg_lo:[1,0,0]
	v_cvt_pk_bf16_f32 v124, v200, v201
	v_cvt_pk_bf16_f32 v125, v202, v203
	v_cvt_pk_bf16_f32 v126, v204, v205
	v_cvt_pk_bf16_f32 v127, v206, v207
	ds_write_b128 v241, v[124:127] offset:288
	s_waitcnt lgkmcnt(2)
; __device__ __forceinline__ unsigned f2bf(float f) { unsigned u = __builtin_bit_cast(unsigned, f); return (u + 0x7fffu + ((u >> 16) & 1u)) >> 16; }
; __device__ __forceinline__ bf16x8 pack8(const float (&f)[8]) { u32x4 h; h.x = pk2(f[0], f[1]); h.y = pk2(f[2], f[3]); h.z = pk2(f[4], f[5]); h.w = pk2(f[6], f[7]); return __builtin_bit_cast(bf16x8, h); }
; template <bool FINAL> __device__ __forceinline__ void phase_s5_scan(const Fr& F) {
;     ...
;         for (int sub = 0; sub < 4; ++sub) {
;             const bf16x8 A1 = __builtin_bit_cast(bf16x8, uc[sub]);
; #pragma unroll
;             for (int nt = 0; nt < 8; ++nt) {
;                 f32x4 acc = {0.f, 0.f, 0.f, 0.f};
;                 acc = __builtin_amdgcn_mfma_f32_16x16x32_bf16(A1, B1[nt], acc, 0, 0, 0);
; #pragma unroll
;                 for (int reg = 0; reg < 4; ++reg) BUl[(4 * lq + reg) * 132 + 16 * nt + l15] = acc[reg];
;             }
;             asm volatile("s_waitcnt lgkmcnt(0)" ::: "memory");
; #pragma unroll 4
;             for (int jj = 0; jj < 16; ++jj) {
;                 const float br_ = BUl[jj * 132 + lane], bi_ = BUl[jj * 132 + 64 + lane];
;                 const float nr = ar * xr - ai * xi + br_, ni = ar * xi + ai * xr + bi_; xr = nr; xi = ni;
;                 if (FINAL) { BUl[jj * 132 + lane] = xr; BUl[jj * 132 + 64 + lane] = xi; }
;             }
;             if (FINAL) {
;                 asm volatile("s_waitcnt lgkmcnt(0)" ::: "memory");
;                 f32x4 acc = {0.f, 0.f, 0.f, 0.f};
; #pragma unroll
;                 for (int ks = 0; ks < 4; ++ks) {
;                     const f32x4 t0 = *(const f32x4*)(BUl + l15 * 132 + 32 * ks + 8 * lq), t1 = *(const f32x4*)(BUl + l15 * 132 + 32 * ks + 8 * lq + 4);
;                     const float xf[8] = {t0.x, t0.y, t0.z, t0.w, t1.x, t1.y, t1.z, t1.w};
;                     acc = __builtin_amdgcn_mfma_f32_16x16x32_bf16(pack8(xf), Chi[ks], acc, 0, 0, 0);
;                 }
; #pragma unroll
;                 for (int reg = 0; reg < 4; ++reg) { const int tok = tokof(s, chunk * 64 + sub * 16 + 4 * lq + reg);
;                     Yb[((size_t)b * TB + tok) * D + g * 16 + l15] = (bf16)f2bf(acc[reg]); }
;                 asm volatile("s_waitcnt lgkmcnt(0)" ::: "memory");
	v_mfma_f32_16x16x32_bf16 v[120:123], v[40:43], v[216:219], 0
	v_mfma_f32_16x16x32_bf16 v[120:123], v[44:47], v[220:223], v[120:123]
	v_mfma_f32_16x16x32_bf16 v[120:123], v[48:51], v[224:227], v[120:123]
	v_mfma_f32_16x16x32_bf16 v[120:123], v[52:55], v[228:231], v[120:123]
	v_pk_mov_b32 v[232:233], v[138:139], v[154:155] op_sel:[0,0]
	v_pk_mov_b32 v[234:235], v[142:143], v[158:159] op_sel:[0,0]
	v_pk_mov_b32 v[244:245], v[146:147], v[162:163] op_sel:[0,0]
	v_pk_mov_b32 v[254:255], v[150:151], v[166:167] op_sel:[0,0]
	v_pk_fma_f32 v[232:233], v[32:33], v[200:201], v[232:233] op_sel_hi:[0,1,1]
	v_pk_fma_f32 v[234:235], v[34:35], v[202:203], v[234:235] op_sel_hi:[0,1,1]
	v_pk_fma_f32 v[244:245], v[36:37], v[204:205], v[244:245] op_sel_hi:[0,1,1]
	v_pk_fma_f32 v[254:255], v[38:39], v[206:207], v[254:255] op_sel_hi:[0,1,1]
	v_pk_fma_f32 v[200:201], v[32:33], v[200:201], v[232:233] op_sel:[1,1,0] op_sel_hi:[1,0,1] neg_lo:[1,0,0]
	v_pk_fma_f32 v[202:203], v[34:35], v[202:203], v[234:235] op_sel:[1,1,0] op_sel_hi:[1,0,1] neg_lo:[1,0,0]
	v_pk_fma_f32 v[204:205], v[36:37], v[204:205], v[244:245] op_sel:[1,1,0] op_sel_hi:[1,0,1] neg_lo:[1,0,0]
	v_pk_fma_f32 v[206:207], v[38:39], v[206:207], v[254:255] op_sel:[1,1,0] op_sel_hi:[1,0,1] neg_lo:[1,0,0]
	v_cvt_pk_bf16_f32 v124, v200, v201
	v_cvt_pk_bf16_f32 v125, v202, v203
	v_cvt_pk_bf16_f32 v126, v204, v205
	v_cvt_pk_bf16_f32 v127, v206, v207
	ds_write_b128 v241, v[124:127] offset:576
	v_pk_mov_b32 v[232:233], v[138:139], v[154:155] op_sel:[1,1]
	v_pk_mov_b32 v[234:235], v[142:143], v[158:159] op_sel:[1,1]
	v_pk_mov_b32 v[244:245], v[146:147], v[162:163] op_sel:[1,1]
	v_pk_mov_b32 v[254:255], v[150:151], v[166:167] op_sel:[1,1]
	v_pk_fma_f32 v[232:233], v[32:33], v[200:201], v[232:233] op_sel_hi:[0,1,1]
	v_pk_fma_f32 v[234:235], v[34:35], v[202:203], v[234:235] op_sel_hi:[0,1,1]
	v_pk_fma_f32 v[244:245], v[36:37], v[204:205], v[244:245] op_sel_hi:[0,1,1]
	v_pk_fma_f32 v[254:255], v[38:39], v[206:207], v[254:255] op_sel_hi:[0,1,1]
	v_pk_fma_f32 v[200:201], v[32:33], v[200:201], v[232:233] op_sel:[1,1,0] op_sel_hi:[1,0,1] neg_lo:[1,0,0]
	v_pk_fma_f32 v[202:203], v[34:35], v[202:203], v[234:235] op_sel:[1,1,0] op_sel_hi:[1,0,1] neg_lo:[1,0,0]
	v_pk_fma_f32 v[204:205], v[36:37], v[204:205], v[244:245] op_sel:[1,1,0] op_sel_hi:[1,0,1] neg_lo:[1,0,0]
	v_pk_fma_f32 v[206:207], v[38:39], v[206:207], v[254:255] op_sel:[1,1,0] op_sel_hi:[1,0,1] neg_lo:[1,0,0]
	v_cvt_pk_bf16_f32 v124, v200, v201
	v_cvt_pk_bf16_f32 v125, v202, v203
	v_cvt_pk_bf16_f32 v126, v204, v205
	v_cvt_pk_bf16_f32 v127, v206, v207
	ds_write_b128 v241, v[124:127] offset:864
	global_load_dwordx4 v[88:91], v238, s[20:21]
	v_add_u32_e32 v238, v238, v243
	v_cvt_pk_bf16_f32 v124, v120, v121
	v_cvt_pk_bf16_f32 v125, v122, v123
	s_nop 0
	global_store_dwordx2 v239, v[124:125], s[24:25]
	v_add_u32_e32 v239, v239, v243
	s_waitcnt vmcnt(33)
	v_mfma_f32_16x16x32_bf16 v[136:139], v[96:99], v[0:3], 0
	v_mfma_f32_16x16x32_bf16 v[140:143], v[96:99], v[4:7], 0
	v_mfma_f32_16x16x32_bf16 v[144:147], v[96:99], v[8:11], 0
	v_mfma_f32_16x16x32_bf16 v[148:151], v[96:99], v[12:15], 0
	v_mfma_f32_16x16x32_bf16 v[152:155], v[96:99], v[16:19], 0
	v_mfma_f32_16x16x32_bf16 v[156:159], v[96:99], v[20:23], 0
	v_mfma_f32_16x16x32_bf16 v[160:163], v[96:99], v[24:27], 0
	v_mfma_f32_16x16x32_bf16 v[164:167], v[96:99], v[28:31], 0
	ds_read_b128 v[216:219], v242 offset:0
	ds_read_b128 v[220:223], v242 offset:64
	ds_read_b128 v[224:227], v242 offset:128
	ds_read_b128 v[228:231], v242 offset:192
	v_pk_mov_b32 v[232:233], v[168:169], v[184:185] op_sel:[0,0]
	v_pk_mov_b32 v[234:235], v[172:173], v[188:189] op_sel:[0,0]
	v_pk_mov_b32 v[244:245], v[176:177], v[192:193] op_sel:[0,0]
	v_pk_mov_b32 v[254:255], v[180:181], v[196:197] op_sel:[0,0]
	v_pk_fma_f32 v[232:233], v[32:33], v[200:201], v[232:233] op_sel_hi:[0,1,1]
	v_pk_fma_f32 v[234:235], v[34:35], v[202:203], v[234:235] op_sel_hi:[0,1,1]
	v_pk_fma_f32 v[244:245], v[36:37], v[204:205], v[244:245] op_sel_hi:[0,1,1]
	v_pk_fma_f32 v[254:255], v[38:39], v[206:207], v[254:255] op_sel_hi:[0,1,1]
	v_pk_fma_f32 v[200:201], v[32:33], v[200:201], v[232:233] op_sel:[1,1,0] op_sel_hi:[1,0,1] neg_lo:[1,0,0]
	v_pk_fma_f32 v[202:203], v[34:35], v[202:203], v[234:235] op_sel:[1,1,0] op_sel_hi:[1,0,1] neg_lo:[1,0,0]
	v_pk_fma_f32 v[204:205], v[36:37], v[204:205], v[244:245] op_sel:[1,1,0] op_sel_hi:[1,0,1] neg_lo:[1,0,0]
	v_pk_fma_f32 v[206:207], v[38:39], v[206:207], v[254:255] op_sel:[1,1,0] op_sel_hi:[1,0,1] neg_lo:[1,0,0]
	v_cvt_pk_bf16_f32 v124, v200, v201
	v_cvt_pk_bf16_f32 v125, v202, v203
	v_cvt_pk_bf16_f32 v126, v204, v205
	v_cvt_pk_bf16_f32 v127, v206, v207
	ds_write_b128 v241, v[124:127] offset:4608
	v_pk_mov_b32 v[232:233], v[168:169], v[184:185] op_sel:[1,1]
	v_pk_mov_b32 v[234:235], v[172:173], v[188:189] op_sel:[1,1]
	v_pk_mov_b32 v[244:245], v[176:177], v[192:193] op_sel:[1,1]
	v_pk_mov_b32 v[254:255], v[180:181], v[196:197] op_sel:[1,1]
	v_pk_fma_f32 v[232:233], v[32:33], v[200:201], v[232:233] op_sel_hi:[0,1,1]
	v_pk_fma_f32 v[234:235], v[34:35], v[202:203], v[234:235] op_sel_hi:[0,1,1]
	v_pk_fma_f32 v[244:245], v[36:37], v[204:205], v[244:245] op_sel_hi:[0,1,1]
	v_pk_fma_f32 v[254:255], v[38:39], v[206:207], v[254:255] op_sel_hi:[0,1,1]
	v_pk_fma_f32 v[200:201], v[32:33], v[200:201], v[232:233] op_sel:[1,1,0] op_sel_hi:[1,0,1] neg_lo:[1,0,0]
	v_pk_fma_f32 v[202:203], v[34:35], v[202:203], v[234:235] op_sel:[1,1,0] op_sel_hi:[1,0,1] neg_lo:[1,0,0]
	v_pk_fma_f32 v[204:205], v[36:37], v[204:205], v[244:245] op_sel:[1,1,0] op_sel_hi:[1,0,1] neg_lo:[1,0,0]
	v_pk_fma_f32 v[206:207], v[38:39], v[206:207], v[254:255] op_sel:[1,1,0] op_sel_hi:[1,0,1] neg_lo:[1,0,0]
	v_cvt_pk_bf16_f32 v124, v200, v201
	v_cvt_pk_bf16_f32 v125, v202, v203
	v_cvt_pk_bf16_f32 v126, v204, v205
	v_cvt_pk_bf16_f32 v127, v206, v207
	ds_write_b128 v241, v[124:127] offset:4896
	s_waitcnt lgkmcnt(2)
; __device__ __forceinline__ unsigned f2bf(float f) { unsigned u = __builtin_bit_cast(unsigned, f); return (u + 0x7fffu + ((u >> 16) & 1u)) >> 16; }
; __device__ __forceinline__ bf16x8 pack8(const float (&f)[8]) { u32x4 h; h.x = pk2(f[0], f[1]); h.y = pk2(f[2], f[3]); h.z = pk2(f[4], f[5]); h.w = pk2(f[6], f[7]); return __builtin_bit_cast(bf16x8, h); }
; template <bool FINAL> __device__ __forceinline__ void phase_s5_scan(const Fr& F) {
;     ...
;         for (int sub = 0; sub < 4; ++sub) {
;             const bf16x8 A1 = __builtin_bit_cast(bf16x8, uc[sub]);
; #pragma unroll
;             for (int nt = 0; nt < 8; ++nt) {
;                 f32x4 acc = {0.f, 0.f, 0.f, 0.f};
;                 acc = __builtin_amdgcn_mfma_f32_16x16x32_bf16(A1, B1[nt], acc, 0, 0, 0);
; #pragma unroll
;                 for (int reg = 0; reg < 4; ++reg) BUl[(4 * lq + reg) * 132 + 16 * nt + l15] = acc[reg];
;             }
;             asm volatile("s_waitcnt lgkmcnt(0)" ::: "memory");
; #pragma unroll 4
;             for (int jj = 0; jj < 16; ++jj) {
;                 const float br_ = BUl[jj * 132 + lane], bi_ = BUl[jj * 132 + 64 + lane];
;                 const float nr = ar * xr - ai * xi + br_, ni = ar * xi + ai * xr + bi_; xr = nr; xi = ni;
;                 if (FINAL) { BUl[jj * 132 + lane] = xr; BUl[jj * 132 + 64 + lane] = xi; }
;             }
;             if (FINAL) {
;                 asm volatile("s_waitcnt lgkmcnt(0)" ::: "memory");
;                 f32x4 acc = {0.f, 0.f, 0.f, 0.f};
; #pragma unroll
;                 for (int ks = 0; ks < 4; ++ks) {
;                     const f32x4 t0 = *(const f32x4*)(BUl + l15 * 132 + 32 * ks + 8 * lq), t1 = *(const f32x4*)(BUl + l15 * 132 + 32 * ks + 8 * lq + 4);
;                     const float xf[8] = {t0.x, t0.y, t0.z, t0.w, t1.x, t1.y, t1.z, t1.w};
;                     acc = __builtin_amdgcn_mfma_f32_16x16x32_bf16(pack8(xf), Chi[ks], acc, 0, 0, 0);
;                 }
; #pragma unroll
;                 for (int reg = 0; reg < 4; ++reg) { const int tok = tokof(s, chunk * 64 + sub * 16 + 4 * lq + reg);
;                     Yb[((size_t)b * TB + tok) * D + g * 16 + l15] = (bf16)f2bf(acc[reg]); }
;                 asm volatile("s_waitcnt lgkmcnt(0)" ::: "memory");
	v_mfma_f32_16x16x32_bf16 v[120:123], v[40:43], v[216:219], 0
	v_mfma_f32_16x16x32_bf16 v[120:123], v[44:47], v[220:223], v[120:123]
	v_mfma_f32_16x16x32_bf16 v[120:123], v[48:51], v[224:227], v[120:123]
	v_mfma_f32_16x16x32_bf16 v[120:123], v[52:55], v[228:231], v[120:123]
	v_pk_mov_b32 v[232:233], v[170:171], v[186:187] op_sel:[0,0]
	v_pk_mov_b32 v[234:235], v[174:175], v[190:191] op_sel:[0,0]
	v_pk_mov_b32 v[244:245], v[178:179], v[194:195] op_sel:[0,0]
	v_pk_mov_b32 v[254:255], v[182:183], v[198:199] op_sel:[0,0]
	v_pk_fma_f32 v[232:233], v[32:33], v[200:201], v[232:233] op_sel_hi:[0,1,1]
	v_pk_fma_f32 v[234:235], v[34:35], v[202:203], v[234:235] op_sel_hi:[0,1,1]
	v_pk_fma_f32 v[244:245], v[36:37], v[204:205], v[244:245] op_sel_hi:[0,1,1]
	v_pk_fma_f32 v[254:255], v[38:39], v[206:207], v[254:255] op_sel_hi:[0,1,1]
	v_pk_fma_f32 v[200:201], v[32:33], v[200:201], v[232:233] op_sel:[1,1,0] op_sel_hi:[1,0,1] neg_lo:[1,0,0]
	v_pk_fma_f32 v[202:203], v[34:35], v[202:203], v[234:235] op_sel:[1,1,0] op_sel_hi:[1,0,1] neg_lo:[1,0,0]
	v_pk_fma_f32 v[204:205], v[36:37], v[204:205], v[244:245] op_sel:[1,1,0] op_sel_hi:[1,0,1] neg_lo:[1,0,0]
	v_pk_fma_f32 v[206:207], v[38:39], v[206:207], v[254:255] op_sel:[1,1,0] op_sel_hi:[1,0,1] neg_lo:[1,0,0]
	v_cvt_pk_bf16_f32 v124, v200, v201
	v_cvt_pk_bf16_f32 v125, v202, v203
	v_cvt_pk_bf16_f32 v126, v204, v205
	v_cvt_pk_bf16_f32 v127, v206, v207
	ds_write_b128 v241, v[124:127] offset:5184
	v_pk_mov_b32 v[232:233], v[170:171], v[186:187] op_sel:[1,1]
	v_pk_mov_b32 v[234:235], v[174:175], v[190:191] op_sel:[1,1]
	v_pk_mov_b32 v[244:245], v[178:179], v[194:195] op_sel:[1,1]
	v_pk_mov_b32 v[254:255], v[182:183], v[198:199] op_sel:[1,1]
	v_pk_fma_f32 v[232:233], v[32:33], v[200:201], v[232:233] op_sel_hi:[0,1,1]
	v_pk_fma_f32 v[234:235], v[34:35], v[202:203], v[234:235] op_sel_hi:[0,1,1]
	v_pk_fma_f32 v[244:245], v[36:37], v[204:205], v[244:245] op_sel_hi:[0,1,1]
	v_pk_fma_f32 v[254:255], v[38:39], v[206:207], v[254:255] op_sel_hi:[0,1,1]
	v_pk_fma_f32 v[200:201], v[32:33], v[200:201], v[232:233] op_sel:[1,1,0] op_sel_hi:[1,0,1] neg_lo:[1,0,0]
	v_pk_fma_f32 v[202:203], v[34:35], v[202:203], v[234:235] op_sel:[1,1,0] op_sel_hi:[1,0,1] neg_lo:[1,0,0]
	v_pk_fma_f32 v[204:205], v[36:37], v[204:205], v[244:245] op_sel:[1,1,0] op_sel_hi:[1,0,1] neg_lo:[1,0,0]
	v_pk_fma_f32 v[206:207], v[38:39], v[206:207], v[254:255] op_sel:[1,1,0] op_sel_hi:[1,0,1] neg_lo:[1,0,0]
	v_cvt_pk_bf16_f32 v124, v200, v201
	v_cvt_pk_bf16_f32 v125, v202, v203
	v_cvt_pk_bf16_f32 v126, v204, v205
	v_cvt_pk_bf16_f32 v127, v206, v207
	ds_write_b128 v241, v[124:127] offset:5472
	global_load_dwordx4 v[92:95], v238, s[20:21]
	v_add_u32_e32 v238, v238, v243
	v_cvt_pk_bf16_f32 v124, v120, v121
	v_cvt_pk_bf16_f32 v125, v122, v123
	s_nop 0
	global_store_dwordx2 v239, v[124:125], s[24:25]
	v_add_u32_e32 v239, v239, v243
	s_waitcnt vmcnt(33)
	v_mfma_f32_16x16x32_bf16 v[168:171], v[100:103], v[0:3], 0
	v_mfma_f32_16x16x32_bf16 v[172:175], v[100:103], v[4:7], 0
	v_mfma_f32_16x16x32_bf16 v[176:179], v[100:103], v[8:11], 0
	v_mfma_f32_16x16x32_bf16 v[180:183], v[100:103], v[12:15], 0
	v_mfma_f32_16x16x32_bf16 v[184:187], v[100:103], v[16:19], 0
	v_mfma_f32_16x16x32_bf16 v[188:191], v[100:103], v[20:23], 0
	v_mfma_f32_16x16x32_bf16 v[192:195], v[100:103], v[24:27], 0
	v_mfma_f32_16x16x32_bf16 v[196:199], v[100:103], v[28:31], 0
	ds_read_b128 v[216:219], v242 offset:4608
	ds_read_b128 v[220:223], v242 offset:4672
	ds_read_b128 v[224:227], v242 offset:4736
	ds_read_b128 v[228:231], v242 offset:4800
	v_pk_mov_b32 v[232:233], v[136:137], v[152:153] op_sel:[0,0]
	v_pk_mov_b32 v[234:235], v[140:141], v[156:157] op_sel:[0,0]
	v_pk_mov_b32 v[244:245], v[144:145], v[160:161] op_sel:[0,0]
	v_pk_mov_b32 v[254:255], v[148:149], v[164:165] op_sel:[0,0]
	v_pk_fma_f32 v[232:233], v[32:33], v[200:201], v[232:233] op_sel_hi:[0,1,1]
	v_pk_fma_f32 v[234:235], v[34:35], v[202:203], v[234:235] op_sel_hi:[0,1,1]
	v_pk_fma_f32 v[244:245], v[36:37], v[204:205], v[244:245] op_sel_hi:[0,1,1]
	v_pk_fma_f32 v[254:255], v[38:39], v[206:207], v[254:255] op_sel_hi:[0,1,1]
	v_pk_fma_f32 v[200:201], v[32:33], v[200:201], v[232:233] op_sel:[1,1,0] op_sel_hi:[1,0,1] neg_lo:[1,0,0]
	v_pk_fma_f32 v[202:203], v[34:35], v[202:203], v[234:235] op_sel:[1,1,0] op_sel_hi:[1,0,1] neg_lo:[1,0,0]
	v_pk_fma_f32 v[204:205], v[36:37], v[204:205], v[244:245] op_sel:[1,1,0] op_sel_hi:[1,0,1] neg_lo:[1,0,0]
	v_pk_fma_f32 v[206:207], v[38:39], v[206:207], v[254:255] op_sel:[1,1,0] op_sel_hi:[1,0,1] neg_lo:[1,0,0]
	v_cvt_pk_bf16_f32 v124, v200, v201
	v_cvt_pk_bf16_f32 v125, v202, v203
	v_cvt_pk_bf16_f32 v126, v204, v205
	v_cvt_pk_bf16_f32 v127, v206, v207
	ds_write_b128 v241, v[124:127] offset:0
	v_pk_mov_b32 v[232:233], v[136:137], v[152:153] op_sel:[1,1]
	v_pk_mov_b32 v[234:235], v[140:141], v[156:157] op_sel:[1,1]
	v_pk_mov_b32 v[244:245], v[144:145], v[160:161] op_sel:[1,1]
	v_pk_mov_b32 v[254:255], v[148:149], v[164:165] op_sel:[1,1]
	v_pk_fma_f32 v[232:233], v[32:33], v[200:201], v[232:233] op_sel_hi:[0,1,1]
	v_pk_fma_f32 v[234:235], v[34:35], v[202:203], v[234:235] op_sel_hi:[0,1,1]
	v_pk_fma_f32 v[244:245], v[36:37], v[204:205], v[244:245] op_sel_hi:[0,1,1]
	v_pk_fma_f32 v[254:255], v[38:39], v[206:207], v[254:255] op_sel_hi:[0,1,1]
	v_pk_fma_f32 v[200:201], v[32:33], v[200:201], v[232:233] op_sel:[1,1,0] op_sel_hi:[1,0,1] neg_lo:[1,0,0]
	v_pk_fma_f32 v[202:203], v[34:35], v[202:203], v[234:235] op_sel:[1,1,0] op_sel_hi:[1,0,1] neg_lo:[1,0,0]
	v_pk_fma_f32 v[204:205], v[36:37], v[204:205], v[244:245] op_sel:[1,1,0] op_sel_hi:[1,0,1] neg_lo:[1,0,0]
	v_pk_fma_f32 v[206:207], v[38:39], v[206:207], v[254:255] op_sel:[1,1,0] op_sel_hi:[1,0,1] neg_lo:[1,0,0]
	v_cvt_pk_bf16_f32 v124, v200, v201
	v_cvt_pk_bf16_f32 v125, v202, v203
	v_cvt_pk_bf16_f32 v126, v204, v205
	v_cvt_pk_bf16_f32 v127, v206, v207
	ds_write_b128 v241, v[124:127] offset:288
	s_waitcnt lgkmcnt(2)
; __device__ __forceinline__ unsigned f2bf(float f) { unsigned u = __builtin_bit_cast(unsigned, f); return (u + 0x7fffu + ((u >> 16) & 1u)) >> 16; }
; __device__ __forceinline__ bf16x8 pack8(const float (&f)[8]) { u32x4 h; h.x = pk2(f[0], f[1]); h.y = pk2(f[2], f[3]); h.z = pk2(f[4], f[5]); h.w = pk2(f[6], f[7]); return __builtin_bit_cast(bf16x8, h); }
; template <bool FINAL> __device__ __forceinline__ void phase_s5_scan(const Fr& F) {
;     ...
;         for (int sub = 0; sub < 4; ++sub) {
;             const bf16x8 A1 = __builtin_bit_cast(bf16x8, uc[sub]);
; #pragma unroll
;             for (int nt = 0; nt < 8; ++nt) {
;                 f32x4 acc = {0.f, 0.f, 0.f, 0.f};
;                 acc = __builtin_amdgcn_mfma_f32_16x16x32_bf16(A1, B1[nt], acc, 0, 0, 0);
; #pragma unroll
;                 for (int reg = 0; reg < 4; ++reg) BUl[(4 * lq + reg) * 132 + 16 * nt + l15] = acc[reg];
;             }
;             asm volatile("s_waitcnt lgkmcnt(0)" ::: "memory");
; #pragma unroll 4
;             for (int jj = 0; jj < 16; ++jj) {
;                 const float br_ = BUl[jj * 132 + lane], bi_ = BUl[jj * 132 + 64 + lane];
;                 const float nr = ar * xr - ai * xi + br_, ni = ar * xi + ai * xr + bi_; xr = nr; xi = ni;
;                 if (FINAL) { BUl[jj * 132 + lane] = xr; BUl[jj * 132 + 64 + lane] = xi; }
;             }
;             if (FINAL) {
;                 asm volatile("s_waitcnt lgkmcnt(0)" ::: "memory");
;                 f32x4 acc = {0.f, 0.f, 0.f, 0.f};
; #pragma unroll
;                 for (int ks = 0; ks < 4; ++ks) {
;                     const f32x4 t0 = *(const f32x4*)(BUl + l15 * 132 + 32 * ks + 8 * lq), t1 = *(const f32x4*)(BUl + l15 * 132 + 32 * ks + 8 * lq + 4);
;                     const float xf[8] = {t0.x, t0.y, t0.z, t0.w, t1.x, t1.y, t1.z, t1.w};
;                     acc = __builtin_amdgcn_mfma_f32_16x16x32_bf16(pack8(xf), Chi[ks], acc, 0, 0, 0);
;                 }
; #pragma unroll
;                 for (int reg = 0; reg < 4; ++reg) { const int tok = tokof(s, chunk * 64 + sub * 16 + 4 * lq + reg);
;                     Yb[((size_t)b * TB + tok) * D + g * 16 + l15] = (bf16)f2bf(acc[reg]); }
;                 asm volatile("s_waitcnt lgkmcnt(0)" ::: "memory");
	v_mfma_f32_16x16x32_bf16 v[120:123], v[40:43], v[216:219], 0
	v_mfma_f32_16x16x32_bf16 v[120:123], v[44:47], v[220:223], v[120:123]
	v_mfma_f32_16x16x32_bf16 v[120:123], v[48:51], v[224:227], v[120:123]
	v_mfma_f32_16x16x32_bf16 v[120:123], v[52:55], v[228:231], v[120:123]
	v_pk_mov_b32 v[232:233], v[138:139], v[154:155] op_sel:[0,0]
	v_pk_mov_b32 v[234:235], v[142:143], v[158:159] op_sel:[0,0]
	v_pk_mov_b32 v[244:245], v[146:147], v[162:163] op_sel:[0,0]
	v_pk_mov_b32 v[254:255], v[150:151], v[166:167] op_sel:[0,0]
	v_pk_fma_f32 v[232:233], v[32:33], v[200:201], v[232:233] op_sel_hi:[0,1,1]
	v_pk_fma_f32 v[234:235], v[34:35], v[202:203], v[234:235] op_sel_hi:[0,1,1]
	v_pk_fma_f32 v[244:245], v[36:37], v[204:205], v[244:245] op_sel_hi:[0,1,1]
	v_pk_fma_f32 v[254:255], v[38:39], v[206:207], v[254:255] op_sel_hi:[0,1,1]
	v_pk_fma_f32 v[200:201], v[32:33], v[200:201], v[232:233] op_sel:[1,1,0] op_sel_hi:[1,0,1] neg_lo:[1,0,0]
	v_pk_fma_f32 v[202:203], v[34:35], v[202:203], v[234:235] op_sel:[1,1,0] op_sel_hi:[1,0,1] neg_lo:[1,0,0]
	v_pk_fma_f32 v[204:205], v[36:37], v[204:205], v[244:245] op_sel:[1,1,0] op_sel_hi:[1,0,1] neg_lo:[1,0,0]
	v_pk_fma_f32 v[206:207], v[38:39], v[206:207], v[254:255] op_sel:[1,1,0] op_sel_hi:[1,0,1] neg_lo:[1,0,0]
	v_cvt_pk_bf16_f32 v124, v200, v201
	v_cvt_pk_bf16_f32 v125, v202, v203
	v_cvt_pk_bf16_f32 v126, v204, v205
	v_cvt_pk_bf16_f32 v127, v206, v207
	ds_write_b128 v241, v[124:127] offset:576
	v_pk_mov_b32 v[232:233], v[138:139], v[154:155] op_sel:[1,1]
	v_pk_mov_b32 v[234:235], v[142:143], v[158:159] op_sel:[1,1]
	v_pk_mov_b32 v[244:245], v[146:147], v[162:163] op_sel:[1,1]
	v_pk_mov_b32 v[254:255], v[150:151], v[166:167] op_sel:[1,1]
	v_pk_fma_f32 v[232:233], v[32:33], v[200:201], v[232:233] op_sel_hi:[0,1,1]
	v_pk_fma_f32 v[234:235], v[34:35], v[202:203], v[234:235] op_sel_hi:[0,1,1]
	v_pk_fma_f32 v[244:245], v[36:37], v[204:205], v[244:245] op_sel_hi:[0,1,1]
	v_pk_fma_f32 v[254:255], v[38:39], v[206:207], v[254:255] op_sel_hi:[0,1,1]
	v_pk_fma_f32 v[200:201], v[32:33], v[200:201], v[232:233] op_sel:[1,1,0] op_sel_hi:[1,0,1] neg_lo:[1,0,0]
	v_pk_fma_f32 v[202:203], v[34:35], v[202:203], v[234:235] op_sel:[1,1,0] op_sel_hi:[1,0,1] neg_lo:[1,0,0]
	v_pk_fma_f32 v[204:205], v[36:37], v[204:205], v[244:245] op_sel:[1,1,0] op_sel_hi:[1,0,1] neg_lo:[1,0,0]
	v_pk_fma_f32 v[206:207], v[38:39], v[206:207], v[254:255] op_sel:[1,1,0] op_sel_hi:[1,0,1] neg_lo:[1,0,0]
	v_cvt_pk_bf16_f32 v124, v200, v201
	v_cvt_pk_bf16_f32 v125, v202, v203
	v_cvt_pk_bf16_f32 v126, v204, v205
	v_cvt_pk_bf16_f32 v127, v206, v207
	ds_write_b128 v241, v[124:127] offset:864
	global_load_dwordx4 v[96:99], v238, s[20:21]
	v_add_u32_e32 v238, v238, v243
	v_cvt_pk_bf16_f32 v124, v120, v121
	v_cvt_pk_bf16_f32 v125, v122, v123
	s_nop 0
	global_store_dwordx2 v239, v[124:125], s[24:25]
	v_add_u32_e32 v239, v239, v243
	s_waitcnt vmcnt(33)
	v_mfma_f32_16x16x32_bf16 v[136:139], v[104:107], v[0:3], 0
	v_mfma_f32_16x16x32_bf16 v[140:143], v[104:107], v[4:7], 0
	v_mfma_f32_16x16x32_bf16 v[144:147], v[104:107], v[8:11], 0
	v_mfma_f32_16x16x32_bf16 v[148:151], v[104:107], v[12:15], 0
	v_mfma_f32_16x16x32_bf16 v[152:155], v[104:107], v[16:19], 0
	v_mfma_f32_16x16x32_bf16 v[156:159], v[104:107], v[20:23], 0
	v_mfma_f32_16x16x32_bf16 v[160:163], v[104:107], v[24:27], 0
	v_mfma_f32_16x16x32_bf16 v[164:167], v[104:107], v[28:31], 0
	ds_read_b128 v[216:219], v242 offset:0
	ds_read_b128 v[220:223], v242 offset:64
	ds_read_b128 v[224:227], v242 offset:128
	ds_read_b128 v[228:231], v242 offset:192
	v_pk_mov_b32 v[232:233], v[168:169], v[184:185] op_sel:[0,0]
	v_pk_mov_b32 v[234:235], v[172:173], v[188:189] op_sel:[0,0]
	v_pk_mov_b32 v[244:245], v[176:177], v[192:193] op_sel:[0,0]
	v_pk_mov_b32 v[254:255], v[180:181], v[196:197] op_sel:[0,0]
	v_pk_fma_f32 v[232:233], v[32:33], v[200:201], v[232:233] op_sel_hi:[0,1,1]
	v_pk_fma_f32 v[234:235], v[34:35], v[202:203], v[234:235] op_sel_hi:[0,1,1]
	v_pk_fma_f32 v[244:245], v[36:37], v[204:205], v[244:245] op_sel_hi:[0,1,1]
	v_pk_fma_f32 v[254:255], v[38:39], v[206:207], v[254:255] op_sel_hi:[0,1,1]
	v_pk_fma_f32 v[200:201], v[32:33], v[200:201], v[232:233] op_sel:[1,1,0] op_sel_hi:[1,0,1] neg_lo:[1,0,0]
	v_pk_fma_f32 v[202:203], v[34:35], v[202:203], v[234:235] op_sel:[1,1,0] op_sel_hi:[1,0,1] neg_lo:[1,0,0]
	v_pk_fma_f32 v[204:205], v[36:37], v[204:205], v[244:245] op_sel:[1,1,0] op_sel_hi:[1,0,1] neg_lo:[1,0,0]
	v_pk_fma_f32 v[206:207], v[38:39], v[206:207], v[254:255] op_sel:[1,1,0] op_sel_hi:[1,0,1] neg_lo:[1,0,0]
	v_cvt_pk_bf16_f32 v124, v200, v201
	v_cvt_pk_bf16_f32 v125, v202, v203
	v_cvt_pk_bf16_f32 v126, v204, v205
	v_cvt_pk_bf16_f32 v127, v206, v207
	ds_write_b128 v241, v[124:127] offset:4608
	v_pk_mov_b32 v[232:233], v[168:169], v[184:185] op_sel:[1,1]
	v_pk_mov_b32 v[234:235], v[172:173], v[188:189] op_sel:[1,1]
	v_pk_mov_b32 v[244:245], v[176:177], v[192:193] op_sel:[1,1]
	v_pk_mov_b32 v[254:255], v[180:181], v[196:197] op_sel:[1,1]
	v_pk_fma_f32 v[232:233], v[32:33], v[200:201], v[232:233] op_sel_hi:[0,1,1]
	v_pk_fma_f32 v[234:235], v[34:35], v[202:203], v[234:235] op_sel_hi:[0,1,1]
	v_pk_fma_f32 v[244:245], v[36:37], v[204:205], v[244:245] op_sel_hi:[0,1,1]
	v_pk_fma_f32 v[254:255], v[38:39], v[206:207], v[254:255] op_sel_hi:[0,1,1]
	v_pk_fma_f32 v[200:201], v[32:33], v[200:201], v[232:233] op_sel:[1,1,0] op_sel_hi:[1,0,1] neg_lo:[1,0,0]
	v_pk_fma_f32 v[202:203], v[34:35], v[202:203], v[234:235] op_sel:[1,1,0] op_sel_hi:[1,0,1] neg_lo:[1,0,0]
	v_pk_fma_f32 v[204:205], v[36:37], v[204:205], v[244:245] op_sel:[1,1,0] op_sel_hi:[1,0,1] neg_lo:[1,0,0]
	v_pk_fma_f32 v[206:207], v[38:39], v[206:207], v[254:255] op_sel:[1,1,0] op_sel_hi:[1,0,1] neg_lo:[1,0,0]
	v_cvt_pk_bf16_f32 v124, v200, v201
	v_cvt_pk_bf16_f32 v125, v202, v203
	v_cvt_pk_bf16_f32 v126, v204, v205
	v_cvt_pk_bf16_f32 v127, v206, v207
	ds_write_b128 v241, v[124:127] offset:4896
	s_waitcnt lgkmcnt(2)
; __device__ __forceinline__ unsigned f2bf(float f) { unsigned u = __builtin_bit_cast(unsigned, f); return (u + 0x7fffu + ((u >> 16) & 1u)) >> 16; }
; __device__ __forceinline__ bf16x8 pack8(const float (&f)[8]) { u32x4 h; h.x = pk2(f[0], f[1]); h.y = pk2(f[2], f[3]); h.z = pk2(f[4], f[5]); h.w = pk2(f[6], f[7]); return __builtin_bit_cast(bf16x8, h); }
; template <bool FINAL> __device__ __forceinline__ void phase_s5_scan(const Fr& F) {
;     ...
;         for (int sub = 0; sub < 4; ++sub) {
;             const bf16x8 A1 = __builtin_bit_cast(bf16x8, uc[sub]);
; #pragma unroll
;             for (int nt = 0; nt < 8; ++nt) {
;                 f32x4 acc = {0.f, 0.f, 0.f, 0.f};
;                 acc = __builtin_amdgcn_mfma_f32_16x16x32_bf16(A1, B1[nt], acc, 0, 0, 0);
; #pragma unroll
;                 for (int reg = 0; reg < 4; ++reg) BUl[(4 * lq + reg) * 132 + 16 * nt + l15] = acc[reg];
;             }
;             asm volatile("s_waitcnt lgkmcnt(0)" ::: "memory");
; #pragma unroll 4
;             for (int jj = 0; jj < 16; ++jj) {
;                 const float br_ = BUl[jj * 132 + lane], bi_ = BUl[jj * 132 + 64 + lane];
;                 const float nr = ar * xr - ai * xi + br_, ni = ar * xi + ai * xr + bi_; xr = nr; xi = ni;
;                 if (FINAL) { BUl[jj * 132 + lane] = xr; BUl[jj * 132 + 64 + lane] = xi; }
;             }
;             if (FINAL) {
;                 asm volatile("s_waitcnt lgkmcnt(0)" ::: "memory");
;                 f32x4 acc = {0.f, 0.f, 0.f, 0.f};
; #pragma unroll
;                 for (int ks = 0; ks < 4; ++ks) {
;                     const f32x4 t0 = *(const f32x4*)(BUl + l15 * 132 + 32 * ks + 8 * lq), t1 = *(const f32x4*)(BUl + l15 * 132 + 32 * ks + 8 * lq + 4);
;                     const float xf[8] = {t0.x, t0.y, t0.z, t0.w, t1.x, t1.y, t1.z, t1.w};
;                     acc = __builtin_amdgcn_mfma_f32_16x16x32_bf16(pack8(xf), Chi[ks], acc, 0, 0, 0);
;                 }
; #pragma unroll
;                 for (int reg = 0; reg < 4; ++reg) { const int tok = tokof(s, chunk * 64 + sub * 16 + 4 * lq + reg);
;                     Yb[((size_t)b * TB + tok) * D + g * 16 + l15] = (bf16)f2bf(acc[reg]); }
;                 asm volatile("s_waitcnt lgkmcnt(0)" ::: "memory");
	v_mfma_f32_16x16x32_bf16 v[120:123], v[40:43], v[216:219], 0
	v_mfma_f32_16x16x32_bf16 v[120:123], v[44:47], v[220:223], v[120:123]
	v_mfma_f32_16x16x32_bf16 v[120:123], v[48:51], v[224:227], v[120:123]
	v_mfma_f32_16x16x32_bf16 v[120:123], v[52:55], v[228:231], v[120:123]
	v_pk_mov_b32 v[232:233], v[170:171], v[186:187] op_sel:[0,0]
	v_pk_mov_b32 v[234:235], v[174:175], v[190:191] op_sel:[0,0]
	v_pk_mov_b32 v[244:245], v[178:179], v[194:195] op_sel:[0,0]
	v_pk_mov_b32 v[254:255], v[182:183], v[198:199] op_sel:[0,0]
	v_pk_fma_f32 v[232:233], v[32:33], v[200:201], v[232:233] op_sel_hi:[0,1,1]
	v_pk_fma_f32 v[234:235], v[34:35], v[202:203], v[234:235] op_sel_hi:[0,1,1]
	v_pk_fma_f32 v[244:245], v[36:37], v[204:205], v[244:245] op_sel_hi:[0,1,1]
	v_pk_fma_f32 v[254:255], v[38:39], v[206:207], v[254:255] op_sel_hi:[0,1,1]
	v_pk_fma_f32 v[200:201], v[32:33], v[200:201], v[232:233] op_sel:[1,1,0] op_sel_hi:[1,0,1] neg_lo:[1,0,0]
	v_pk_fma_f32 v[202:203], v[34:35], v[202:203], v[234:235] op_sel:[1,1,0] op_sel_hi:[1,0,1] neg_lo:[1,0,0]
	v_pk_fma_f32 v[204:205], v[36:37], v[204:205], v[244:245] op_sel:[1,1,0] op_sel_hi:[1,0,1] neg_lo:[1,0,0]
	v_pk_fma_f32 v[206:207], v[38:39], v[206:207], v[254:255] op_sel:[1,1,0] op_sel_hi:[1,0,1] neg_lo:[1,0,0]
	v_cvt_pk_bf16_f32 v124, v200, v201
	v_cvt_pk_bf16_f32 v125, v202, v203
	v_cvt_pk_bf16_f32 v126, v204, v205
	v_cvt_pk_bf16_f32 v127, v206, v207
	ds_write_b128 v241, v[124:127] offset:5184
	v_pk_mov_b32 v[232:233], v[170:171], v[186:187] op_sel:[1,1]
	v_pk_mov_b32 v[234:235], v[174:175], v[190:191] op_sel:[1,1]
	v_pk_mov_b32 v[244:245], v[178:179], v[194:195] op_sel:[1,1]
	v_pk_mov_b32 v[254:255], v[182:183], v[198:199] op_sel:[1,1]
	v_pk_fma_f32 v[232:233], v[32:33], v[200:201], v[232:233] op_sel_hi:[0,1,1]
	v_pk_fma_f32 v[234:235], v[34:35], v[202:203], v[234:235] op_sel_hi:[0,1,1]
	v_pk_fma_f32 v[244:245], v[36:37], v[204:205], v[244:245] op_sel_hi:[0,1,1]
	v_pk_fma_f32 v[254:255], v[38:39], v[206:207], v[254:255] op_sel_hi:[0,1,1]
	v_pk_fma_f32 v[200:201], v[32:33], v[200:201], v[232:233] op_sel:[1,1,0] op_sel_hi:[1,0,1] neg_lo:[1,0,0]
	v_pk_fma_f32 v[202:203], v[34:35], v[202:203], v[234:235] op_sel:[1,1,0] op_sel_hi:[1,0,1] neg_lo:[1,0,0]
	v_pk_fma_f32 v[204:205], v[36:37], v[204:205], v[244:245] op_sel:[1,1,0] op_sel_hi:[1,0,1] neg_lo:[1,0,0]
	v_pk_fma_f32 v[206:207], v[38:39], v[206:207], v[254:255] op_sel:[1,1,0] op_sel_hi:[1,0,1] neg_lo:[1,0,0]
	v_cvt_pk_bf16_f32 v124, v200, v201
	v_cvt_pk_bf16_f32 v125, v202, v203
	v_cvt_pk_bf16_f32 v126, v204, v205
	v_cvt_pk_bf16_f32 v127, v206, v207
	ds_write_b128 v241, v[124:127] offset:5472
	global_load_dwordx4 v[100:103], v238, s[20:21]
	v_add_u32_e32 v238, v238, v243
	v_cvt_pk_bf16_f32 v124, v120, v121
	v_cvt_pk_bf16_f32 v125, v122, v123
	s_nop 0
	global_store_dwordx2 v239, v[124:125], s[24:25]
	v_add_u32_e32 v239, v239, v243
	s_waitcnt vmcnt(33)
	v_mfma_f32_16x16x32_bf16 v[168:171], v[108:111], v[0:3], 0
	v_mfma_f32_16x16x32_bf16 v[172:175], v[108:111], v[4:7], 0
	v_mfma_f32_16x16x32_bf16 v[176:179], v[108:111], v[8:11], 0
	v_mfma_f32_16x16x32_bf16 v[180:183], v[108:111], v[12:15], 0
	v_mfma_f32_16x16x32_bf16 v[184:187], v[108:111], v[16:19], 0
	v_mfma_f32_16x16x32_bf16 v[188:191], v[108:111], v[20:23], 0
	v_mfma_f32_16x16x32_bf16 v[192:195], v[108:111], v[24:27], 0
	v_mfma_f32_16x16x32_bf16 v[196:199], v[108:111], v[28:31], 0
	ds_read_b128 v[216:219], v242 offset:4608
	ds_read_b128 v[220:223], v242 offset:4672
	ds_read_b128 v[224:227], v242 offset:4736
	ds_read_b128 v[228:231], v242 offset:4800
	v_pk_mov_b32 v[232:233], v[136:137], v[152:153] op_sel:[0,0]
	v_pk_mov_b32 v[234:235], v[140:141], v[156:157] op_sel:[0,0]
	v_pk_mov_b32 v[244:245], v[144:145], v[160:161] op_sel:[0,0]
	v_pk_mov_b32 v[254:255], v[148:149], v[164:165] op_sel:[0,0]
	v_pk_fma_f32 v[232:233], v[32:33], v[200:201], v[232:233] op_sel_hi:[0,1,1]
	v_pk_fma_f32 v[234:235], v[34:35], v[202:203], v[234:235] op_sel_hi:[0,1,1]
	v_pk_fma_f32 v[244:245], v[36:37], v[204:205], v[244:245] op_sel_hi:[0,1,1]
	v_pk_fma_f32 v[254:255], v[38:39], v[206:207], v[254:255] op_sel_hi:[0,1,1]
	v_pk_fma_f32 v[200:201], v[32:33], v[200:201], v[232:233] op_sel:[1,1,0] op_sel_hi:[1,0,1] neg_lo:[1,0,0]
	v_pk_fma_f32 v[202:203], v[34:35], v[202:203], v[234:235] op_sel:[1,1,0] op_sel_hi:[1,0,1] neg_lo:[1,0,0]
	v_pk_fma_f32 v[204:205], v[36:37], v[204:205], v[244:245] op_sel:[1,1,0] op_sel_hi:[1,0,1] neg_lo:[1,0,0]
	v_pk_fma_f32 v[206:207], v[38:39], v[206:207], v[254:255] op_sel:[1,1,0] op_sel_hi:[1,0,1] neg_lo:[1,0,0]
	v_cvt_pk_bf16_f32 v124, v200, v201
	v_cvt_pk_bf16_f32 v125, v202, v203
	v_cvt_pk_bf16_f32 v126, v204, v205
	v_cvt_pk_bf16_f32 v127, v206, v207
	ds_write_b128 v241, v[124:127] offset:0
	v_pk_mov_b32 v[232:233], v[136:137], v[152:153] op_sel:[1,1]
	v_pk_mov_b32 v[234:235], v[140:141], v[156:157] op_sel:[1,1]
	v_pk_mov_b32 v[244:245], v[144:145], v[160:161] op_sel:[1,1]
	v_pk_mov_b32 v[254:255], v[148:149], v[164:165] op_sel:[1,1]
	v_pk_fma_f32 v[232:233], v[32:33], v[200:201], v[232:233] op_sel_hi:[0,1,1]
	v_pk_fma_f32 v[234:235], v[34:35], v[202:203], v[234:235] op_sel_hi:[0,1,1]
	v_pk_fma_f32 v[244:245], v[36:37], v[204:205], v[244:245] op_sel_hi:[0,1,1]
	v_pk_fma_f32 v[254:255], v[38:39], v[206:207], v[254:255] op_sel_hi:[0,1,1]
	v_pk_fma_f32 v[200:201], v[32:33], v[200:201], v[232:233] op_sel:[1,1,0] op_sel_hi:[1,0,1] neg_lo:[1,0,0]
	v_pk_fma_f32 v[202:203], v[34:35], v[202:203], v[234:235] op_sel:[1,1,0] op_sel_hi:[1,0,1] neg_lo:[1,0,0]
	v_pk_fma_f32 v[204:205], v[36:37], v[204:205], v[244:245] op_sel:[1,1,0] op_sel_hi:[1,0,1] neg_lo:[1,0,0]
	v_pk_fma_f32 v[206:207], v[38:39], v[206:207], v[254:255] op_sel:[1,1,0] op_sel_hi:[1,0,1] neg_lo:[1,0,0]
	v_cvt_pk_bf16_f32 v124, v200, v201
	v_cvt_pk_bf16_f32 v125, v202, v203
	v_cvt_pk_bf16_f32 v126, v204, v205
	v_cvt_pk_bf16_f32 v127, v206, v207
	ds_write_b128 v241, v[124:127] offset:288
	s_waitcnt lgkmcnt(2)
; __device__ __forceinline__ unsigned f2bf(float f) { unsigned u = __builtin_bit_cast(unsigned, f); return (u + 0x7fffu + ((u >> 16) & 1u)) >> 16; }
; __device__ __forceinline__ bf16x8 pack8(const float (&f)[8]) { u32x4 h; h.x = pk2(f[0], f[1]); h.y = pk2(f[2], f[3]); h.z = pk2(f[4], f[5]); h.w = pk2(f[6], f[7]); return __builtin_bit_cast(bf16x8, h); }
; template <bool FINAL> __device__ __forceinline__ void phase_s5_scan(const Fr& F) {
;     ...
;         for (int sub = 0; sub < 4; ++sub) {
;             const bf16x8 A1 = __builtin_bit_cast(bf16x8, uc[sub]);
; #pragma unroll
;             for (int nt = 0; nt < 8; ++nt) {
;                 f32x4 acc = {0.f, 0.f, 0.f, 0.f};
;                 acc = __builtin_amdgcn_mfma_f32_16x16x32_bf16(A1, B1[nt], acc, 0, 0, 0);
; #pragma unroll
;                 for (int reg = 0; reg < 4; ++reg) BUl[(4 * lq + reg) * 132 + 16 * nt + l15] = acc[reg];
;             }
;             asm volatile("s_waitcnt lgkmcnt(0)" ::: "memory");
; #pragma unroll 4
;             for (int jj = 0; jj < 16; ++jj) {
;                 const float br_ = BUl[jj * 132 + lane], bi_ = BUl[jj * 132 + 64 + lane];
;                 const float nr = ar * xr - ai * xi + br_, ni = ar * xi + ai * xr + bi_; xr = nr; xi = ni;
;                 if (FINAL) { BUl[jj * 132 + lane] = xr; BUl[jj * 132 + 64 + lane] = xi; }
;             }
;             if (FINAL) {
;                 asm volatile("s_waitcnt lgkmcnt(0)" ::: "memory");
;                 f32x4 acc = {0.f, 0.f, 0.f, 0.f};
; #pragma unroll
;                 for (int ks = 0; ks < 4; ++ks) {
;                     const f32x4 t0 = *(const f32x4*)(BUl + l15 * 132 + 32 * ks + 8 * lq), t1 = *(const f32x4*)(BUl + l15 * 132 + 32 * ks + 8 * lq + 4);
;                     const float xf[8] = {t0.x, t0.y, t0.z, t0.w, t1.x, t1.y, t1.z, t1.w};
;                     acc = __builtin_amdgcn_mfma_f32_16x16x32_bf16(pack8(xf), Chi[ks], acc, 0, 0, 0);
;                 }
; #pragma unroll
;                 for (int reg = 0; reg < 4; ++reg) { const int tok = tokof(s, chunk * 64 + sub * 16 + 4 * lq + reg);
;                     Yb[((size_t)b * TB + tok) * D + g * 16 + l15] = (bf16)f2bf(acc[reg]); }
;                 asm volatile("s_waitcnt lgkmcnt(0)" ::: "memory");
	v_mfma_f32_16x16x32_bf16 v[120:123], v[40:43], v[216:219], 0
	v_mfma_f32_16x16x32_bf16 v[120:123], v[44:47], v[220:223], v[120:123]
	v_mfma_f32_16x16x32_bf16 v[120:123], v[48:51], v[224:227], v[120:123]
	v_mfma_f32_16x16x32_bf16 v[120:123], v[52:55], v[228:231], v[120:123]
	v_pk_mov_b32 v[232:233], v[138:139], v[154:155] op_sel:[0,0]
	v_pk_mov_b32 v[234:235], v[142:143], v[158:159] op_sel:[0,0]
	v_pk_mov_b32 v[244:245], v[146:147], v[162:163] op_sel:[0,0]
	v_pk_mov_b32 v[254:255], v[150:151], v[166:167] op_sel:[0,0]
	v_pk_fma_f32 v[232:233], v[32:33], v[200:201], v[232:233] op_sel_hi:[0,1,1]
	v_pk_fma_f32 v[234:235], v[34:35], v[202:203], v[234:235] op_sel_hi:[0,1,1]
	v_pk_fma_f32 v[244:245], v[36:37], v[204:205], v[244:245] op_sel_hi:[0,1,1]
	v_pk_fma_f32 v[254:255], v[38:39], v[206:207], v[254:255] op_sel_hi:[0,1,1]
	v_pk_fma_f32 v[200:201], v[32:33], v[200:201], v[232:233] op_sel:[1,1,0] op_sel_hi:[1,0,1] neg_lo:[1,0,0]
	v_pk_fma_f32 v[202:203], v[34:35], v[202:203], v[234:235] op_sel:[1,1,0] op_sel_hi:[1,0,1] neg_lo:[1,0,0]
	v_pk_fma_f32 v[204:205], v[36:37], v[204:205], v[244:245] op_sel:[1,1,0] op_sel_hi:[1,0,1] neg_lo:[1,0,0]
	v_pk_fma_f32 v[206:207], v[38:39], v[206:207], v[254:255] op_sel:[1,1,0] op_sel_hi:[1,0,1] neg_lo:[1,0,0]
	v_cvt_pk_bf16_f32 v124, v200, v201
	v_cvt_pk_bf16_f32 v125, v202, v203
	v_cvt_pk_bf16_f32 v126, v204, v205
	v_cvt_pk_bf16_f32 v127, v206, v207
	ds_write_b128 v241, v[124:127] offset:576
	v_pk_mov_b32 v[232:233], v[138:139], v[154:155] op_sel:[1,1]
	v_pk_mov_b32 v[234:235], v[142:143], v[158:159] op_sel:[1,1]
	v_pk_mov_b32 v[244:245], v[146:147], v[162:163] op_sel:[1,1]
	v_pk_mov_b32 v[254:255], v[150:151], v[166:167] op_sel:[1,1]
	v_pk_fma_f32 v[232:233], v[32:33], v[200:201], v[232:233] op_sel_hi:[0,1,1]
	v_pk_fma_f32 v[234:235], v[34:35], v[202:203], v[234:235] op_sel_hi:[0,1,1]
	v_pk_fma_f32 v[244:245], v[36:37], v[204:205], v[244:245] op_sel_hi:[0,1,1]
	v_pk_fma_f32 v[254:255], v[38:39], v[206:207], v[254:255] op_sel_hi:[0,1,1]
	v_pk_fma_f32 v[200:201], v[32:33], v[200:201], v[232:233] op_sel:[1,1,0] op_sel_hi:[1,0,1] neg_lo:[1,0,0]
	v_pk_fma_f32 v[202:203], v[34:35], v[202:203], v[234:235] op_sel:[1,1,0] op_sel_hi:[1,0,1] neg_lo:[1,0,0]
	v_pk_fma_f32 v[204:205], v[36:37], v[204:205], v[244:245] op_sel:[1,1,0] op_sel_hi:[1,0,1] neg_lo:[1,0,0]
	v_pk_fma_f32 v[206:207], v[38:39], v[206:207], v[254:255] op_sel:[1,1,0] op_sel_hi:[1,0,1] neg_lo:[1,0,0]
	v_cvt_pk_bf16_f32 v124, v200, v201
	v_cvt_pk_bf16_f32 v125, v202, v203
	v_cvt_pk_bf16_f32 v126, v204, v205
	v_cvt_pk_bf16_f32 v127, v206, v207
	ds_write_b128 v241, v[124:127] offset:864
	global_load_dwordx4 v[104:107], v238, s[20:21]
	v_add_u32_e32 v238, v238, v243
	v_cvt_pk_bf16_f32 v124, v120, v121
	v_cvt_pk_bf16_f32 v125, v122, v123
	s_nop 0
	global_store_dwordx2 v239, v[124:125], s[24:25]
	v_add_u32_e32 v239, v239, v243
	s_waitcnt vmcnt(33)
	v_mfma_f32_16x16x32_bf16 v[136:139], v[112:115], v[0:3], 0
	v_mfma_f32_16x16x32_bf16 v[140:143], v[112:115], v[4:7], 0
	v_mfma_f32_16x16x32_bf16 v[144:147], v[112:115], v[8:11], 0
	v_mfma_f32_16x16x32_bf16 v[148:151], v[112:115], v[12:15], 0
	v_mfma_f32_16x16x32_bf16 v[152:155], v[112:115], v[16:19], 0
	v_mfma_f32_16x16x32_bf16 v[156:159], v[112:115], v[20:23], 0
	v_mfma_f32_16x16x32_bf16 v[160:163], v[112:115], v[24:27], 0
	v_mfma_f32_16x16x32_bf16 v[164:167], v[112:115], v[28:31], 0
	ds_read_b128 v[216:219], v242 offset:0
	ds_read_b128 v[220:223], v242 offset:64
	ds_read_b128 v[224:227], v242 offset:128
	ds_read_b128 v[228:231], v242 offset:192
	v_pk_mov_b32 v[232:233], v[168:169], v[184:185] op_sel:[0,0]
	v_pk_mov_b32 v[234:235], v[172:173], v[188:189] op_sel:[0,0]
	v_pk_mov_b32 v[244:245], v[176:177], v[192:193] op_sel:[0,0]
	v_pk_mov_b32 v[254:255], v[180:181], v[196:197] op_sel:[0,0]
	v_pk_fma_f32 v[232:233], v[32:33], v[200:201], v[232:233] op_sel_hi:[0,1,1]
	v_pk_fma_f32 v[234:235], v[34:35], v[202:203], v[234:235] op_sel_hi:[0,1,1]
	v_pk_fma_f32 v[244:245], v[36:37], v[204:205], v[244:245] op_sel_hi:[0,1,1]
	v_pk_fma_f32 v[254:255], v[38:39], v[206:207], v[254:255] op_sel_hi:[0,1,1]
	v_pk_fma_f32 v[200:201], v[32:33], v[200:201], v[232:233] op_sel:[1,1,0] op_sel_hi:[1,0,1] neg_lo:[1,0,0]
	v_pk_fma_f32 v[202:203], v[34:35], v[202:203], v[234:235] op_sel:[1,1,0] op_sel_hi:[1,0,1] neg_lo:[1,0,0]
	v_pk_fma_f32 v[204:205], v[36:37], v[204:205], v[244:245] op_sel:[1,1,0] op_sel_hi:[1,0,1] neg_lo:[1,0,0]
	v_pk_fma_f32 v[206:207], v[38:39], v[206:207], v[254:255] op_sel:[1,1,0] op_sel_hi:[1,0,1] neg_lo:[1,0,0]
	v_cvt_pk_bf16_f32 v124, v200, v201
	v_cvt_pk_bf16_f32 v125, v202, v203
	v_cvt_pk_bf16_f32 v126, v204, v205
	v_cvt_pk_bf16_f32 v127, v206, v207
	ds_write_b128 v241, v[124:127] offset:4608
	v_pk_mov_b32 v[232:233], v[168:169], v[184:185] op_sel:[1,1]
	v_pk_mov_b32 v[234:235], v[172:173], v[188:189] op_sel:[1,1]
	v_pk_mov_b32 v[244:245], v[176:177], v[192:193] op_sel:[1,1]
	v_pk_mov_b32 v[254:255], v[180:181], v[196:197] op_sel:[1,1]
	v_pk_fma_f32 v[232:233], v[32:33], v[200:201], v[232:233] op_sel_hi:[0,1,1]
	v_pk_fma_f32 v[234:235], v[34:35], v[202:203], v[234:235] op_sel_hi:[0,1,1]
	v_pk_fma_f32 v[244:245], v[36:37], v[204:205], v[244:245] op_sel_hi:[0,1,1]
	v_pk_fma_f32 v[254:255], v[38:39], v[206:207], v[254:255] op_sel_hi:[0,1,1]
	v_pk_fma_f32 v[200:201], v[32:33], v[200:201], v[232:233] op_sel:[1,1,0] op_sel_hi:[1,0,1] neg_lo:[1,0,0]
	v_pk_fma_f32 v[202:203], v[34:35], v[202:203], v[234:235] op_sel:[1,1,0] op_sel_hi:[1,0,1] neg_lo:[1,0,0]
	v_pk_fma_f32 v[204:205], v[36:37], v[204:205], v[244:245] op_sel:[1,1,0] op_sel_hi:[1,0,1] neg_lo:[1,0,0]
	v_pk_fma_f32 v[206:207], v[38:39], v[206:207], v[254:255] op_sel:[1,1,0] op_sel_hi:[1,0,1] neg_lo:[1,0,0]
	v_cvt_pk_bf16_f32 v124, v200, v201
	v_cvt_pk_bf16_f32 v125, v202, v203
	v_cvt_pk_bf16_f32 v126, v204, v205
	v_cvt_pk_bf16_f32 v127, v206, v207
	ds_write_b128 v241, v[124:127] offset:4896
	s_waitcnt lgkmcnt(2)
; __device__ __forceinline__ unsigned f2bf(float f) { unsigned u = __builtin_bit_cast(unsigned, f); return (u + 0x7fffu + ((u >> 16) & 1u)) >> 16; }
; __device__ __forceinline__ bf16x8 pack8(const float (&f)[8]) { u32x4 h; h.x = pk2(f[0], f[1]); h.y = pk2(f[2], f[3]); h.z = pk2(f[4], f[5]); h.w = pk2(f[6], f[7]); return __builtin_bit_cast(bf16x8, h); }
; template <bool FINAL> __device__ __forceinline__ void phase_s5_scan(const Fr& F) {
;     ...
;         for (int sub = 0; sub < 4; ++sub) {
;             const bf16x8 A1 = __builtin_bit_cast(bf16x8, uc[sub]);
; #pragma unroll
;             for (int nt = 0; nt < 8; ++nt) {
;                 f32x4 acc = {0.f, 0.f, 0.f, 0.f};
;                 acc = __builtin_amdgcn_mfma_f32_16x16x32_bf16(A1, B1[nt], acc, 0, 0, 0);
; #pragma unroll
;                 for (int reg = 0; reg < 4; ++reg) BUl[(4 * lq + reg) * 132 + 16 * nt + l15] = acc[reg];
;             }
;             asm volatile("s_waitcnt lgkmcnt(0)" ::: "memory");
; #pragma unroll 4
;             for (int jj = 0; jj < 16; ++jj) {
;                 const float br_ = BUl[jj * 132 + lane], bi_ = BUl[jj * 132 + 64 + lane];
;                 const float nr = ar * xr - ai * xi + br_, ni = ar * xi + ai * xr + bi_; xr = nr; xi = ni;
;                 if (FINAL) { BUl[jj * 132 + lane] = xr; BUl[jj * 132 + 64 + lane] = xi; }
;             }
;             if (FINAL) {
;                 asm volatile("s_waitcnt lgkmcnt(0)" ::: "memory");
;                 f32x4 acc = {0.f, 0.f, 0.f, 0.f};
; #pragma unroll
;                 for (int ks = 0; ks < 4; ++ks) {
;                     const f32x4 t0 = *(const f32x4*)(BUl + l15 * 132 + 32 * ks + 8 * lq), t1 = *(const f32x4*)(BUl + l15 * 132 + 32 * ks + 8 * lq + 4);
;                     const float xf[8] = {t0.x, t0.y, t0.z, t0.w, t1.x, t1.y, t1.z, t1.w};
;                     acc = __builtin_amdgcn_mfma_f32_16x16x32_bf16(pack8(xf), Chi[ks], acc, 0, 0, 0);
;                 }
; #pragma unroll
;                 for (int reg = 0; reg < 4; ++reg) { const int tok = tokof(s, chunk * 64 + sub * 16 + 4 * lq + reg);
;                     Yb[((size_t)b * TB + tok) * D + g * 16 + l15] = (bf16)f2bf(acc[reg]); }
;                 asm volatile("s_waitcnt lgkmcnt(0)" ::: "memory");
	v_mfma_f32_16x16x32_bf16 v[120:123], v[40:43], v[216:219], 0
	v_mfma_f32_16x16x32_bf16 v[120:123], v[44:47], v[220:223], v[120:123]
	v_mfma_f32_16x16x32_bf16 v[120:123], v[48:51], v[224:227], v[120:123]
	v_mfma_f32_16x16x32_bf16 v[120:123], v[52:55], v[228:231], v[120:123]
	v_pk_mov_b32 v[232:233], v[170:171], v[186:187] op_sel:[0,0]
	v_pk_mov_b32 v[234:235], v[174:175], v[190:191] op_sel:[0,0]
	v_pk_mov_b32 v[244:245], v[178:179], v[194:195] op_sel:[0,0]
	v_pk_mov_b32 v[254:255], v[182:183], v[198:199] op_sel:[0,0]
	v_pk_fma_f32 v[232:233], v[32:33], v[200:201], v[232:233] op_sel_hi:[0,1,1]
	v_pk_fma_f32 v[234:235], v[34:35], v[202:203], v[234:235] op_sel_hi:[0,1,1]
	v_pk_fma_f32 v[244:245], v[36:37], v[204:205], v[244:245] op_sel_hi:[0,1,1]
	v_pk_fma_f32 v[254:255], v[38:39], v[206:207], v[254:255] op_sel_hi:[0,1,1]
	v_pk_fma_f32 v[200:201], v[32:33], v[200:201], v[232:233] op_sel:[1,1,0] op_sel_hi:[1,0,1] neg_lo:[1,0,0]
	v_pk_fma_f32 v[202:203], v[34:35], v[202:203], v[234:235] op_sel:[1,1,0] op_sel_hi:[1,0,1] neg_lo:[1,0,0]
	v_pk_fma_f32 v[204:205], v[36:37], v[204:205], v[244:245] op_sel:[1,1,0] op_sel_hi:[1,0,1] neg_lo:[1,0,0]
	v_pk_fma_f32 v[206:207], v[38:39], v[206:207], v[254:255] op_sel:[1,1,0] op_sel_hi:[1,0,1] neg_lo:[1,0,0]
	v_cvt_pk_bf16_f32 v124, v200, v201
	v_cvt_pk_bf16_f32 v125, v202, v203
	v_cvt_pk_bf16_f32 v126, v204, v205
	v_cvt_pk_bf16_f32 v127, v206, v207
	ds_write_b128 v241, v[124:127] offset:5184
	v_pk_mov_b32 v[232:233], v[170:171], v[186:187] op_sel:[1,1]
	v_pk_mov_b32 v[234:235], v[174:175], v[190:191] op_sel:[1,1]
	v_pk_mov_b32 v[244:245], v[178:179], v[194:195] op_sel:[1,1]
	v_pk_mov_b32 v[254:255], v[182:183], v[198:199] op_sel:[1,1]
	v_pk_fma_f32 v[232:233], v[32:33], v[200:201], v[232:233] op_sel_hi:[0,1,1]
	v_pk_fma_f32 v[234:235], v[34:35], v[202:203], v[234:235] op_sel_hi:[0,1,1]
	v_pk_fma_f32 v[244:245], v[36:37], v[204:205], v[244:245] op_sel_hi:[0,1,1]
	v_pk_fma_f32 v[254:255], v[38:39], v[206:207], v[254:255] op_sel_hi:[0,1,1]
	v_pk_fma_f32 v[200:201], v[32:33], v[200:201], v[232:233] op_sel:[1,1,0] op_sel_hi:[1,0,1] neg_lo:[1,0,0]
	v_pk_fma_f32 v[202:203], v[34:35], v[202:203], v[234:235] op_sel:[1,1,0] op_sel_hi:[1,0,1] neg_lo:[1,0,0]
	v_pk_fma_f32 v[204:205], v[36:37], v[204:205], v[244:245] op_sel:[1,1,0] op_sel_hi:[1,0,1] neg_lo:[1,0,0]
	v_pk_fma_f32 v[206:207], v[38:39], v[206:207], v[254:255] op_sel:[1,1,0] op_sel_hi:[1,0,1] neg_lo:[1,0,0]
	v_cvt_pk_bf16_f32 v124, v200, v201
	v_cvt_pk_bf16_f32 v125, v202, v203
	v_cvt_pk_bf16_f32 v126, v204, v205
	v_cvt_pk_bf16_f32 v127, v206, v207
	ds_write_b128 v241, v[124:127] offset:5472
	global_load_dwordx4 v[108:111], v238, s[20:21]
	v_add_u32_e32 v238, v238, v243
	v_cvt_pk_bf16_f32 v124, v120, v121
	v_cvt_pk_bf16_f32 v125, v122, v123
	s_nop 0
	global_store_dwordx2 v239, v[124:125], s[24:25]
	v_add_u32_e32 v239, v239, v243
	s_waitcnt vmcnt(33)
	v_mfma_f32_16x16x32_bf16 v[168:171], v[116:119], v[0:3], 0
	v_mfma_f32_16x16x32_bf16 v[172:175], v[116:119], v[4:7], 0
	v_mfma_f32_16x16x32_bf16 v[176:179], v[116:119], v[8:11], 0
	v_mfma_f32_16x16x32_bf16 v[180:183], v[116:119], v[12:15], 0
	v_mfma_f32_16x16x32_bf16 v[184:187], v[116:119], v[16:19], 0
	v_mfma_f32_16x16x32_bf16 v[188:191], v[116:119], v[20:23], 0
	v_mfma_f32_16x16x32_bf16 v[192:195], v[116:119], v[24:27], 0
	v_mfma_f32_16x16x32_bf16 v[196:199], v[116:119], v[28:31], 0
	ds_read_b128 v[216:219], v242 offset:4608
	ds_read_b128 v[220:223], v242 offset:4672
	ds_read_b128 v[224:227], v242 offset:4736
	ds_read_b128 v[228:231], v242 offset:4800
	v_pk_mov_b32 v[232:233], v[136:137], v[152:153] op_sel:[0,0]
	v_pk_mov_b32 v[234:235], v[140:141], v[156:157] op_sel:[0,0]
	v_pk_mov_b32 v[244:245], v[144:145], v[160:161] op_sel:[0,0]
	v_pk_mov_b32 v[254:255], v[148:149], v[164:165] op_sel:[0,0]
	v_pk_fma_f32 v[232:233], v[32:33], v[200:201], v[232:233] op_sel_hi:[0,1,1]
	v_pk_fma_f32 v[234:235], v[34:35], v[202:203], v[234:235] op_sel_hi:[0,1,1]
	v_pk_fma_f32 v[244:245], v[36:37], v[204:205], v[244:245] op_sel_hi:[0,1,1]
	v_pk_fma_f32 v[254:255], v[38:39], v[206:207], v[254:255] op_sel_hi:[0,1,1]
	v_pk_fma_f32 v[200:201], v[32:33], v[200:201], v[232:233] op_sel:[1,1,0] op_sel_hi:[1,0,1] neg_lo:[1,0,0]
	v_pk_fma_f32 v[202:203], v[34:35], v[202:203], v[234:235] op_sel:[1,1,0] op_sel_hi:[1,0,1] neg_lo:[1,0,0]
	v_pk_fma_f32 v[204:205], v[36:37], v[204:205], v[244:245] op_sel:[1,1,0] op_sel_hi:[1,0,1] neg_lo:[1,0,0]
	v_pk_fma_f32 v[206:207], v[38:39], v[206:207], v[254:255] op_sel:[1,1,0] op_sel_hi:[1,0,1] neg_lo:[1,0,0]
	v_cvt_pk_bf16_f32 v124, v200, v201
	v_cvt_pk_bf16_f32 v125, v202, v203
	v_cvt_pk_bf16_f32 v126, v204, v205
	v_cvt_pk_bf16_f32 v127, v206, v207
	ds_write_b128 v241, v[124:127] offset:0
	v_pk_mov_b32 v[232:233], v[136:137], v[152:153] op_sel:[1,1]
	v_pk_mov_b32 v[234:235], v[140:141], v[156:157] op_sel:[1,1]
	v_pk_mov_b32 v[244:245], v[144:145], v[160:161] op_sel:[1,1]
	v_pk_mov_b32 v[254:255], v[148:149], v[164:165] op_sel:[1,1]
	v_pk_fma_f32 v[232:233], v[32:33], v[200:201], v[232:233] op_sel_hi:[0,1,1]
	v_pk_fma_f32 v[234:235], v[34:35], v[202:203], v[234:235] op_sel_hi:[0,1,1]
	v_pk_fma_f32 v[244:245], v[36:37], v[204:205], v[244:245] op_sel_hi:[0,1,1]
	v_pk_fma_f32 v[254:255], v[38:39], v[206:207], v[254:255] op_sel_hi:[0,1,1]
	v_pk_fma_f32 v[200:201], v[32:33], v[200:201], v[232:233] op_sel:[1,1,0] op_sel_hi:[1,0,1] neg_lo:[1,0,0]
	v_pk_fma_f32 v[202:203], v[34:35], v[202:203], v[234:235] op_sel:[1,1,0] op_sel_hi:[1,0,1] neg_lo:[1,0,0]
	v_pk_fma_f32 v[204:205], v[36:37], v[204:205], v[244:245] op_sel:[1,1,0] op_sel_hi:[1,0,1] neg_lo:[1,0,0]
	v_pk_fma_f32 v[206:207], v[38:39], v[206:207], v[254:255] op_sel:[1,1,0] op_sel_hi:[1,0,1] neg_lo:[1,0,0]
	v_cvt_pk_bf16_f32 v124, v200, v201
	v_cvt_pk_bf16_f32 v125, v202, v203
	v_cvt_pk_bf16_f32 v126, v204, v205
	v_cvt_pk_bf16_f32 v127, v206, v207
	ds_write_b128 v241, v[124:127] offset:288
	s_waitcnt lgkmcnt(2)
; __device__ __forceinline__ unsigned f2bf(float f) { unsigned u = __builtin_bit_cast(unsigned, f); return (u + 0x7fffu + ((u >> 16) & 1u)) >> 16; }
; __device__ __forceinline__ bf16x8 pack8(const float (&f)[8]) { u32x4 h; h.x = pk2(f[0], f[1]); h.y = pk2(f[2], f[3]); h.z = pk2(f[4], f[5]); h.w = pk2(f[6], f[7]); return __builtin_bit_cast(bf16x8, h); }
; template <bool FINAL> __device__ __forceinline__ void phase_s5_scan(const Fr& F) {
;     ...
;         for (int sub = 0; sub < 4; ++sub) {
;             const bf16x8 A1 = __builtin_bit_cast(bf16x8, uc[sub]);
; #pragma unroll
;             for (int nt = 0; nt < 8; ++nt) {
;                 f32x4 acc = {0.f, 0.f, 0.f, 0.f};
;                 acc = __builtin_amdgcn_mfma_f32_16x16x32_bf16(A1, B1[nt], acc, 0, 0, 0);
; #pragma unroll
;                 for (int reg = 0; reg < 4; ++reg) BUl[(4 * lq + reg) * 132 + 16 * nt + l15] = acc[reg];
;             }
;             asm volatile("s_waitcnt lgkmcnt(0)" ::: "memory");
; #pragma unroll 4
;             for (int jj = 0; jj < 16; ++jj) {
;                 const float br_ = BUl[jj * 132 + lane], bi_ = BUl[jj * 132 + 64 + lane];
;                 const float nr = ar * xr - ai * xi + br_, ni = ar * xi + ai * xr + bi_; xr = nr; xi = ni;
;                 if (FINAL) { BUl[jj * 132 + lane] = xr; BUl[jj * 132 + 64 + lane] = xi; }
;             }
;             if (FINAL) {
;                 asm volatile("s_waitcnt lgkmcnt(0)" ::: "memory");
;                 f32x4 acc = {0.f, 0.f, 0.f, 0.f};
; #pragma unroll
;                 for (int ks = 0; ks < 4; ++ks) {
;                     const f32x4 t0 = *(const f32x4*)(BUl + l15 * 132 + 32 * ks + 8 * lq), t1 = *(const f32x4*)(BUl + l15 * 132 + 32 * ks + 8 * lq + 4);
;                     const float xf[8] = {t0.x, t0.y, t0.z, t0.w, t1.x, t1.y, t1.z, t1.w};
;                     acc = __builtin_amdgcn_mfma_f32_16x16x32_bf16(pack8(xf), Chi[ks], acc, 0, 0, 0);
;                 }
; #pragma unroll
;                 for (int reg = 0; reg < 4; ++reg) { const int tok = tokof(s, chunk * 64 + sub * 16 + 4 * lq + reg);
;                     Yb[((size_t)b * TB + tok) * D + g * 16 + l15] = (bf16)f2bf(acc[reg]); }
;                 asm volatile("s_waitcnt lgkmcnt(0)" ::: "memory");
	v_mfma_f32_16x16x32_bf16 v[120:123], v[40:43], v[216:219], 0
	v_mfma_f32_16x16x32_bf16 v[120:123], v[44:47], v[220:223], v[120:123]
	v_mfma_f32_16x16x32_bf16 v[120:123], v[48:51], v[224:227], v[120:123]
	v_mfma_f32_16x16x32_bf16 v[120:123], v[52:55], v[228:231], v[120:123]
	v_pk_mov_b32 v[232:233], v[138:139], v[154:155] op_sel:[0,0]
	v_pk_mov_b32 v[234:235], v[142:143], v[158:159] op_sel:[0,0]
	v_pk_mov_b32 v[244:245], v[146:147], v[162:163] op_sel:[0,0]
	v_pk_mov_b32 v[254:255], v[150:151], v[166:167] op_sel:[0,0]
	v_pk_fma_f32 v[232:233], v[32:33], v[200:201], v[232:233] op_sel_hi:[0,1,1]
	v_pk_fma_f32 v[234:235], v[34:35], v[202:203], v[234:235] op_sel_hi:[0,1,1]
	v_pk_fma_f32 v[244:245], v[36:37], v[204:205], v[244:245] op_sel_hi:[0,1,1]
	v_pk_fma_f32 v[254:255], v[38:39], v[206:207], v[254:255] op_sel_hi:[0,1,1]
	v_pk_fma_f32 v[200:201], v[32:33], v[200:201], v[232:233] op_sel:[1,1,0] op_sel_hi:[1,0,1] neg_lo:[1,0,0]
	v_pk_fma_f32 v[202:203], v[34:35], v[202:203], v[234:235] op_sel:[1,1,0] op_sel_hi:[1,0,1] neg_lo:[1,0,0]
	v_pk_fma_f32 v[204:205], v[36:37], v[204:205], v[244:245] op_sel:[1,1,0] op_sel_hi:[1,0,1] neg_lo:[1,0,0]
	v_pk_fma_f32 v[206:207], v[38:39], v[206:207], v[254:255] op_sel:[1,1,0] op_sel_hi:[1,0,1] neg_lo:[1,0,0]
	v_cvt_pk_bf16_f32 v124, v200, v201
	v_cvt_pk_bf16_f32 v125, v202, v203
	v_cvt_pk_bf16_f32 v126, v204, v205
	v_cvt_pk_bf16_f32 v127, v206, v207
	ds_write_b128 v241, v[124:127] offset:576
	v_pk_mov_b32 v[232:233], v[138:139], v[154:155] op_sel:[1,1]
	v_pk_mov_b32 v[234:235], v[142:143], v[158:159] op_sel:[1,1]
	v_pk_mov_b32 v[244:245], v[146:147], v[162:163] op_sel:[1,1]
	v_pk_mov_b32 v[254:255], v[150:151], v[166:167] op_sel:[1,1]
	v_pk_fma_f32 v[232:233], v[32:33], v[200:201], v[232:233] op_sel_hi:[0,1,1]
	v_pk_fma_f32 v[234:235], v[34:35], v[202:203], v[234:235] op_sel_hi:[0,1,1]
	v_pk_fma_f32 v[244:245], v[36:37], v[204:205], v[244:245] op_sel_hi:[0,1,1]
	v_pk_fma_f32 v[254:255], v[38:39], v[206:207], v[254:255] op_sel_hi:[0,1,1]
	v_pk_fma_f32 v[200:201], v[32:33], v[200:201], v[232:233] op_sel:[1,1,0] op_sel_hi:[1,0,1] neg_lo:[1,0,0]
	v_pk_fma_f32 v[202:203], v[34:35], v[202:203], v[234:235] op_sel:[1,1,0] op_sel_hi:[1,0,1] neg_lo:[1,0,0]
	v_pk_fma_f32 v[204:205], v[36:37], v[204:205], v[244:245] op_sel:[1,1,0] op_sel_hi:[1,0,1] neg_lo:[1,0,0]
	v_pk_fma_f32 v[206:207], v[38:39], v[206:207], v[254:255] op_sel:[1,1,0] op_sel_hi:[1,0,1] neg_lo:[1,0,0]
	v_cvt_pk_bf16_f32 v124, v200, v201
	v_cvt_pk_bf16_f32 v125, v202, v203
	v_cvt_pk_bf16_f32 v126, v204, v205
	v_cvt_pk_bf16_f32 v127, v206, v207
	ds_write_b128 v241, v[124:127] offset:864
	global_load_dwordx4 v[112:115], v238, s[20:21]
	v_add_u32_e32 v238, v238, v243
	v_cvt_pk_bf16_f32 v124, v120, v121
	v_cvt_pk_bf16_f32 v125, v122, v123
	s_nop 0
	global_store_dwordx2 v239, v[124:125], s[24:25]
	v_add_u32_e32 v239, v239, v243
	ds_read_b128 v[216:219], v242 offset:0
	ds_read_b128 v[220:223], v242 offset:64
	ds_read_b128 v[224:227], v242 offset:128
	ds_read_b128 v[228:231], v242 offset:192
	v_pk_mov_b32 v[232:233], v[168:169], v[184:185] op_sel:[0,0]
	v_pk_mov_b32 v[234:235], v[172:173], v[188:189] op_sel:[0,0]
	v_pk_mov_b32 v[244:245], v[176:177], v[192:193] op_sel:[0,0]
	v_pk_mov_b32 v[254:255], v[180:181], v[196:197] op_sel:[0,0]
	v_pk_fma_f32 v[232:233], v[32:33], v[200:201], v[232:233] op_sel_hi:[0,1,1]
	v_pk_fma_f32 v[234:235], v[34:35], v[202:203], v[234:235] op_sel_hi:[0,1,1]
	v_pk_fma_f32 v[244:245], v[36:37], v[204:205], v[244:245] op_sel_hi:[0,1,1]
	v_pk_fma_f32 v[254:255], v[38:39], v[206:207], v[254:255] op_sel_hi:[0,1,1]
	v_pk_fma_f32 v[200:201], v[32:33], v[200:201], v[232:233] op_sel:[1,1,0] op_sel_hi:[1,0,1] neg_lo:[1,0,0]
	v_pk_fma_f32 v[202:203], v[34:35], v[202:203], v[234:235] op_sel:[1,1,0] op_sel_hi:[1,0,1] neg_lo:[1,0,0]
	v_pk_fma_f32 v[204:205], v[36:37], v[204:205], v[244:245] op_sel:[1,1,0] op_sel_hi:[1,0,1] neg_lo:[1,0,0]
	v_pk_fma_f32 v[206:207], v[38:39], v[206:207], v[254:255] op_sel:[1,1,0] op_sel_hi:[1,0,1] neg_lo:[1,0,0]
	v_cvt_pk_bf16_f32 v124, v200, v201
	v_cvt_pk_bf16_f32 v125, v202, v203
	v_cvt_pk_bf16_f32 v126, v204, v205
	v_cvt_pk_bf16_f32 v127, v206, v207
	ds_write_b128 v241, v[124:127] offset:4608
	v_pk_mov_b32 v[232:233], v[168:169], v[184:185] op_sel:[1,1]
	v_pk_mov_b32 v[234:235], v[172:173], v[188:189] op_sel:[1,1]
	v_pk_mov_b32 v[244:245], v[176:177], v[192:193] op_sel:[1,1]
	v_pk_mov_b32 v[254:255], v[180:181], v[196:197] op_sel:[1,1]
	v_pk_fma_f32 v[232:233], v[32:33], v[200:201], v[232:233] op_sel_hi:[0,1,1]
	v_pk_fma_f32 v[234:235], v[34:35], v[202:203], v[234:235] op_sel_hi:[0,1,1]
	v_pk_fma_f32 v[244:245], v[36:37], v[204:205], v[244:245] op_sel_hi:[0,1,1]
	v_pk_fma_f32 v[254:255], v[38:39], v[206:207], v[254:255] op_sel_hi:[0,1,1]
	v_pk_fma_f32 v[200:201], v[32:33], v[200:201], v[232:233] op_sel:[1,1,0] op_sel_hi:[1,0,1] neg_lo:[1,0,0]
	v_pk_fma_f32 v[202:203], v[34:35], v[202:203], v[234:235] op_sel:[1,1,0] op_sel_hi:[1,0,1] neg_lo:[1,0,0]
	v_pk_fma_f32 v[204:205], v[36:37], v[204:205], v[244:245] op_sel:[1,1,0] op_sel_hi:[1,0,1] neg_lo:[1,0,0]
	v_pk_fma_f32 v[206:207], v[38:39], v[206:207], v[254:255] op_sel:[1,1,0] op_sel_hi:[1,0,1] neg_lo:[1,0,0]
	v_cvt_pk_bf16_f32 v124, v200, v201
	v_cvt_pk_bf16_f32 v125, v202, v203
	v_cvt_pk_bf16_f32 v126, v204, v205
	v_cvt_pk_bf16_f32 v127, v206, v207
	ds_write_b128 v241, v[124:127] offset:4896
	s_waitcnt lgkmcnt(2)
; __device__ __forceinline__ unsigned f2bf(float f) { unsigned u = __builtin_bit_cast(unsigned, f); return (u + 0x7fffu + ((u >> 16) & 1u)) >> 16; }
; template <bool FINAL> __device__ __forceinline__ void phase_s5_scan(const Fr& F) {
;     ...
;     for (int ti = (F.gw & 15); ti < NB * 68; ti += 16) {
;     ...
;         for (int sub = 0; sub < 4; ++sub) {
;             const bf16x8 A1 = __builtin_bit_cast(bf16x8, uc[sub]);
; #pragma unroll
;             for (int nt = 0; nt < 8; ++nt) {
;                 f32x4 acc = {0.f, 0.f, 0.f, 0.f};
;                 acc = __builtin_amdgcn_mfma_f32_16x16x32_bf16(A1, B1[nt], acc, 0, 0, 0);
; #pragma unroll
;                 for (int reg = 0; reg < 4; ++reg) BUl[(4 * lq + reg) * 132 + 16 * nt + l15] = acc[reg];
;             }
;             asm volatile("s_waitcnt lgkmcnt(0)" ::: "memory");
; #pragma unroll 4
;             for (int jj = 0; jj < 16; ++jj) {
;                 const float br_ = BUl[jj * 132 + lane], bi_ = BUl[jj * 132 + 64 + lane];
;                 const float nr = ar * xr - ai * xi + br_, ni = ar * xi + ai * xr + bi_; xr = nr; xi = ni;
;                 if (FINAL) { BUl[jj * 132 + lane] = xr; BUl[jj * 132 + 64 + lane] = xi; }
;             }
;             if (FINAL) {
;                 asm volatile("s_waitcnt lgkmcnt(0)" ::: "memory");
;                 f32x4 acc = {0.f, 0.f, 0.f, 0.f};
; #pragma unroll
;                 for (int ks = 0; ks < 4; ++ks) {
;                     const f32x4 t0 = *(const f32x4*)(BUl + l15 * 132 + 32 * ks + 8 * lq), t1 = *(const f32x4*)(BUl + l15 * 132 + 32 * ks + 8 * lq + 4);
;                     const float xf[8] = {t0.x, t0.y, t0.z, t0.w, t1.x, t1.y, t1.z, t1.w};
;                     acc = __builtin_amdgcn_mfma_f32_16x16x32_bf16(pack8(xf), Chi[ks], acc, 0, 0, 0);
;                 }
; #pragma unroll
;                 for (int reg = 0; reg < 4; ++reg) { const int tok = tokof(s, chunk * 64 + sub * 16 + 4 * lq + reg);
;                     Yb[((size_t)b * TB + tok) * D + g * 16 + l15] = (bf16)f2bf(acc[reg]); }
;                 asm volatile("s_waitcnt lgkmcnt(0)" ::: "memory");
;             }
;         }
;         if (!FINAL) { float* e = E + ((size_t)task * 64 + lane) * 2; e[0] = xr; e[1] = xi; }
;     }
	v_mfma_f32_16x16x32_bf16 v[120:123], v[40:43], v[216:219], 0
	v_mfma_f32_16x16x32_bf16 v[120:123], v[44:47], v[220:223], v[120:123]
	v_mfma_f32_16x16x32_bf16 v[120:123], v[48:51], v[224:227], v[120:123]
	v_mfma_f32_16x16x32_bf16 v[120:123], v[52:55], v[228:231], v[120:123]
	v_pk_mov_b32 v[232:233], v[170:171], v[186:187] op_sel:[0,0]
	v_pk_mov_b32 v[234:235], v[174:175], v[190:191] op_sel:[0,0]
	v_pk_mov_b32 v[244:245], v[178:179], v[194:195] op_sel:[0,0]
	v_pk_mov_b32 v[254:255], v[182:183], v[198:199] op_sel:[0,0]
	v_pk_fma_f32 v[232:233], v[32:33], v[200:201], v[232:233] op_sel_hi:[0,1,1]
	v_pk_fma_f32 v[234:235], v[34:35], v[202:203], v[234:235] op_sel_hi:[0,1,1]
	v_pk_fma_f32 v[244:245], v[36:37], v[204:205], v[244:245] op_sel_hi:[0,1,1]
	v_pk_fma_f32 v[254:255], v[38:39], v[206:207], v[254:255] op_sel_hi:[0,1,1]
	v_pk_fma_f32 v[200:201], v[32:33], v[200:201], v[232:233] op_sel:[1,1,0] op_sel_hi:[1,0,1] neg_lo:[1,0,0]
	v_pk_fma_f32 v[202:203], v[34:35], v[202:203], v[234:235] op_sel:[1,1,0] op_sel_hi:[1,0,1] neg_lo:[1,0,0]
	v_pk_fma_f32 v[204:205], v[36:37], v[204:205], v[244:245] op_sel:[1,1,0] op_sel_hi:[1,0,1] neg_lo:[1,0,0]
	v_pk_fma_f32 v[206:207], v[38:39], v[206:207], v[254:255] op_sel:[1,1,0] op_sel_hi:[1,0,1] neg_lo:[1,0,0]
	v_cvt_pk_bf16_f32 v124, v200, v201
	v_cvt_pk_bf16_f32 v125, v202, v203
	v_cvt_pk_bf16_f32 v126, v204, v205
	v_cvt_pk_bf16_f32 v127, v206, v207
	ds_write_b128 v241, v[124:127] offset:5184
	v_pk_mov_b32 v[232:233], v[170:171], v[186:187] op_sel:[1,1]
	v_pk_mov_b32 v[234:235], v[174:175], v[190:191] op_sel:[1,1]
	v_pk_mov_b32 v[244:245], v[178:179], v[194:195] op_sel:[1,1]
	v_pk_mov_b32 v[254:255], v[182:183], v[198:199] op_sel:[1,1]
	v_pk_fma_f32 v[232:233], v[32:33], v[200:201], v[232:233] op_sel_hi:[0,1,1]
	v_pk_fma_f32 v[234:235], v[34:35], v[202:203], v[234:235] op_sel_hi:[0,1,1]
	v_pk_fma_f32 v[244:245], v[36:37], v[204:205], v[244:245] op_sel_hi:[0,1,1]
	v_pk_fma_f32 v[254:255], v[38:39], v[206:207], v[254:255] op_sel_hi:[0,1,1]
	v_pk_fma_f32 v[200:201], v[32:33], v[200:201], v[232:233] op_sel:[1,1,0] op_sel_hi:[1,0,1] neg_lo:[1,0,0]
	v_pk_fma_f32 v[202:203], v[34:35], v[202:203], v[234:235] op_sel:[1,1,0] op_sel_hi:[1,0,1] neg_lo:[1,0,0]
	v_pk_fma_f32 v[204:205], v[36:37], v[204:205], v[244:245] op_sel:[1,1,0] op_sel_hi:[1,0,1] neg_lo:[1,0,0]
	v_pk_fma_f32 v[206:207], v[38:39], v[206:207], v[254:255] op_sel:[1,1,0] op_sel_hi:[1,0,1] neg_lo:[1,0,0]
	v_cvt_pk_bf16_f32 v124, v200, v201
	v_cvt_pk_bf16_f32 v125, v202, v203
	v_cvt_pk_bf16_f32 v126, v204, v205
	v_cvt_pk_bf16_f32 v127, v206, v207
	ds_write_b128 v241, v[124:127] offset:5472
	global_load_dwordx4 v[116:119], v238, s[20:21]
	v_add_u32_e32 v238, v238, v243
	v_cvt_pk_bf16_f32 v124, v120, v121
	v_cvt_pk_bf16_f32 v125, v122, v123
	s_nop 0
	global_store_dwordx2 v239, v[124:125], s[24:25]
	v_add_u32_e32 v239, v239, v243
	ds_read_b128 v[216:219], v242 offset:4608
	ds_read_b128 v[220:223], v242 offset:4672
	ds_read_b128 v[224:227], v242 offset:4736
	ds_read_b128 v[228:231], v242 offset:4800
	s_waitcnt lgkmcnt(0)
	v_mfma_f32_16x16x32_bf16 v[120:123], v[40:43], v[216:219], 0
	v_mfma_f32_16x16x32_bf16 v[120:123], v[44:47], v[220:223], v[120:123]
	v_mfma_f32_16x16x32_bf16 v[120:123], v[48:51], v[224:227], v[120:123]
	v_mfma_f32_16x16x32_bf16 v[120:123], v[52:55], v[228:231], v[120:123]
	s_nop 7
	s_nop 1
	v_cvt_pk_bf16_f32 v124, v120, v121
	v_cvt_pk_bf16_f32 v125, v122, v123
	s_nop 0
	global_store_dwordx2 v239, v[124:125], s[24:25]
	v_add_u32_e32 v239, v239, v243
	s_add_i32 s14, s14, 16
	s_add_i32 s19, s19, 1
	s_cmp_lt_u32 s19, s56
	s_cbranch_scc1 .Ls5b_grp
	s_waitcnt vmcnt(0) lgkmcnt(0)
	v_mov_b32_e32 v2, s34
	v_mov_b32_e32 v3, s35
